# GEMM K loops: the 32 adjacent s_setprio 0 / s_setprio 1 flip pairs inside the 32-MFMA compute segments deleted (two SALU slots per segment)
# speedup vs baseline: 1.0014x; 1.0014x over previous
; #define PG8_STAGE(bufoff, gbase, voff) do { _Pragma("unroll") for (int _i = 0; _i < 2; ++_i) \
;         __builtin_amdgcn_global_load_lds((const unsigned*)((const char*)(gbase) + (voff)[_i]), (PG8_LAS unsigned*)(lds + (bufoff) + ldsw + _i * 8192), 16, 0, 0); } while (0)
; #define PG8_LDA(dst, b, h) do { _Pragma("unroll") for (int m = 0; m < 4; ++m) _Pragma("unroll") for (int k = 0; k < 2; ++k) dst[m][k] = *(const PG8_LAS bf16x8*)(lds + PG8_SA(b, h) + aoff + m * 2048 + k * 1024); } while (0)
; #define PG8_LDB(dst, b, h) do { _Pragma("unroll") for (int n = 0; n < 2; ++n) _Pragma("unroll") for (int k = 0; k < 2; ++k) dst[n][k] = *(const PG8_LAS bf16x8*)(lds + PG8_SB(b, h) + boff + n * 2048 + k * 1024); } while (0)
; #define PG8_WAIT_V(n) asm volatile("s_waitcnt vmcnt(" #n ")" ::: "memory")
; #define PG8_WAIT_L(n) asm volatile("s_waitcnt lgkmcnt(" #n ")" ::: "memory")
; #define PG8_BAR __builtin_amdgcn_s_barrier()
; #define PG8_SCHED __builtin_amdgcn_sched_barrier(0)
; template <class Epi, class Sched, bool ALIGN_EPI = false, bool SP2 = false>
; __device__ __forceinline__ void gemm_phase(PG8_LAS unsigned char* lds, const Gemm g, const Sched& S, const Epi& E) {
;     ...
;         const char* nA = has_next ? (const char*)g.A + (size_t)nxt.pm * tstep : cA; const char* nB = has_next ? (const char*)g.Bt + (size_t)nxt.pn * tstep : cB;
;         for (int t = 0; t < nt; t += 2) {
;             const bool last = (t == nt - 2);
;             const char* a1 = cA + (size_t)(t + 1) * kstep;
;             const char* a2 = last ? nA : cA + (size_t)(t + 2) * kstep; const char* b2 = last ? nB : cB + (size_t)(t + 2) * kstep;
;             const char* a3 = a2 + kstep; const char* b3 = b2 + kstep;
;             if (last && has_next) S.a_ready(nxt);
;             if constexpr (SP2) {
;             PG8_LDB(B0, 0, 0); PG8_LDB(B1, 0, 1); PG8_SCHED; PG8_LDA(At, 0, 0); PG8_STAGE(PG8_SA(1, 1), a1 + hstep, voffA);
;             PG8_WAIT_V(8); PG8_WAIT_L(0); PG8_BAR; PG8_MMA(0, 0, At, B0); PG8_MMA(0, 1, At, B1); PG8_BAR; PG8_SCHED;
;             PG8_LDA(At, 0, 1); PG8_STAGE(PG8_SB(0, 0), b2, voffB); PG8_STAGE(PG8_SB(0, 1), b2 + hstep, voffB); PG8_STAGE(PG8_SA(0, 0), a2, voffA);
;             PG8_WAIT_V(8); PG8_WAIT_L(0); PG8_BAR; PG8_MMA(1, 0, At, B0); PG8_MMA(1, 1, At, B1); PG8_BAR; PG8_SCHED;
.LBB0_132:
	s_add_u32 s10, s54, 0xfffc0080
	s_addc_u32 s11, s55, -1
	s_add_i32 s12, 0, 0x10000
	s_cmp_eq_u32 s31, 12
	s_cselect_b32 s59, s49, s11
	s_cselect_b32 s58, s73, s10
	v_add_u32_e32 v152, s12, v156
	s_cselect_b32 s57, s43, s30
	s_cselect_b32 s56, vcc_lo, vcc_hi
	s_add_i32 s13, 0, 0x14000
	ds_read_b128 v[144:147], v152
	ds_read_b128 v[148:151], v152 offset:1024
	ds_read_b128 v[160:163], v152 offset:2048
	ds_read_b128 v[164:167], v152 offset:3072
	v_add_u32_e32 v152, s13, v156
	ds_read_b128 v[168:171], v152
	ds_read_b128 v[172:175], v152 offset:1024
	ds_read_b128 v[176:179], v152 offset:2048
	ds_read_b128 v[180:183], v152 offset:3072
	s_add_i32 m0, s0, 0xc000
	ds_read_b128 v[198:201], v158
	ds_read_b128 v[202:205], v158 offset:1024
	ds_read_b128 v[206:209], v158 offset:2048
	ds_read_b128 v[210:213], v158 offset:3072
	ds_read_b128 v[214:217], v158 offset:4096
	ds_read_b128 v[226:229], v158 offset:5120
	ds_read_b128 v[230:233], v158 offset:6144
	ds_read_b128 v[234:237], v158 offset:7168
	global_load_lds_dwordx4 v140, s[54:55]
	s_add_i32 m0, s0, 0xe000
	s_nop 0
	global_load_lds_dwordx4 v142, s[54:55]
	s_waitcnt vmcnt(8)
	s_waitcnt lgkmcnt(0)
	s_barrier
	s_setprio 1
	s_waitcnt lgkmcnt(0)
	v_mfma_f32_16x16x32_bf16 v[124:127], v[144:147], v[198:201], v[124:127]
	v_mfma_f32_16x16x32_bf16 v[120:123], v[160:163], v[198:201], v[120:123]
	v_mfma_f32_16x16x32_bf16 v[108:111], v[144:147], v[206:209], v[108:111]
	v_mfma_f32_16x16x32_bf16 v[104:107], v[160:163], v[206:209], v[104:107]
	v_mfma_f32_16x16x32_bf16 v[92:95], v[144:147], v[214:217], v[92:95]
	v_mfma_f32_16x16x32_bf16 v[88:91], v[160:163], v[214:217], v[88:91]
	v_mfma_f32_16x16x32_bf16 v[76:79], v[144:147], v[230:233], v[76:79]
	v_mfma_f32_16x16x32_bf16 v[72:75], v[160:163], v[230:233], v[72:75]
	v_mfma_f32_16x16x32_bf16 v[124:127], v[148:151], v[202:205], v[124:127]
	v_mfma_f32_16x16x32_bf16 v[120:123], v[164:167], v[202:205], v[120:123]
	v_mfma_f32_16x16x32_bf16 v[108:111], v[148:151], v[210:213], v[108:111]
	v_mfma_f32_16x16x32_bf16 v[104:107], v[164:167], v[210:213], v[104:107]
	v_mfma_f32_16x16x32_bf16 v[92:95], v[148:151], v[226:229], v[92:95]
	v_mfma_f32_16x16x32_bf16 v[88:91], v[164:167], v[226:229], v[88:91]
	v_mfma_f32_16x16x32_bf16 v[76:79], v[148:151], v[234:237], v[76:79]
	v_mfma_f32_16x16x32_bf16 v[72:75], v[164:167], v[234:237], v[72:75]
	v_mfma_f32_16x16x32_bf16 v[116:119], v[168:171], v[198:201], v[116:119]
	v_mfma_f32_16x16x32_bf16 v[112:115], v[176:179], v[198:201], v[112:115]
	v_mfma_f32_16x16x32_bf16 v[100:103], v[168:171], v[206:209], v[100:103]
	v_mfma_f32_16x16x32_bf16 v[96:99], v[176:179], v[206:209], v[96:99]
	v_mfma_f32_16x16x32_bf16 v[84:87], v[168:171], v[214:217], v[84:87]
	v_mfma_f32_16x16x32_bf16 v[80:83], v[176:179], v[214:217], v[80:83]
	v_mfma_f32_16x16x32_bf16 v[68:71], v[168:171], v[230:233], v[68:71]
	v_mfma_f32_16x16x32_bf16 v[64:67], v[176:179], v[230:233], v[64:67]
	v_mfma_f32_16x16x32_bf16 v[116:119], v[172:175], v[202:205], v[116:119]
	v_mfma_f32_16x16x32_bf16 v[112:115], v[180:183], v[202:205], v[112:115]
	v_mfma_f32_16x16x32_bf16 v[100:103], v[172:175], v[210:213], v[100:103]
	v_mfma_f32_16x16x32_bf16 v[96:99], v[180:183], v[210:213], v[96:99]
	v_mfma_f32_16x16x32_bf16 v[84:87], v[172:175], v[226:229], v[84:87]
	v_mfma_f32_16x16x32_bf16 v[80:83], v[180:183], v[226:229], v[80:83]
	v_mfma_f32_16x16x32_bf16 v[68:71], v[172:175], v[234:237], v[68:71]
	v_mfma_f32_16x16x32_bf16 v[64:67], v[180:183], v[234:237], v[64:67]
	s_setprio 0
	s_barrier
	s_add_i32 s10, s12, s29
	v_lshl_add_u64 v[152:153], s[56:57], 0, v[132:133]
	s_mov_b32 m0, s10
	ds_read_b128 v[198:201], v158 offset:16384
	ds_read_b128 v[202:205], v158 offset:17408
	ds_read_b128 v[206:209], v158 offset:18432
	ds_read_b128 v[210:213], v158 offset:19456
	ds_read_b128 v[214:217], v158 offset:20480
	ds_read_b128 v[226:229], v158 offset:21504
	ds_read_b128 v[230:233], v158 offset:22528
	ds_read_b128 v[234:237], v158 offset:23552
	global_load_lds_dwordx4 v[152:153], off
	s_add_i32 m0, s10, 0x2000
	s_add_u32 s10, s56, 0x40000
	v_lshl_add_u64 v[238:239], s[56:57], 0, v[128:129]
	s_addc_u32 s11, s57, 0
	s_add_i32 s12, s13, s29
	global_load_lds_dwordx4 v[238:239], off
	s_mov_b32 m0, s12
	v_lshl_add_u64 v[242:243], s[58:59], 0, v[130:131]
	global_load_lds_dwordx4 v132, s[10:11]
	s_add_i32 m0, s12, 0x2000
	s_nop 0
	global_load_lds_dwordx4 v128, s[10:11]
	v_lshl_add_u64 v[240:241], s[58:59], 0, v[134:135]
	s_mov_b32 m0, s0
	s_nop 0
	global_load_lds_dwordx4 v[240:241], off
	s_mov_b32 m0, s1
	s_nop 0
	global_load_lds_dwordx4 v[242:243], off
	s_waitcnt vmcnt(8)
	s_waitcnt lgkmcnt(0)
	s_barrier
; #define PG8_STAGE(bufoff, gbase, voff) do { _Pragma("unroll") for (int _i = 0; _i < 2; ++_i) \
;         __builtin_amdgcn_global_load_lds((const unsigned*)((const char*)(gbase) + (voff)[_i]), (PG8_LAS unsigned*)(lds + (bufoff) + ldsw + _i * 8192), 16, 0, 0); } while (0)
; #define PG8_LDA(dst, b, h) do { _Pragma("unroll") for (int m = 0; m < 4; ++m) _Pragma("unroll") for (int k = 0; k < 2; ++k) dst[m][k] = *(const PG8_LAS bf16x8*)(lds + PG8_SA(b, h) + aoff + m * 2048 + k * 1024); } while (0)
; #define PG8_LDB(dst, b, h) do { _Pragma("unroll") for (int n = 0; n < 2; ++n) _Pragma("unroll") for (int k = 0; k < 2; ++k) dst[n][k] = *(const PG8_LAS bf16x8*)(lds + PG8_SB(b, h) + boff + n * 2048 + k * 1024); } while (0)
; #define PG8_MMA(ai, bj, At, Bt) do { __builtin_amdgcn_s_setprio(1); _Pragma("unroll") for (int m = 0; m < 4; ++m) _Pragma("unroll") for (int n = 0; n < 2; ++n) _Pragma("unroll") for (int k = 0; k < 2; ++k) \
;         acc[ai][bj][m][n] = __builtin_amdgcn_mfma_f32_16x16x32_bf16(Bt[n][k], At[m][k], acc[ai][bj][m][n], 0, 0, 0); __builtin_amdgcn_s_setprio(0); } while (0)
; #define PG8_WAIT_V(n) asm volatile("s_waitcnt vmcnt(" #n ")" ::: "memory")
; #define PG8_WAIT_L(n) asm volatile("s_waitcnt lgkmcnt(" #n ")" ::: "memory")
; #define PG8_BAR __builtin_amdgcn_s_barrier()
; #define PG8_SCHED __builtin_amdgcn_sched_barrier(0)
; template <class Epi, class Sched, bool ALIGN_EPI = false, bool SP2 = false>
; __device__ __forceinline__ void gemm_phase(PG8_LAS unsigned char* lds, const Gemm g, const Sched& S, const Epi& E) {
;     ...
;             PG8_WAIT_V(8); PG8_WAIT_L(0); PG8_BAR; PG8_MMA(1, 0, At, B0); PG8_MMA(1, 1, At, B1); PG8_BAR; PG8_SCHED;
;             PG8_LDB(B0, 1, 0); PG8_LDB(B1, 1, 1); PG8_SCHED; PG8_LDA(At, 1, 0); PG8_STAGE(PG8_SA(0, 1), a2 + hstep, voffA);
;             PG8_WAIT_V(8); PG8_WAIT_L(0); PG8_BAR; PG8_MMA(0, 0, At, B0); PG8_MMA(0, 1, At, B1); PG8_BAR; PG8_SCHED;
	s_setprio 1
	s_waitcnt lgkmcnt(0)
	v_mfma_f32_16x16x32_bf16 v[60:63], v[144:147], v[198:201], v[60:63]
	v_mfma_f32_16x16x32_bf16 v[56:59], v[160:163], v[198:201], v[56:59]
	v_mfma_f32_16x16x32_bf16 v[44:47], v[144:147], v[206:209], v[44:47]
	v_mfma_f32_16x16x32_bf16 v[40:43], v[160:163], v[206:209], v[40:43]
	v_mfma_f32_16x16x32_bf16 v[28:31], v[144:147], v[214:217], v[28:31]
	v_mfma_f32_16x16x32_bf16 v[24:27], v[160:163], v[214:217], v[24:27]
	v_mfma_f32_16x16x32_bf16 v[12:15], v[144:147], v[230:233], v[12:15]
	v_mfma_f32_16x16x32_bf16 v[8:11], v[160:163], v[230:233], v[8:11]
	v_mfma_f32_16x16x32_bf16 v[60:63], v[148:151], v[202:205], v[60:63]
	v_mfma_f32_16x16x32_bf16 v[56:59], v[164:167], v[202:205], v[56:59]
	v_mfma_f32_16x16x32_bf16 v[44:47], v[148:151], v[210:213], v[44:47]
	v_mfma_f32_16x16x32_bf16 v[40:43], v[164:167], v[210:213], v[40:43]
	v_mfma_f32_16x16x32_bf16 v[28:31], v[148:151], v[226:229], v[28:31]
	v_mfma_f32_16x16x32_bf16 v[24:27], v[164:167], v[226:229], v[24:27]
	v_mfma_f32_16x16x32_bf16 v[12:15], v[148:151], v[234:237], v[12:15]
	v_mfma_f32_16x16x32_bf16 v[8:11], v[164:167], v[234:237], v[8:11]
	v_mfma_f32_16x16x32_bf16 v[52:55], v[168:171], v[198:201], v[52:55]
	v_mfma_f32_16x16x32_bf16 v[48:51], v[176:179], v[198:201], v[48:51]
	v_mfma_f32_16x16x32_bf16 v[36:39], v[168:171], v[206:209], v[36:39]
	v_mfma_f32_16x16x32_bf16 v[32:35], v[176:179], v[206:209], v[32:35]
	v_mfma_f32_16x16x32_bf16 v[20:23], v[168:171], v[214:217], v[20:23]
	v_mfma_f32_16x16x32_bf16 v[16:19], v[176:179], v[214:217], v[16:19]
	v_mfma_f32_16x16x32_bf16 v[4:7], v[168:171], v[230:233], v[4:7]
	v_mfma_f32_16x16x32_bf16 v[0:3], v[176:179], v[230:233], v[0:3]
	v_mfma_f32_16x16x32_bf16 v[52:55], v[172:175], v[202:205], v[52:55]
	v_mfma_f32_16x16x32_bf16 v[48:51], v[180:183], v[202:205], v[48:51]
	v_mfma_f32_16x16x32_bf16 v[36:39], v[172:175], v[210:213], v[36:39]
	v_mfma_f32_16x16x32_bf16 v[32:35], v[180:183], v[210:213], v[32:35]
	v_mfma_f32_16x16x32_bf16 v[20:23], v[172:175], v[226:229], v[20:23]
	v_mfma_f32_16x16x32_bf16 v[16:19], v[180:183], v[226:229], v[16:19]
	v_mfma_f32_16x16x32_bf16 v[4:7], v[172:175], v[234:237], v[4:7]
	v_mfma_f32_16x16x32_bf16 v[0:3], v[180:183], v[234:237], v[0:3]
	s_setprio 0
	s_barrier
	s_add_i32 s12, 0, 0x18000
	v_add_u32_e32 v159, s12, v156
	s_add_i32 s13, 0, 0x1c000
	ds_read_b128 v[144:147], v159
	ds_read_b128 v[148:151], v159 offset:1024
	ds_read_b128 v[160:163], v159 offset:2048
	ds_read_b128 v[164:167], v159 offset:3072
	v_add_u32_e32 v159, s13, v156
	ds_read_b128 v[168:171], v159
	ds_read_b128 v[172:175], v159 offset:1024
	ds_read_b128 v[176:179], v159 offset:2048
	ds_read_b128 v[180:183], v159 offset:3072
	s_add_u32 s10, s58, 0x40000
	s_addc_u32 s11, s59, 0
	s_mov_b32 m0, s3
	ds_read_b128 v[198:201], v158 offset:32768
	ds_read_b128 v[202:205], v158 offset:33792
	ds_read_b128 v[206:209], v158 offset:34816
	ds_read_b128 v[210:213], v158 offset:35840
	ds_read_b128 v[214:217], v158 offset:36864
	ds_read_b128 v[226:229], v158 offset:37888
	ds_read_b128 v[230:233], v158 offset:38912
	ds_read_b128 v[234:237], v158 offset:39936
	global_load_lds_dwordx4 v134, s[10:11]
	s_mov_b32 m0, s20
	s_nop 0
	global_load_lds_dwordx4 v130, s[10:11]
	s_waitcnt vmcnt(8)
	s_waitcnt lgkmcnt(0)
	s_barrier
	s_setprio 1
	s_waitcnt lgkmcnt(0)
	v_mfma_f32_16x16x32_bf16 v[124:127], v[144:147], v[198:201], v[124:127]
	v_mfma_f32_16x16x32_bf16 v[120:123], v[160:163], v[198:201], v[120:123]
	v_mfma_f32_16x16x32_bf16 v[108:111], v[144:147], v[206:209], v[108:111]
	v_mfma_f32_16x16x32_bf16 v[104:107], v[160:163], v[206:209], v[104:107]
	v_mfma_f32_16x16x32_bf16 v[92:95], v[144:147], v[214:217], v[92:95]
	v_mfma_f32_16x16x32_bf16 v[88:91], v[160:163], v[214:217], v[88:91]
	v_mfma_f32_16x16x32_bf16 v[76:79], v[144:147], v[230:233], v[76:79]
	v_mfma_f32_16x16x32_bf16 v[72:75], v[160:163], v[230:233], v[72:75]
	v_mfma_f32_16x16x32_bf16 v[124:127], v[148:151], v[202:205], v[124:127]
	v_mfma_f32_16x16x32_bf16 v[120:123], v[164:167], v[202:205], v[120:123]
	v_mfma_f32_16x16x32_bf16 v[108:111], v[148:151], v[210:213], v[108:111]
	v_mfma_f32_16x16x32_bf16 v[104:107], v[164:167], v[210:213], v[104:107]
	v_mfma_f32_16x16x32_bf16 v[92:95], v[148:151], v[226:229], v[92:95]
	v_mfma_f32_16x16x32_bf16 v[88:91], v[164:167], v[226:229], v[88:91]
	v_mfma_f32_16x16x32_bf16 v[76:79], v[148:151], v[234:237], v[76:79]
	v_mfma_f32_16x16x32_bf16 v[72:75], v[164:167], v[234:237], v[72:75]
	v_mfma_f32_16x16x32_bf16 v[116:119], v[168:171], v[198:201], v[116:119]
	v_mfma_f32_16x16x32_bf16 v[112:115], v[176:179], v[198:201], v[112:115]
	v_mfma_f32_16x16x32_bf16 v[100:103], v[168:171], v[206:209], v[100:103]
	v_mfma_f32_16x16x32_bf16 v[96:99], v[176:179], v[206:209], v[96:99]
	v_mfma_f32_16x16x32_bf16 v[84:87], v[168:171], v[214:217], v[84:87]
	v_mfma_f32_16x16x32_bf16 v[80:83], v[176:179], v[214:217], v[80:83]
	v_mfma_f32_16x16x32_bf16 v[68:71], v[168:171], v[230:233], v[68:71]
	v_mfma_f32_16x16x32_bf16 v[64:67], v[176:179], v[230:233], v[64:67]
	v_mfma_f32_16x16x32_bf16 v[116:119], v[172:175], v[202:205], v[116:119]
	v_mfma_f32_16x16x32_bf16 v[112:115], v[180:183], v[202:205], v[112:115]
	v_mfma_f32_16x16x32_bf16 v[100:103], v[172:175], v[210:213], v[100:103]
	v_mfma_f32_16x16x32_bf16 v[96:99], v[180:183], v[210:213], v[96:99]
	v_mfma_f32_16x16x32_bf16 v[84:87], v[172:175], v[226:229], v[84:87]
	v_mfma_f32_16x16x32_bf16 v[80:83], v[180:183], v[226:229], v[80:83]
	v_mfma_f32_16x16x32_bf16 v[68:71], v[172:175], v[234:237], v[68:71]
	v_mfma_f32_16x16x32_bf16 v[64:67], v[180:183], v[234:237], v[64:67]
	s_setprio 0
	s_barrier
; #define PG8_STAGE(bufoff, gbase, voff) do { _Pragma("unroll") for (int _i = 0; _i < 2; ++_i) \
;         __builtin_amdgcn_global_load_lds((const unsigned*)((const char*)(gbase) + (voff)[_i]), (PG8_LAS unsigned*)(lds + (bufoff) + ldsw + _i * 8192), 16, 0, 0); } while (0)
; #define PG8_LDA(dst, b, h) do { _Pragma("unroll") for (int m = 0; m < 4; ++m) _Pragma("unroll") for (int k = 0; k < 2; ++k) dst[m][k] = *(const PG8_LAS bf16x8*)(lds + PG8_SA(b, h) + aoff + m * 2048 + k * 1024); } while (0)
; #define PG8_MMA(ai, bj, At, Bt) do { __builtin_amdgcn_s_setprio(1); _Pragma("unroll") for (int m = 0; m < 4; ++m) _Pragma("unroll") for (int n = 0; n < 2; ++n) _Pragma("unroll") for (int k = 0; k < 2; ++k) \
;         acc[ai][bj][m][n] = __builtin_amdgcn_mfma_f32_16x16x32_bf16(Bt[n][k], At[m][k], acc[ai][bj][m][n], 0, 0, 0); __builtin_amdgcn_s_setprio(0); } while (0)
; #define PG8_WAIT_V(n) asm volatile("s_waitcnt vmcnt(" #n ")" ::: "memory")
; #define PG8_WAIT_L(n) asm volatile("s_waitcnt lgkmcnt(" #n ")" ::: "memory")
; #define PG8_BAR __builtin_amdgcn_s_barrier()
; #define PG8_SCHED __builtin_amdgcn_sched_barrier(0)
; template <class Epi, class Sched, bool ALIGN_EPI = false, bool SP2 = false>
; __device__ __forceinline__ void gemm_phase(PG8_LAS unsigned char* lds, const Gemm g, const Sched& S, const Epi& E) {
;     ...
;             PG8_LDA(At, 1, 1); PG8_STAGE(PG8_SB(1, 0), b3, voffB); PG8_STAGE(PG8_SB(1, 1), b3 + hstep, voffB); PG8_STAGE(PG8_SA(1, 0), a3, voffA);
;             PG8_WAIT_V(8); PG8_WAIT_L(0); PG8_BAR; PG8_MMA(1, 0, At, B0); PG8_MMA(1, 1, At, B1); PG8_BAR; PG8_SCHED;
;     ...
;         if constexpr (ALIGN_EPI) { if (wr == 0) PG8_BAR; }
	s_add_i32 s10, s12, s29
	v_lshl_add_u64 v[152:153], v[152:153], 0, s[34:35]
	s_mov_b32 m0, s10
	ds_read_b128 v[198:201], v158 offset:49152
	ds_read_b128 v[202:205], v158 offset:50176
	ds_read_b128 v[206:209], v158 offset:51200
	ds_read_b128 v[210:213], v158 offset:52224
	ds_read_b128 v[214:217], v158 offset:53248
	ds_read_b128 v[226:229], v158 offset:54272
	ds_read_b128 v[230:233], v158 offset:55296
	ds_read_b128 v[234:237], v158 offset:56320
	global_load_lds_dwordx4 v[152:153], off
	s_add_i32 m0, s10, 0x2000
	s_add_u32 s10, s56, 0x40080
	v_lshl_add_u64 v[152:153], v[238:239], 0, s[34:35]
	s_addc_u32 s11, s57, 0
	s_add_i32 s12, s13, s29
	global_load_lds_dwordx4 v[152:153], off
	s_mov_b32 m0, s12
	s_nop 0
	global_load_lds_dwordx4 v132, s[10:11]
	s_add_i32 m0, s12, 0x2000
	s_nop 0
	global_load_lds_dwordx4 v128, s[10:11]
	v_lshl_add_u64 v[152:153], v[240:241], 0, s[34:35]
	s_mov_b32 m0, s8
	s_nop 0
	global_load_lds_dwordx4 v[152:153], off
	v_lshl_add_u64 v[152:153], v[242:243], 0, s[34:35]
	s_mov_b32 m0, s21
	s_nop 0
	global_load_lds_dwordx4 v[152:153], off
	s_waitcnt vmcnt(8)
	s_waitcnt lgkmcnt(0)
	s_barrier
	s_setprio 1
	s_waitcnt lgkmcnt(0)
	v_mfma_f32_16x16x32_bf16 v[60:63], v[144:147], v[198:201], v[60:63]
	v_mfma_f32_16x16x32_bf16 v[56:59], v[160:163], v[198:201], v[56:59]
	v_mfma_f32_16x16x32_bf16 v[44:47], v[144:147], v[206:209], v[44:47]
	v_mfma_f32_16x16x32_bf16 v[40:43], v[160:163], v[206:209], v[40:43]
	v_mfma_f32_16x16x32_bf16 v[28:31], v[144:147], v[214:217], v[28:31]
	v_mfma_f32_16x16x32_bf16 v[24:27], v[160:163], v[214:217], v[24:27]
	v_mfma_f32_16x16x32_bf16 v[12:15], v[144:147], v[230:233], v[12:15]
	v_mfma_f32_16x16x32_bf16 v[8:11], v[160:163], v[230:233], v[8:11]
	v_mfma_f32_16x16x32_bf16 v[60:63], v[148:151], v[202:205], v[60:63]
	v_mfma_f32_16x16x32_bf16 v[56:59], v[164:167], v[202:205], v[56:59]
	v_mfma_f32_16x16x32_bf16 v[44:47], v[148:151], v[210:213], v[44:47]
	v_mfma_f32_16x16x32_bf16 v[40:43], v[164:167], v[210:213], v[40:43]
	v_mfma_f32_16x16x32_bf16 v[28:31], v[148:151], v[226:229], v[28:31]
	v_mfma_f32_16x16x32_bf16 v[24:27], v[164:167], v[226:229], v[24:27]
	v_mfma_f32_16x16x32_bf16 v[12:15], v[148:151], v[234:237], v[12:15]
	v_mfma_f32_16x16x32_bf16 v[8:11], v[164:167], v[234:237], v[8:11]
	v_mfma_f32_16x16x32_bf16 v[52:55], v[168:171], v[198:201], v[52:55]
	v_mfma_f32_16x16x32_bf16 v[48:51], v[176:179], v[198:201], v[48:51]
	v_mfma_f32_16x16x32_bf16 v[36:39], v[168:171], v[206:209], v[36:39]
	v_mfma_f32_16x16x32_bf16 v[32:35], v[176:179], v[206:209], v[32:35]
	v_mfma_f32_16x16x32_bf16 v[20:23], v[168:171], v[214:217], v[20:23]
	v_mfma_f32_16x16x32_bf16 v[16:19], v[176:179], v[214:217], v[16:19]
	v_mfma_f32_16x16x32_bf16 v[4:7], v[168:171], v[230:233], v[4:7]
	v_mfma_f32_16x16x32_bf16 v[0:3], v[176:179], v[230:233], v[0:3]
	v_mfma_f32_16x16x32_bf16 v[52:55], v[172:175], v[202:205], v[52:55]
	v_mfma_f32_16x16x32_bf16 v[48:51], v[180:183], v[202:205], v[48:51]
	v_mfma_f32_16x16x32_bf16 v[36:39], v[172:175], v[210:213], v[36:39]
	v_mfma_f32_16x16x32_bf16 v[32:35], v[180:183], v[210:213], v[32:35]
	v_mfma_f32_16x16x32_bf16 v[20:23], v[172:175], v[226:229], v[20:23]
	v_mfma_f32_16x16x32_bf16 v[16:19], v[180:183], v[226:229], v[16:19]
	v_mfma_f32_16x16x32_bf16 v[4:7], v[172:175], v[234:237], v[4:7]
	v_mfma_f32_16x16x32_bf16 v[0:3], v[180:183], v[234:237], v[0:3]
	s_setprio 0
	s_barrier
	s_add_i32 s31, s31, 2
	s_add_u32 s54, s54, 0x100
	s_addc_u32 s55, s55, 0
	s_add_u32 vcc_hi, vcc_hi, 0x100
	s_addc_u32 s30, s30, 0
	s_cmp_gt_u32 s31, 13
	s_cbranch_scc0 .LBB0_132
	s_and_b64 vcc, exec, s[22:23]
	s_cbranch_vccz .LBB0_135
	s_barrier

; #define PG8_STAGE(bufoff, gbase, voff) do { _Pragma("unroll") for (int _i = 0; _i < 2; ++_i) \
;         __builtin_amdgcn_global_load_lds((const unsigned*)((const char*)(gbase) + (voff)[_i]), (PG8_LAS unsigned*)(lds + (bufoff) + ldsw + _i * 8192), 16, 0, 0); } while (0)
; #define PG8_LDA(dst, b, h) do { _Pragma("unroll") for (int m = 0; m < 4; ++m) _Pragma("unroll") for (int k = 0; k < 2; ++k) dst[m][k] = *(const PG8_LAS bf16x8*)(lds + PG8_SA(b, h) + aoff + m * 2048 + k * 1024); } while (0)
; #define PG8_LDB(dst, b, h) do { _Pragma("unroll") for (int n = 0; n < 2; ++n) _Pragma("unroll") for (int k = 0; k < 2; ++k) dst[n][k] = *(const PG8_LAS bf16x8*)(lds + PG8_SB(b, h) + boff + n * 2048 + k * 1024); } while (0)
; #define PG8_WAIT_V(n) asm volatile("s_waitcnt vmcnt(" #n ")" ::: "memory")
; #define PG8_WAIT_L(n) asm volatile("s_waitcnt lgkmcnt(" #n ")" ::: "memory")
; #define PG8_BAR __builtin_amdgcn_s_barrier()
; #define PG8_SCHED __builtin_amdgcn_sched_barrier(0)
; template <class Epi, class Sched, bool ALIGN_EPI = false, bool SP2 = false>
; __device__ __forceinline__ void gemm_phase(PG8_LAS unsigned char* lds, const Gemm g, const Sched& S, const Epi& E) {
;     ...
;         const char* nA = has_next ? (const char*)g.A + (size_t)nxt.pm * tstep : cA; const char* nB = has_next ? (const char*)g.Bt + (size_t)nxt.pn * tstep : cB;
;         for (int t = 0; t < nt; t += 2) {
;             const bool last = (t == nt - 2);
;             const char* a1 = cA + (size_t)(t + 1) * kstep;
;             const char* a2 = last ? nA : cA + (size_t)(t + 2) * kstep; const char* b2 = last ? nB : cB + (size_t)(t + 2) * kstep;
;             const char* a3 = a2 + kstep; const char* b3 = b2 + kstep;
;             if (last && has_next) S.a_ready(nxt);
;             if constexpr (SP2) {
;             PG8_LDB(B0, 0, 0); PG8_LDB(B1, 0, 1); PG8_SCHED; PG8_LDA(At, 0, 0); PG8_STAGE(PG8_SA(1, 1), a1 + hstep, voffA);
;             PG8_WAIT_V(8); PG8_WAIT_L(0); PG8_BAR; PG8_MMA(0, 0, At, B0); PG8_MMA(0, 1, At, B1); PG8_BAR; PG8_SCHED;
;             PG8_LDA(At, 0, 1); PG8_STAGE(PG8_SB(0, 0), b2, voffB); PG8_STAGE(PG8_SB(0, 1), b2 + hstep, voffB); PG8_STAGE(PG8_SA(0, 0), a2, voffA);
;             PG8_WAIT_V(8); PG8_WAIT_L(0); PG8_BAR; PG8_MMA(1, 0, At, B0); PG8_MMA(1, 1, At, B1); PG8_BAR; PG8_SCHED;
.LBB0_418:
	s_add_u32 s11, s58, 0xfffc0080
	s_addc_u32 s12, s59, -1
	s_add_i32 s13, 0, 0x10000
	s_cmp_eq_u32 s10, 12
	s_cselect_b32 s63, s53, s12
	s_cselect_b32 s62, vcc_lo, s11
	s_cselect_b32 s61, s51, s31
	s_cselect_b32 s60, vcc_hi, s30
	s_add_i32 s11, 0, 0x14000
	v_add_u32_e32 v154, s13, v143
	v_add_u32_e32 v170, s11, v143
	ds_read_b128 v[138:141], v154
	ds_read_b128 v[146:149], v154 offset:1024
	ds_read_b128 v[150:153], v154 offset:2048
	ds_read_b128 v[154:157], v154 offset:3072
	ds_read_b128 v[158:161], v170
	ds_read_b128 v[162:165], v170 offset:1024
	ds_read_b128 v[166:169], v170 offset:2048
	ds_read_b128 v[170:173], v170 offset:3072
	s_add_i32 m0, s8, 0xc000
	ds_read_b128 v[174:177], v145
	ds_read_b128 v[178:181], v145 offset:1024
	ds_read_b128 v[198:201], v145 offset:2048
	ds_read_b128 v[202:205], v145 offset:3072
	ds_read_b128 v[206:209], v145 offset:4096
	ds_read_b128 v[210:213], v145 offset:5120
	ds_read_b128 v[214:217], v145 offset:6144
	ds_read_b128 v[232:235], v145 offset:7168
	global_load_lds_dwordx4 v134, s[58:59]
	s_add_i32 m0, s8, 0xe000
	s_nop 0
	global_load_lds_dwordx4 v136, s[58:59]
	s_waitcnt vmcnt(8)
	s_waitcnt lgkmcnt(0)
	s_barrier
	s_setprio 1
	s_waitcnt lgkmcnt(0)
	v_mfma_f32_16x16x32_bf16 v[124:127], v[138:141], v[174:177], v[124:127]
	v_mfma_f32_16x16x32_bf16 v[120:123], v[150:153], v[174:177], v[120:123]
	v_mfma_f32_16x16x32_bf16 v[108:111], v[138:141], v[198:201], v[108:111]
	v_mfma_f32_16x16x32_bf16 v[104:107], v[150:153], v[198:201], v[104:107]
	v_mfma_f32_16x16x32_bf16 v[92:95], v[138:141], v[206:209], v[92:95]
	v_mfma_f32_16x16x32_bf16 v[88:91], v[150:153], v[206:209], v[88:91]
	v_mfma_f32_16x16x32_bf16 v[76:79], v[138:141], v[214:217], v[76:79]
	v_mfma_f32_16x16x32_bf16 v[72:75], v[150:153], v[214:217], v[72:75]
	v_mfma_f32_16x16x32_bf16 v[124:127], v[146:149], v[178:181], v[124:127]
	v_mfma_f32_16x16x32_bf16 v[120:123], v[154:157], v[178:181], v[120:123]
	v_mfma_f32_16x16x32_bf16 v[108:111], v[146:149], v[202:205], v[108:111]
	v_mfma_f32_16x16x32_bf16 v[104:107], v[154:157], v[202:205], v[104:107]
	v_mfma_f32_16x16x32_bf16 v[92:95], v[146:149], v[210:213], v[92:95]
	v_mfma_f32_16x16x32_bf16 v[88:91], v[154:157], v[210:213], v[88:91]
	v_mfma_f32_16x16x32_bf16 v[76:79], v[146:149], v[232:235], v[76:79]
	v_mfma_f32_16x16x32_bf16 v[72:75], v[154:157], v[232:235], v[72:75]
	v_mfma_f32_16x16x32_bf16 v[116:119], v[158:161], v[174:177], v[116:119]
	v_mfma_f32_16x16x32_bf16 v[112:115], v[166:169], v[174:177], v[112:115]
	v_mfma_f32_16x16x32_bf16 v[100:103], v[158:161], v[198:201], v[100:103]
	v_mfma_f32_16x16x32_bf16 v[96:99], v[166:169], v[198:201], v[96:99]
	v_mfma_f32_16x16x32_bf16 v[84:87], v[158:161], v[206:209], v[84:87]
	v_mfma_f32_16x16x32_bf16 v[80:83], v[166:169], v[206:209], v[80:83]
	v_mfma_f32_16x16x32_bf16 v[68:71], v[158:161], v[214:217], v[68:71]
	v_mfma_f32_16x16x32_bf16 v[64:67], v[166:169], v[214:217], v[64:67]
	v_mfma_f32_16x16x32_bf16 v[116:119], v[162:165], v[178:181], v[116:119]
	v_mfma_f32_16x16x32_bf16 v[112:115], v[170:173], v[178:181], v[112:115]
	v_mfma_f32_16x16x32_bf16 v[100:103], v[162:165], v[202:205], v[100:103]
	v_mfma_f32_16x16x32_bf16 v[96:99], v[170:173], v[202:205], v[96:99]
	v_mfma_f32_16x16x32_bf16 v[84:87], v[162:165], v[210:213], v[84:87]
	v_mfma_f32_16x16x32_bf16 v[80:83], v[170:173], v[210:213], v[80:83]
	v_mfma_f32_16x16x32_bf16 v[68:71], v[162:165], v[232:235], v[68:71]
	v_mfma_f32_16x16x32_bf16 v[64:67], v[170:173], v[232:235], v[64:67]
	s_setprio 0
	s_barrier
	s_add_i32 s12, s13, s3
	v_lshl_add_u64 v[182:183], s[60:61], 0, v[188:189]
	s_mov_b32 m0, s12
	ds_read_b128 v[174:177], v145 offset:16384
	ds_read_b128 v[178:181], v145 offset:17408
	ds_read_b128 v[198:201], v145 offset:18432
	ds_read_b128 v[202:205], v145 offset:19456
	ds_read_b128 v[206:209], v145 offset:20480
	ds_read_b128 v[210:213], v145 offset:21504
	ds_read_b128 v[214:217], v145 offset:22528
	ds_read_b128 v[232:235], v145 offset:23552
	global_load_lds_dwordx4 v[182:183], off
	s_add_i32 m0, s12, 0x2000
	s_add_u32 s12, s60, 0x40000
	v_lshl_add_u64 v[236:237], s[60:61], 0, v[128:129]
	s_addc_u32 s13, s61, 0
	s_add_i32 s11, s11, s3
	global_load_lds_dwordx4 v[236:237], off
	s_mov_b32 m0, s11
	v_lshl_add_u64 v[240:241], s[62:63], 0, v[130:131]
	global_load_lds_dwordx4 v188, s[12:13]
	s_add_i32 m0, s11, 0x2000
	s_nop 0
	global_load_lds_dwordx4 v128, s[12:13]
	v_lshl_add_u64 v[238:239], s[62:63], 0, v[132:133]
	s_mov_b32 m0, s8
	s_nop 0
	global_load_lds_dwordx4 v[238:239], off
	s_mov_b32 m0, s9
	s_nop 0
	global_load_lds_dwordx4 v[240:241], off
	s_waitcnt vmcnt(8)
	s_waitcnt lgkmcnt(0)
	s_barrier
; #define PG8_STAGE(bufoff, gbase, voff) do { _Pragma("unroll") for (int _i = 0; _i < 2; ++_i) \
;         __builtin_amdgcn_global_load_lds((const unsigned*)((const char*)(gbase) + (voff)[_i]), (PG8_LAS unsigned*)(lds + (bufoff) + ldsw + _i * 8192), 16, 0, 0); } while (0)
; #define PG8_LDA(dst, b, h) do { _Pragma("unroll") for (int m = 0; m < 4; ++m) _Pragma("unroll") for (int k = 0; k < 2; ++k) dst[m][k] = *(const PG8_LAS bf16x8*)(lds + PG8_SA(b, h) + aoff + m * 2048 + k * 1024); } while (0)
; #define PG8_LDB(dst, b, h) do { _Pragma("unroll") for (int n = 0; n < 2; ++n) _Pragma("unroll") for (int k = 0; k < 2; ++k) dst[n][k] = *(const PG8_LAS bf16x8*)(lds + PG8_SB(b, h) + boff + n * 2048 + k * 1024); } while (0)
; #define PG8_MMA(ai, bj, At, Bt) do { __builtin_amdgcn_s_setprio(1); _Pragma("unroll") for (int m = 0; m < 4; ++m) _Pragma("unroll") for (int n = 0; n < 2; ++n) _Pragma("unroll") for (int k = 0; k < 2; ++k) \
;         acc[ai][bj][m][n] = __builtin_amdgcn_mfma_f32_16x16x32_bf16(Bt[n][k], At[m][k], acc[ai][bj][m][n], 0, 0, 0); __builtin_amdgcn_s_setprio(0); } while (0)
; #define PG8_WAIT_V(n) asm volatile("s_waitcnt vmcnt(" #n ")" ::: "memory")
; #define PG8_WAIT_L(n) asm volatile("s_waitcnt lgkmcnt(" #n ")" ::: "memory")
; #define PG8_BAR __builtin_amdgcn_s_barrier()
; #define PG8_SCHED __builtin_amdgcn_sched_barrier(0)
; template <class Epi, class Sched, bool ALIGN_EPI = false, bool SP2 = false>
; __device__ __forceinline__ void gemm_phase(PG8_LAS unsigned char* lds, const Gemm g, const Sched& S, const Epi& E) {
;     ...
;             PG8_WAIT_V(8); PG8_WAIT_L(0); PG8_BAR; PG8_MMA(1, 0, At, B0); PG8_MMA(1, 1, At, B1); PG8_BAR; PG8_SCHED;
;             PG8_LDB(B0, 1, 0); PG8_LDB(B1, 1, 1); PG8_SCHED; PG8_LDA(At, 1, 0); PG8_STAGE(PG8_SA(0, 1), a2 + hstep, voffA);
;             PG8_WAIT_V(8); PG8_WAIT_L(0); PG8_BAR; PG8_MMA(0, 0, At, B0); PG8_MMA(0, 1, At, B1); PG8_BAR; PG8_SCHED;
	s_setprio 1
	s_waitcnt lgkmcnt(0)
	v_mfma_f32_16x16x32_bf16 v[60:63], v[138:141], v[174:177], v[60:63]
	v_mfma_f32_16x16x32_bf16 v[56:59], v[150:153], v[174:177], v[56:59]
	v_mfma_f32_16x16x32_bf16 v[44:47], v[138:141], v[198:201], v[44:47]
	v_mfma_f32_16x16x32_bf16 v[40:43], v[150:153], v[198:201], v[40:43]
	v_mfma_f32_16x16x32_bf16 v[28:31], v[138:141], v[206:209], v[28:31]
	v_mfma_f32_16x16x32_bf16 v[24:27], v[150:153], v[206:209], v[24:27]
	v_mfma_f32_16x16x32_bf16 v[12:15], v[138:141], v[214:217], v[12:15]
	v_mfma_f32_16x16x32_bf16 v[8:11], v[150:153], v[214:217], v[8:11]
	v_mfma_f32_16x16x32_bf16 v[60:63], v[146:149], v[178:181], v[60:63]
	v_mfma_f32_16x16x32_bf16 v[56:59], v[154:157], v[178:181], v[56:59]
	v_mfma_f32_16x16x32_bf16 v[44:47], v[146:149], v[202:205], v[44:47]
	v_mfma_f32_16x16x32_bf16 v[40:43], v[154:157], v[202:205], v[40:43]
	v_mfma_f32_16x16x32_bf16 v[28:31], v[146:149], v[210:213], v[28:31]
	v_mfma_f32_16x16x32_bf16 v[24:27], v[154:157], v[210:213], v[24:27]
	v_mfma_f32_16x16x32_bf16 v[12:15], v[146:149], v[232:235], v[12:15]
	v_mfma_f32_16x16x32_bf16 v[8:11], v[154:157], v[232:235], v[8:11]
	v_mfma_f32_16x16x32_bf16 v[52:55], v[158:161], v[174:177], v[52:55]
	v_mfma_f32_16x16x32_bf16 v[48:51], v[166:169], v[174:177], v[48:51]
	v_mfma_f32_16x16x32_bf16 v[36:39], v[158:161], v[198:201], v[36:39]
	v_mfma_f32_16x16x32_bf16 v[32:35], v[166:169], v[198:201], v[32:35]
	v_mfma_f32_16x16x32_bf16 v[20:23], v[158:161], v[206:209], v[20:23]
	v_mfma_f32_16x16x32_bf16 v[16:19], v[166:169], v[206:209], v[16:19]
	v_mfma_f32_16x16x32_bf16 v[4:7], v[158:161], v[214:217], v[4:7]
	v_mfma_f32_16x16x32_bf16 v[0:3], v[166:169], v[214:217], v[0:3]
	v_mfma_f32_16x16x32_bf16 v[52:55], v[162:165], v[178:181], v[52:55]
	v_mfma_f32_16x16x32_bf16 v[48:51], v[170:173], v[178:181], v[48:51]
	v_mfma_f32_16x16x32_bf16 v[36:39], v[162:165], v[202:205], v[36:39]
	v_mfma_f32_16x16x32_bf16 v[32:35], v[170:173], v[202:205], v[32:35]
	v_mfma_f32_16x16x32_bf16 v[20:23], v[162:165], v[210:213], v[20:23]
	v_mfma_f32_16x16x32_bf16 v[16:19], v[170:173], v[210:213], v[16:19]
	v_mfma_f32_16x16x32_bf16 v[4:7], v[162:165], v[232:235], v[4:7]
	v_mfma_f32_16x16x32_bf16 v[0:3], v[170:173], v[232:235], v[0:3]
	s_setprio 0
	s_barrier
	s_add_i32 s11, 0, 0x18000
	s_add_i32 s14, 0, 0x1c000
	v_add_u32_e32 v154, s11, v143
	v_add_u32_e32 v170, s14, v143
	ds_read_b128 v[138:141], v154
	ds_read_b128 v[146:149], v154 offset:1024
	ds_read_b128 v[150:153], v154 offset:2048
	ds_read_b128 v[154:157], v154 offset:3072
	ds_read_b128 v[158:161], v170
	ds_read_b128 v[162:165], v170 offset:1024
	ds_read_b128 v[166:169], v170 offset:2048
	ds_read_b128 v[170:173], v170 offset:3072
	s_add_u32 s12, s62, 0x40000
	s_addc_u32 s13, s63, 0
	s_mov_b32 m0, s20
	ds_read_b128 v[174:177], v145 offset:32768
	ds_read_b128 v[178:181], v145 offset:33792
	ds_read_b128 v[198:201], v145 offset:34816
	ds_read_b128 v[202:205], v145 offset:35840
	ds_read_b128 v[206:209], v145 offset:36864
	ds_read_b128 v[210:213], v145 offset:37888
	ds_read_b128 v[214:217], v145 offset:38912
	ds_read_b128 v[232:235], v145 offset:39936
	global_load_lds_dwordx4 v132, s[12:13]
	s_mov_b32 m0, s21
	s_nop 0
	global_load_lds_dwordx4 v130, s[12:13]
	s_waitcnt vmcnt(8)
	s_waitcnt lgkmcnt(0)
	s_barrier
	s_setprio 1
	s_waitcnt lgkmcnt(0)
	v_mfma_f32_16x16x32_bf16 v[124:127], v[138:141], v[174:177], v[124:127]
	v_mfma_f32_16x16x32_bf16 v[120:123], v[150:153], v[174:177], v[120:123]
	v_mfma_f32_16x16x32_bf16 v[108:111], v[138:141], v[198:201], v[108:111]
	v_mfma_f32_16x16x32_bf16 v[104:107], v[150:153], v[198:201], v[104:107]
	v_mfma_f32_16x16x32_bf16 v[92:95], v[138:141], v[206:209], v[92:95]
	v_mfma_f32_16x16x32_bf16 v[88:91], v[150:153], v[206:209], v[88:91]
	v_mfma_f32_16x16x32_bf16 v[76:79], v[138:141], v[214:217], v[76:79]
	v_mfma_f32_16x16x32_bf16 v[72:75], v[150:153], v[214:217], v[72:75]
	v_mfma_f32_16x16x32_bf16 v[124:127], v[146:149], v[178:181], v[124:127]
	v_mfma_f32_16x16x32_bf16 v[120:123], v[154:157], v[178:181], v[120:123]
	v_mfma_f32_16x16x32_bf16 v[108:111], v[146:149], v[202:205], v[108:111]
	v_mfma_f32_16x16x32_bf16 v[104:107], v[154:157], v[202:205], v[104:107]
	v_mfma_f32_16x16x32_bf16 v[92:95], v[146:149], v[210:213], v[92:95]
	v_mfma_f32_16x16x32_bf16 v[88:91], v[154:157], v[210:213], v[88:91]
	v_mfma_f32_16x16x32_bf16 v[76:79], v[146:149], v[232:235], v[76:79]
	v_mfma_f32_16x16x32_bf16 v[72:75], v[154:157], v[232:235], v[72:75]
	v_mfma_f32_16x16x32_bf16 v[116:119], v[158:161], v[174:177], v[116:119]
	v_mfma_f32_16x16x32_bf16 v[112:115], v[166:169], v[174:177], v[112:115]
	v_mfma_f32_16x16x32_bf16 v[100:103], v[158:161], v[198:201], v[100:103]
	v_mfma_f32_16x16x32_bf16 v[96:99], v[166:169], v[198:201], v[96:99]
	v_mfma_f32_16x16x32_bf16 v[84:87], v[158:161], v[206:209], v[84:87]
	v_mfma_f32_16x16x32_bf16 v[80:83], v[166:169], v[206:209], v[80:83]
	v_mfma_f32_16x16x32_bf16 v[68:71], v[158:161], v[214:217], v[68:71]
	v_mfma_f32_16x16x32_bf16 v[64:67], v[166:169], v[214:217], v[64:67]
	v_mfma_f32_16x16x32_bf16 v[116:119], v[162:165], v[178:181], v[116:119]
	v_mfma_f32_16x16x32_bf16 v[112:115], v[170:173], v[178:181], v[112:115]
	v_mfma_f32_16x16x32_bf16 v[100:103], v[162:165], v[202:205], v[100:103]
	v_mfma_f32_16x16x32_bf16 v[96:99], v[170:173], v[202:205], v[96:99]
	v_mfma_f32_16x16x32_bf16 v[84:87], v[162:165], v[210:213], v[84:87]
	v_mfma_f32_16x16x32_bf16 v[80:83], v[170:173], v[210:213], v[80:83]
	v_mfma_f32_16x16x32_bf16 v[68:71], v[162:165], v[232:235], v[68:71]
	v_mfma_f32_16x16x32_bf16 v[64:67], v[170:173], v[232:235], v[64:67]
	s_setprio 0
	s_barrier
; #define PG8_STAGE(bufoff, gbase, voff) do { _Pragma("unroll") for (int _i = 0; _i < 2; ++_i) \
;         __builtin_amdgcn_global_load_lds((const unsigned*)((const char*)(gbase) + (voff)[_i]), (PG8_LAS unsigned*)(lds + (bufoff) + ldsw + _i * 8192), 16, 0, 0); } while (0)
; #define PG8_LDA(dst, b, h) do { _Pragma("unroll") for (int m = 0; m < 4; ++m) _Pragma("unroll") for (int k = 0; k < 2; ++k) dst[m][k] = *(const PG8_LAS bf16x8*)(lds + PG8_SA(b, h) + aoff + m * 2048 + k * 1024); } while (0)
; #define PG8_MMA(ai, bj, At, Bt) do { __builtin_amdgcn_s_setprio(1); _Pragma("unroll") for (int m = 0; m < 4; ++m) _Pragma("unroll") for (int n = 0; n < 2; ++n) _Pragma("unroll") for (int k = 0; k < 2; ++k) \
;         acc[ai][bj][m][n] = __builtin_amdgcn_mfma_f32_16x16x32_bf16(Bt[n][k], At[m][k], acc[ai][bj][m][n], 0, 0, 0); __builtin_amdgcn_s_setprio(0); } while (0)
; #define PG8_WAIT_V(n) asm volatile("s_waitcnt vmcnt(" #n ")" ::: "memory")
; #define PG8_WAIT_L(n) asm volatile("s_waitcnt lgkmcnt(" #n ")" ::: "memory")
; #define PG8_BAR __builtin_amdgcn_s_barrier()
; #define PG8_SCHED __builtin_amdgcn_sched_barrier(0)
; template <class Epi, class Sched, bool ALIGN_EPI = false, bool SP2 = false>
; __device__ __forceinline__ void gemm_phase(PG8_LAS unsigned char* lds, const Gemm g, const Sched& S, const Epi& E) {
;     ...
;             PG8_LDA(At, 1, 1); PG8_STAGE(PG8_SB(1, 0), b3, voffB); PG8_STAGE(PG8_SB(1, 1), b3 + hstep, voffB); PG8_STAGE(PG8_SA(1, 0), a3, voffA);
;             PG8_WAIT_V(8); PG8_WAIT_L(0); PG8_BAR; PG8_MMA(1, 0, At, B0); PG8_MMA(1, 1, At, B1); PG8_BAR; PG8_SCHED;
;     ...
;         if constexpr (ALIGN_EPI) { if (wr == 0) PG8_BAR; }
	s_add_i32 s11, s11, s3
	v_lshl_add_u64 v[182:183], v[182:183], 0, s[34:35]
	s_mov_b32 m0, s11
	ds_read_b128 v[174:177], v145 offset:49152
	ds_read_b128 v[178:181], v145 offset:50176
	ds_read_b128 v[198:201], v145 offset:51200
	ds_read_b128 v[202:205], v145 offset:52224
	ds_read_b128 v[206:209], v145 offset:53248
	ds_read_b128 v[210:213], v145 offset:54272
	ds_read_b128 v[214:217], v145 offset:55296
	ds_read_b128 v[232:235], v145 offset:56320
	global_load_lds_dwordx4 v[182:183], off
	s_add_i32 m0, s11, 0x2000
	s_add_u32 s12, s60, 0x40080
	v_lshl_add_u64 v[182:183], v[236:237], 0, s[34:35]
	s_addc_u32 s13, s61, 0
	s_add_i32 s11, s14, s3
	global_load_lds_dwordx4 v[182:183], off
	s_mov_b32 m0, s11
	s_nop 0
	global_load_lds_dwordx4 v188, s[12:13]
	s_add_i32 m0, s11, 0x2000
	s_nop 0
	global_load_lds_dwordx4 v128, s[12:13]
	v_lshl_add_u64 v[182:183], v[238:239], 0, s[34:35]
	s_mov_b32 m0, s29
	s_nop 0
	global_load_lds_dwordx4 v[182:183], off
	v_lshl_add_u64 v[182:183], v[240:241], 0, s[34:35]
	s_mov_b32 m0, s39
	s_nop 0
	global_load_lds_dwordx4 v[182:183], off
	s_waitcnt vmcnt(8)
	s_waitcnt lgkmcnt(0)
	s_barrier
	s_setprio 1
	s_waitcnt lgkmcnt(0)
	v_mfma_f32_16x16x32_bf16 v[60:63], v[138:141], v[174:177], v[60:63]
	v_mfma_f32_16x16x32_bf16 v[56:59], v[150:153], v[174:177], v[56:59]
	v_mfma_f32_16x16x32_bf16 v[44:47], v[138:141], v[198:201], v[44:47]
	v_mfma_f32_16x16x32_bf16 v[40:43], v[150:153], v[198:201], v[40:43]
	v_mfma_f32_16x16x32_bf16 v[28:31], v[138:141], v[206:209], v[28:31]
	v_mfma_f32_16x16x32_bf16 v[24:27], v[150:153], v[206:209], v[24:27]
	v_mfma_f32_16x16x32_bf16 v[12:15], v[138:141], v[214:217], v[12:15]
	v_mfma_f32_16x16x32_bf16 v[8:11], v[150:153], v[214:217], v[8:11]
	v_mfma_f32_16x16x32_bf16 v[60:63], v[146:149], v[178:181], v[60:63]
	v_mfma_f32_16x16x32_bf16 v[56:59], v[154:157], v[178:181], v[56:59]
	v_mfma_f32_16x16x32_bf16 v[44:47], v[146:149], v[202:205], v[44:47]
	v_mfma_f32_16x16x32_bf16 v[40:43], v[154:157], v[202:205], v[40:43]
	v_mfma_f32_16x16x32_bf16 v[28:31], v[146:149], v[210:213], v[28:31]
	v_mfma_f32_16x16x32_bf16 v[24:27], v[154:157], v[210:213], v[24:27]
	v_mfma_f32_16x16x32_bf16 v[12:15], v[146:149], v[232:235], v[12:15]
	v_mfma_f32_16x16x32_bf16 v[8:11], v[154:157], v[232:235], v[8:11]
	v_mfma_f32_16x16x32_bf16 v[52:55], v[158:161], v[174:177], v[52:55]
	v_mfma_f32_16x16x32_bf16 v[48:51], v[166:169], v[174:177], v[48:51]
	v_mfma_f32_16x16x32_bf16 v[36:39], v[158:161], v[198:201], v[36:39]
	v_mfma_f32_16x16x32_bf16 v[32:35], v[166:169], v[198:201], v[32:35]
	v_mfma_f32_16x16x32_bf16 v[20:23], v[158:161], v[206:209], v[20:23]
	v_mfma_f32_16x16x32_bf16 v[16:19], v[166:169], v[206:209], v[16:19]
	v_mfma_f32_16x16x32_bf16 v[4:7], v[158:161], v[214:217], v[4:7]
	v_mfma_f32_16x16x32_bf16 v[0:3], v[166:169], v[214:217], v[0:3]
	v_mfma_f32_16x16x32_bf16 v[52:55], v[162:165], v[178:181], v[52:55]
	v_mfma_f32_16x16x32_bf16 v[48:51], v[170:173], v[178:181], v[48:51]
	v_mfma_f32_16x16x32_bf16 v[36:39], v[162:165], v[202:205], v[36:39]
	v_mfma_f32_16x16x32_bf16 v[32:35], v[170:173], v[202:205], v[32:35]
	v_mfma_f32_16x16x32_bf16 v[20:23], v[162:165], v[210:213], v[20:23]
	v_mfma_f32_16x16x32_bf16 v[16:19], v[170:173], v[210:213], v[16:19]
	v_mfma_f32_16x16x32_bf16 v[4:7], v[162:165], v[232:235], v[4:7]
	v_mfma_f32_16x16x32_bf16 v[0:3], v[170:173], v[232:235], v[0:3]
	s_setprio 0
	s_barrier
	s_add_i32 s10, s10, 2
	s_add_u32 s58, s58, 0x100
	s_addc_u32 s59, s59, 0
	s_add_u32 s30, s30, 0x100
	s_addc_u32 s31, s31, 0
	s_cmp_gt_u32 s10, 13
	s_cbranch_scc0 .LBB0_418
	s_and_b64 vcc, exec, s[48:49]
	s_cbranch_vccz .LBB0_421
	s_barrier

; #define PG8_STAGE(bufoff, gbase, voff) do { _Pragma("unroll") for (int _i = 0; _i < 2; ++_i) \
;         __builtin_amdgcn_global_load_lds((const unsigned*)((const char*)(gbase) + (voff)[_i]), (PG8_LAS unsigned*)(lds + (bufoff) + ldsw + _i * 8192), 16, 0, 0); } while (0)
; #define PG8_LDA(dst, b, h) do { _Pragma("unroll") for (int m = 0; m < 4; ++m) _Pragma("unroll") for (int k = 0; k < 2; ++k) dst[m][k] = *(const PG8_LAS bf16x8*)(lds + PG8_SA(b, h) + aoff + m * 2048 + k * 1024); } while (0)
; #define PG8_LDB(dst, b, h) do { _Pragma("unroll") for (int n = 0; n < 2; ++n) _Pragma("unroll") for (int k = 0; k < 2; ++k) dst[n][k] = *(const PG8_LAS bf16x8*)(lds + PG8_SB(b, h) + boff + n * 2048 + k * 1024); } while (0)
; #define PG8_WAIT_V(n) asm volatile("s_waitcnt vmcnt(" #n ")" ::: "memory")
; #define PG8_WAIT_L(n) asm volatile("s_waitcnt lgkmcnt(" #n ")" ::: "memory")
; #define PG8_BAR __builtin_amdgcn_s_barrier()
; #define PG8_SCHED __builtin_amdgcn_sched_barrier(0)
; template <class Epi, class Sched, bool ALIGN_EPI = false, bool SP2 = false>
; __device__ __forceinline__ void gemm_phase(PG8_LAS unsigned char* lds, const Gemm g, const Sched& S, const Epi& E) {
;     ...
;         const char* nA = has_next ? (const char*)g.A + (size_t)nxt.pm * tstep : cA; const char* nB = has_next ? (const char*)g.Bt + (size_t)nxt.pn * tstep : cB;
;         for (int t = 0; t < nt; t += 2) {
;             const bool last = (t == nt - 2);
;             const char* a1 = cA + (size_t)(t + 1) * kstep;
;             const char* a2 = last ? nA : cA + (size_t)(t + 2) * kstep; const char* b2 = last ? nB : cB + (size_t)(t + 2) * kstep;
;             const char* a3 = a2 + kstep; const char* b3 = b2 + kstep;
;             if (last && has_next) S.a_ready(nxt);
;             if constexpr (SP2) {
;             PG8_LDB(B0, 0, 0); PG8_LDB(B1, 0, 1); PG8_SCHED; PG8_LDA(At, 0, 0); PG8_STAGE(PG8_SA(1, 1), a1 + hstep, voffA);
;             PG8_WAIT_V(8); PG8_WAIT_L(0); PG8_BAR; PG8_MMA(0, 0, At, B0); PG8_MMA(0, 1, At, B1); PG8_BAR; PG8_SCHED;
;             PG8_LDA(At, 0, 1); PG8_STAGE(PG8_SB(0, 0), b2, voffB); PG8_STAGE(PG8_SB(0, 1), b2 + hstep, voffB); PG8_STAGE(PG8_SA(0, 0), a2, voffA);
;             PG8_WAIT_V(8); PG8_WAIT_L(0); PG8_BAR; PG8_MMA(1, 0, At, B0); PG8_MMA(1, 1, At, B1); PG8_BAR; PG8_SCHED;
.LBB0_438:
	s_add_u32 s11, s56, 0xfffc0080
	s_addc_u32 s12, s57, -1
	s_add_i32 s13, 0, 0x10000
	s_cmp_eq_u32 s10, 12
	s_cselect_b32 s61, s51, s12
	s_cselect_b32 s60, s72, s11
	s_cselect_b32 s59, s49, s31
	s_cselect_b32 s58, s73, s30
	s_add_i32 s11, 0, 0x14000
	v_add_u32_e32 v154, s13, v143
	v_add_u32_e32 v170, s11, v143
	ds_read_b128 v[138:141], v154
	ds_read_b128 v[146:149], v154 offset:1024
	ds_read_b128 v[150:153], v154 offset:2048
	ds_read_b128 v[154:157], v154 offset:3072
	ds_read_b128 v[158:161], v170
	ds_read_b128 v[162:165], v170 offset:1024
	ds_read_b128 v[166:169], v170 offset:2048
	ds_read_b128 v[170:173], v170 offset:3072
	s_add_i32 m0, s8, 0xc000
	ds_read_b128 v[174:177], v145
	ds_read_b128 v[178:181], v145 offset:1024
	ds_read_b128 v[198:201], v145 offset:2048
	ds_read_b128 v[202:205], v145 offset:3072
	ds_read_b128 v[206:209], v145 offset:4096
	ds_read_b128 v[210:213], v145 offset:5120
	ds_read_b128 v[214:217], v145 offset:6144
	ds_read_b128 v[232:235], v145 offset:7168
	global_load_lds_dwordx4 v134, s[56:57]
	s_add_i32 m0, s8, 0xe000
	s_nop 0
	global_load_lds_dwordx4 v136, s[56:57]
	s_waitcnt vmcnt(8)
	s_waitcnt lgkmcnt(0)
	s_barrier
	s_setprio 1
	s_waitcnt lgkmcnt(0)
	v_mfma_f32_16x16x32_bf16 v[124:127], v[138:141], v[174:177], v[124:127]
	v_mfma_f32_16x16x32_bf16 v[120:123], v[150:153], v[174:177], v[120:123]
	v_mfma_f32_16x16x32_bf16 v[108:111], v[138:141], v[198:201], v[108:111]
	v_mfma_f32_16x16x32_bf16 v[104:107], v[150:153], v[198:201], v[104:107]
	v_mfma_f32_16x16x32_bf16 v[92:95], v[138:141], v[206:209], v[92:95]
	v_mfma_f32_16x16x32_bf16 v[88:91], v[150:153], v[206:209], v[88:91]
	v_mfma_f32_16x16x32_bf16 v[76:79], v[138:141], v[214:217], v[76:79]
	v_mfma_f32_16x16x32_bf16 v[72:75], v[150:153], v[214:217], v[72:75]
	v_mfma_f32_16x16x32_bf16 v[124:127], v[146:149], v[178:181], v[124:127]
	v_mfma_f32_16x16x32_bf16 v[120:123], v[154:157], v[178:181], v[120:123]
	v_mfma_f32_16x16x32_bf16 v[108:111], v[146:149], v[202:205], v[108:111]
	v_mfma_f32_16x16x32_bf16 v[104:107], v[154:157], v[202:205], v[104:107]
	v_mfma_f32_16x16x32_bf16 v[92:95], v[146:149], v[210:213], v[92:95]
	v_mfma_f32_16x16x32_bf16 v[88:91], v[154:157], v[210:213], v[88:91]
	v_mfma_f32_16x16x32_bf16 v[76:79], v[146:149], v[232:235], v[76:79]
	v_mfma_f32_16x16x32_bf16 v[72:75], v[154:157], v[232:235], v[72:75]
	v_mfma_f32_16x16x32_bf16 v[116:119], v[158:161], v[174:177], v[116:119]
	v_mfma_f32_16x16x32_bf16 v[112:115], v[166:169], v[174:177], v[112:115]
	v_mfma_f32_16x16x32_bf16 v[100:103], v[158:161], v[198:201], v[100:103]
	v_mfma_f32_16x16x32_bf16 v[96:99], v[166:169], v[198:201], v[96:99]
	v_mfma_f32_16x16x32_bf16 v[84:87], v[158:161], v[206:209], v[84:87]
	v_mfma_f32_16x16x32_bf16 v[80:83], v[166:169], v[206:209], v[80:83]
	v_mfma_f32_16x16x32_bf16 v[68:71], v[158:161], v[214:217], v[68:71]
	v_mfma_f32_16x16x32_bf16 v[64:67], v[166:169], v[214:217], v[64:67]
	v_mfma_f32_16x16x32_bf16 v[116:119], v[162:165], v[178:181], v[116:119]
	v_mfma_f32_16x16x32_bf16 v[112:115], v[170:173], v[178:181], v[112:115]
	v_mfma_f32_16x16x32_bf16 v[100:103], v[162:165], v[202:205], v[100:103]
	v_mfma_f32_16x16x32_bf16 v[96:99], v[170:173], v[202:205], v[96:99]
	v_mfma_f32_16x16x32_bf16 v[84:87], v[162:165], v[210:213], v[84:87]
	v_mfma_f32_16x16x32_bf16 v[80:83], v[170:173], v[210:213], v[80:83]
	v_mfma_f32_16x16x32_bf16 v[68:71], v[162:165], v[232:235], v[68:71]
	v_mfma_f32_16x16x32_bf16 v[64:67], v[170:173], v[232:235], v[64:67]
	s_setprio 0
	s_barrier
	s_add_i32 s12, s13, s3
	v_lshl_add_u64 v[182:183], s[58:59], 0, v[188:189]
	s_mov_b32 m0, s12
	ds_read_b128 v[174:177], v145 offset:16384
	ds_read_b128 v[178:181], v145 offset:17408
	ds_read_b128 v[198:201], v145 offset:18432
	ds_read_b128 v[202:205], v145 offset:19456
	ds_read_b128 v[206:209], v145 offset:20480
	ds_read_b128 v[210:213], v145 offset:21504
	ds_read_b128 v[214:217], v145 offset:22528
	ds_read_b128 v[232:235], v145 offset:23552
	global_load_lds_dwordx4 v[182:183], off
	s_add_i32 m0, s12, 0x2000
	s_add_u32 s12, s58, 0x40000
	v_lshl_add_u64 v[236:237], s[58:59], 0, v[128:129]
	s_addc_u32 s13, s59, 0
	s_add_i32 s11, s11, s3
	global_load_lds_dwordx4 v[236:237], off
	s_mov_b32 m0, s11
	v_lshl_add_u64 v[240:241], s[60:61], 0, v[130:131]
	global_load_lds_dwordx4 v188, s[12:13]
	s_add_i32 m0, s11, 0x2000
	s_nop 0
	global_load_lds_dwordx4 v128, s[12:13]
	v_lshl_add_u64 v[238:239], s[60:61], 0, v[132:133]
	s_mov_b32 m0, s8
	s_nop 0
	global_load_lds_dwordx4 v[238:239], off
	s_mov_b32 m0, s9
	s_nop 0
	global_load_lds_dwordx4 v[240:241], off
	s_waitcnt vmcnt(8)
	s_waitcnt lgkmcnt(0)
	s_barrier
; #define PG8_STAGE(bufoff, gbase, voff) do { _Pragma("unroll") for (int _i = 0; _i < 2; ++_i) \
;         __builtin_amdgcn_global_load_lds((const unsigned*)((const char*)(gbase) + (voff)[_i]), (PG8_LAS unsigned*)(lds + (bufoff) + ldsw + _i * 8192), 16, 0, 0); } while (0)
; #define PG8_LDA(dst, b, h) do { _Pragma("unroll") for (int m = 0; m < 4; ++m) _Pragma("unroll") for (int k = 0; k < 2; ++k) dst[m][k] = *(const PG8_LAS bf16x8*)(lds + PG8_SA(b, h) + aoff + m * 2048 + k * 1024); } while (0)
; #define PG8_LDB(dst, b, h) do { _Pragma("unroll") for (int n = 0; n < 2; ++n) _Pragma("unroll") for (int k = 0; k < 2; ++k) dst[n][k] = *(const PG8_LAS bf16x8*)(lds + PG8_SB(b, h) + boff + n * 2048 + k * 1024); } while (0)
; #define PG8_MMA(ai, bj, At, Bt) do { __builtin_amdgcn_s_setprio(1); _Pragma("unroll") for (int m = 0; m < 4; ++m) _Pragma("unroll") for (int n = 0; n < 2; ++n) _Pragma("unroll") for (int k = 0; k < 2; ++k) \
;         acc[ai][bj][m][n] = __builtin_amdgcn_mfma_f32_16x16x32_bf16(Bt[n][k], At[m][k], acc[ai][bj][m][n], 0, 0, 0); __builtin_amdgcn_s_setprio(0); } while (0)
; #define PG8_WAIT_V(n) asm volatile("s_waitcnt vmcnt(" #n ")" ::: "memory")
; #define PG8_WAIT_L(n) asm volatile("s_waitcnt lgkmcnt(" #n ")" ::: "memory")
; #define PG8_BAR __builtin_amdgcn_s_barrier()
; #define PG8_SCHED __builtin_amdgcn_sched_barrier(0)
; template <class Epi, class Sched, bool ALIGN_EPI = false, bool SP2 = false>
; __device__ __forceinline__ void gemm_phase(PG8_LAS unsigned char* lds, const Gemm g, const Sched& S, const Epi& E) {
;     ...
;             PG8_WAIT_V(8); PG8_WAIT_L(0); PG8_BAR; PG8_MMA(1, 0, At, B0); PG8_MMA(1, 1, At, B1); PG8_BAR; PG8_SCHED;
;             PG8_LDB(B0, 1, 0); PG8_LDB(B1, 1, 1); PG8_SCHED; PG8_LDA(At, 1, 0); PG8_STAGE(PG8_SA(0, 1), a2 + hstep, voffA);
;             PG8_WAIT_V(8); PG8_WAIT_L(0); PG8_BAR; PG8_MMA(0, 0, At, B0); PG8_MMA(0, 1, At, B1); PG8_BAR; PG8_SCHED;
	s_setprio 1
	s_waitcnt lgkmcnt(0)
	v_mfma_f32_16x16x32_bf16 v[60:63], v[138:141], v[174:177], v[60:63]
	v_mfma_f32_16x16x32_bf16 v[56:59], v[150:153], v[174:177], v[56:59]
	v_mfma_f32_16x16x32_bf16 v[44:47], v[138:141], v[198:201], v[44:47]
	v_mfma_f32_16x16x32_bf16 v[40:43], v[150:153], v[198:201], v[40:43]
	v_mfma_f32_16x16x32_bf16 v[28:31], v[138:141], v[206:209], v[28:31]
	v_mfma_f32_16x16x32_bf16 v[24:27], v[150:153], v[206:209], v[24:27]
	v_mfma_f32_16x16x32_bf16 v[12:15], v[138:141], v[214:217], v[12:15]
	v_mfma_f32_16x16x32_bf16 v[8:11], v[150:153], v[214:217], v[8:11]
	v_mfma_f32_16x16x32_bf16 v[60:63], v[146:149], v[178:181], v[60:63]
	v_mfma_f32_16x16x32_bf16 v[56:59], v[154:157], v[178:181], v[56:59]
	v_mfma_f32_16x16x32_bf16 v[44:47], v[146:149], v[202:205], v[44:47]
	v_mfma_f32_16x16x32_bf16 v[40:43], v[154:157], v[202:205], v[40:43]
	v_mfma_f32_16x16x32_bf16 v[28:31], v[146:149], v[210:213], v[28:31]
	v_mfma_f32_16x16x32_bf16 v[24:27], v[154:157], v[210:213], v[24:27]
	v_mfma_f32_16x16x32_bf16 v[12:15], v[146:149], v[232:235], v[12:15]
	v_mfma_f32_16x16x32_bf16 v[8:11], v[154:157], v[232:235], v[8:11]
	v_mfma_f32_16x16x32_bf16 v[52:55], v[158:161], v[174:177], v[52:55]
	v_mfma_f32_16x16x32_bf16 v[48:51], v[166:169], v[174:177], v[48:51]
	v_mfma_f32_16x16x32_bf16 v[36:39], v[158:161], v[198:201], v[36:39]
	v_mfma_f32_16x16x32_bf16 v[32:35], v[166:169], v[198:201], v[32:35]
	v_mfma_f32_16x16x32_bf16 v[20:23], v[158:161], v[206:209], v[20:23]
	v_mfma_f32_16x16x32_bf16 v[16:19], v[166:169], v[206:209], v[16:19]
	v_mfma_f32_16x16x32_bf16 v[4:7], v[158:161], v[214:217], v[4:7]
	v_mfma_f32_16x16x32_bf16 v[0:3], v[166:169], v[214:217], v[0:3]
	v_mfma_f32_16x16x32_bf16 v[52:55], v[162:165], v[178:181], v[52:55]
	v_mfma_f32_16x16x32_bf16 v[48:51], v[170:173], v[178:181], v[48:51]
	v_mfma_f32_16x16x32_bf16 v[36:39], v[162:165], v[202:205], v[36:39]
	v_mfma_f32_16x16x32_bf16 v[32:35], v[170:173], v[202:205], v[32:35]
	v_mfma_f32_16x16x32_bf16 v[20:23], v[162:165], v[210:213], v[20:23]
	v_mfma_f32_16x16x32_bf16 v[16:19], v[170:173], v[210:213], v[16:19]
	v_mfma_f32_16x16x32_bf16 v[4:7], v[162:165], v[232:235], v[4:7]
	v_mfma_f32_16x16x32_bf16 v[0:3], v[170:173], v[232:235], v[0:3]
	s_setprio 0
	s_barrier
	s_add_i32 s11, 0, 0x18000
	s_add_i32 s14, 0, 0x1c000
	v_add_u32_e32 v154, s11, v143
	v_add_u32_e32 v170, s14, v143
	ds_read_b128 v[138:141], v154
	ds_read_b128 v[146:149], v154 offset:1024
	ds_read_b128 v[150:153], v154 offset:2048
	ds_read_b128 v[154:157], v154 offset:3072
	ds_read_b128 v[158:161], v170
	ds_read_b128 v[162:165], v170 offset:1024
	ds_read_b128 v[166:169], v170 offset:2048
	ds_read_b128 v[170:173], v170 offset:3072
	s_add_u32 s12, s60, 0x40000
	s_addc_u32 s13, s61, 0
	s_mov_b32 m0, s20
	ds_read_b128 v[174:177], v145 offset:32768
	ds_read_b128 v[178:181], v145 offset:33792
	ds_read_b128 v[198:201], v145 offset:34816
	ds_read_b128 v[202:205], v145 offset:35840
	ds_read_b128 v[206:209], v145 offset:36864
	ds_read_b128 v[210:213], v145 offset:37888
	ds_read_b128 v[214:217], v145 offset:38912
	ds_read_b128 v[232:235], v145 offset:39936
	global_load_lds_dwordx4 v132, s[12:13]
	s_mov_b32 m0, s21
	s_nop 0
	global_load_lds_dwordx4 v130, s[12:13]
	s_waitcnt vmcnt(8)
	s_waitcnt lgkmcnt(0)
	s_barrier
	s_setprio 1
	s_waitcnt lgkmcnt(0)
	v_mfma_f32_16x16x32_bf16 v[124:127], v[138:141], v[174:177], v[124:127]
	v_mfma_f32_16x16x32_bf16 v[120:123], v[150:153], v[174:177], v[120:123]
	v_mfma_f32_16x16x32_bf16 v[108:111], v[138:141], v[198:201], v[108:111]
	v_mfma_f32_16x16x32_bf16 v[104:107], v[150:153], v[198:201], v[104:107]
	v_mfma_f32_16x16x32_bf16 v[92:95], v[138:141], v[206:209], v[92:95]
	v_mfma_f32_16x16x32_bf16 v[88:91], v[150:153], v[206:209], v[88:91]
	v_mfma_f32_16x16x32_bf16 v[76:79], v[138:141], v[214:217], v[76:79]
	v_mfma_f32_16x16x32_bf16 v[72:75], v[150:153], v[214:217], v[72:75]
	v_mfma_f32_16x16x32_bf16 v[124:127], v[146:149], v[178:181], v[124:127]
	v_mfma_f32_16x16x32_bf16 v[120:123], v[154:157], v[178:181], v[120:123]
	v_mfma_f32_16x16x32_bf16 v[108:111], v[146:149], v[202:205], v[108:111]
	v_mfma_f32_16x16x32_bf16 v[104:107], v[154:157], v[202:205], v[104:107]
	v_mfma_f32_16x16x32_bf16 v[92:95], v[146:149], v[210:213], v[92:95]
	v_mfma_f32_16x16x32_bf16 v[88:91], v[154:157], v[210:213], v[88:91]
	v_mfma_f32_16x16x32_bf16 v[76:79], v[146:149], v[232:235], v[76:79]
	v_mfma_f32_16x16x32_bf16 v[72:75], v[154:157], v[232:235], v[72:75]
	v_mfma_f32_16x16x32_bf16 v[116:119], v[158:161], v[174:177], v[116:119]
	v_mfma_f32_16x16x32_bf16 v[112:115], v[166:169], v[174:177], v[112:115]
	v_mfma_f32_16x16x32_bf16 v[100:103], v[158:161], v[198:201], v[100:103]
	v_mfma_f32_16x16x32_bf16 v[96:99], v[166:169], v[198:201], v[96:99]
	v_mfma_f32_16x16x32_bf16 v[84:87], v[158:161], v[206:209], v[84:87]
	v_mfma_f32_16x16x32_bf16 v[80:83], v[166:169], v[206:209], v[80:83]
	v_mfma_f32_16x16x32_bf16 v[68:71], v[158:161], v[214:217], v[68:71]
	v_mfma_f32_16x16x32_bf16 v[64:67], v[166:169], v[214:217], v[64:67]
	v_mfma_f32_16x16x32_bf16 v[116:119], v[162:165], v[178:181], v[116:119]
	v_mfma_f32_16x16x32_bf16 v[112:115], v[170:173], v[178:181], v[112:115]
	v_mfma_f32_16x16x32_bf16 v[100:103], v[162:165], v[202:205], v[100:103]
	v_mfma_f32_16x16x32_bf16 v[96:99], v[170:173], v[202:205], v[96:99]
	v_mfma_f32_16x16x32_bf16 v[84:87], v[162:165], v[210:213], v[84:87]
	v_mfma_f32_16x16x32_bf16 v[80:83], v[170:173], v[210:213], v[80:83]
	v_mfma_f32_16x16x32_bf16 v[68:71], v[162:165], v[232:235], v[68:71]
	v_mfma_f32_16x16x32_bf16 v[64:67], v[170:173], v[232:235], v[64:67]
	s_setprio 0
	s_barrier
; #define PG8_STAGE(bufoff, gbase, voff) do { _Pragma("unroll") for (int _i = 0; _i < 2; ++_i) \
;         __builtin_amdgcn_global_load_lds((const unsigned*)((const char*)(gbase) + (voff)[_i]), (PG8_LAS unsigned*)(lds + (bufoff) + ldsw + _i * 8192), 16, 0, 0); } while (0)
; #define PG8_LDA(dst, b, h) do { _Pragma("unroll") for (int m = 0; m < 4; ++m) _Pragma("unroll") for (int k = 0; k < 2; ++k) dst[m][k] = *(const PG8_LAS bf16x8*)(lds + PG8_SA(b, h) + aoff + m * 2048 + k * 1024); } while (0)
; #define PG8_MMA(ai, bj, At, Bt) do { __builtin_amdgcn_s_setprio(1); _Pragma("unroll") for (int m = 0; m < 4; ++m) _Pragma("unroll") for (int n = 0; n < 2; ++n) _Pragma("unroll") for (int k = 0; k < 2; ++k) \
;         acc[ai][bj][m][n] = __builtin_amdgcn_mfma_f32_16x16x32_bf16(Bt[n][k], At[m][k], acc[ai][bj][m][n], 0, 0, 0); __builtin_amdgcn_s_setprio(0); } while (0)
; #define PG8_WAIT_V(n) asm volatile("s_waitcnt vmcnt(" #n ")" ::: "memory")
; #define PG8_WAIT_L(n) asm volatile("s_waitcnt lgkmcnt(" #n ")" ::: "memory")
; #define PG8_BAR __builtin_amdgcn_s_barrier()
; #define PG8_SCHED __builtin_amdgcn_sched_barrier(0)
; template <class Epi, class Sched, bool ALIGN_EPI = false, bool SP2 = false>
; __device__ __forceinline__ void gemm_phase(PG8_LAS unsigned char* lds, const Gemm g, const Sched& S, const Epi& E) {
;     ...
;             PG8_LDA(At, 1, 1); PG8_STAGE(PG8_SB(1, 0), b3, voffB); PG8_STAGE(PG8_SB(1, 1), b3 + hstep, voffB); PG8_STAGE(PG8_SA(1, 0), a3, voffA);
;             PG8_WAIT_V(8); PG8_WAIT_L(0); PG8_BAR; PG8_MMA(1, 0, At, B0); PG8_MMA(1, 1, At, B1); PG8_BAR; PG8_SCHED;
;     ...
;         if constexpr (ALIGN_EPI) { if (wr == 0) PG8_BAR; }
	s_add_i32 s11, s11, s3
	v_lshl_add_u64 v[182:183], v[182:183], 0, s[34:35]
	s_mov_b32 m0, s11
	ds_read_b128 v[174:177], v145 offset:49152
	ds_read_b128 v[178:181], v145 offset:50176
	ds_read_b128 v[198:201], v145 offset:51200
	ds_read_b128 v[202:205], v145 offset:52224
	ds_read_b128 v[206:209], v145 offset:53248
	ds_read_b128 v[210:213], v145 offset:54272
	ds_read_b128 v[214:217], v145 offset:55296
	ds_read_b128 v[232:235], v145 offset:56320
	global_load_lds_dwordx4 v[182:183], off
	s_add_i32 m0, s11, 0x2000
	s_add_u32 s12, s58, 0x40080
	v_lshl_add_u64 v[182:183], v[236:237], 0, s[34:35]
	s_addc_u32 s13, s59, 0
	s_add_i32 s11, s14, s3
	global_load_lds_dwordx4 v[182:183], off
	s_mov_b32 m0, s11
	s_nop 0
	global_load_lds_dwordx4 v188, s[12:13]
	s_add_i32 m0, s11, 0x2000
	s_nop 0
	global_load_lds_dwordx4 v128, s[12:13]
	v_lshl_add_u64 v[182:183], v[238:239], 0, s[34:35]
	s_mov_b32 m0, s29
	s_nop 0
	global_load_lds_dwordx4 v[182:183], off
	v_lshl_add_u64 v[182:183], v[240:241], 0, s[34:35]
	s_mov_b32 m0, s39
	s_nop 0
	global_load_lds_dwordx4 v[182:183], off
	s_waitcnt vmcnt(8)
	s_waitcnt lgkmcnt(0)
	s_barrier
	s_setprio 1
	s_waitcnt lgkmcnt(0)
	v_mfma_f32_16x16x32_bf16 v[60:63], v[138:141], v[174:177], v[60:63]
	v_mfma_f32_16x16x32_bf16 v[56:59], v[150:153], v[174:177], v[56:59]
	v_mfma_f32_16x16x32_bf16 v[44:47], v[138:141], v[198:201], v[44:47]
	v_mfma_f32_16x16x32_bf16 v[40:43], v[150:153], v[198:201], v[40:43]
	v_mfma_f32_16x16x32_bf16 v[28:31], v[138:141], v[206:209], v[28:31]
	v_mfma_f32_16x16x32_bf16 v[24:27], v[150:153], v[206:209], v[24:27]
	v_mfma_f32_16x16x32_bf16 v[12:15], v[138:141], v[214:217], v[12:15]
	v_mfma_f32_16x16x32_bf16 v[8:11], v[150:153], v[214:217], v[8:11]
	v_mfma_f32_16x16x32_bf16 v[60:63], v[146:149], v[178:181], v[60:63]
	v_mfma_f32_16x16x32_bf16 v[56:59], v[154:157], v[178:181], v[56:59]
	v_mfma_f32_16x16x32_bf16 v[44:47], v[146:149], v[202:205], v[44:47]
	v_mfma_f32_16x16x32_bf16 v[40:43], v[154:157], v[202:205], v[40:43]
	v_mfma_f32_16x16x32_bf16 v[28:31], v[146:149], v[210:213], v[28:31]
	v_mfma_f32_16x16x32_bf16 v[24:27], v[154:157], v[210:213], v[24:27]
	v_mfma_f32_16x16x32_bf16 v[12:15], v[146:149], v[232:235], v[12:15]
	v_mfma_f32_16x16x32_bf16 v[8:11], v[154:157], v[232:235], v[8:11]
	v_mfma_f32_16x16x32_bf16 v[52:55], v[158:161], v[174:177], v[52:55]
	v_mfma_f32_16x16x32_bf16 v[48:51], v[166:169], v[174:177], v[48:51]
	v_mfma_f32_16x16x32_bf16 v[36:39], v[158:161], v[198:201], v[36:39]
	v_mfma_f32_16x16x32_bf16 v[32:35], v[166:169], v[198:201], v[32:35]
	v_mfma_f32_16x16x32_bf16 v[20:23], v[158:161], v[206:209], v[20:23]
	v_mfma_f32_16x16x32_bf16 v[16:19], v[166:169], v[206:209], v[16:19]
	v_mfma_f32_16x16x32_bf16 v[4:7], v[158:161], v[214:217], v[4:7]
	v_mfma_f32_16x16x32_bf16 v[0:3], v[166:169], v[214:217], v[0:3]
	v_mfma_f32_16x16x32_bf16 v[52:55], v[162:165], v[178:181], v[52:55]
	v_mfma_f32_16x16x32_bf16 v[48:51], v[170:173], v[178:181], v[48:51]
	v_mfma_f32_16x16x32_bf16 v[36:39], v[162:165], v[202:205], v[36:39]
	v_mfma_f32_16x16x32_bf16 v[32:35], v[170:173], v[202:205], v[32:35]
	v_mfma_f32_16x16x32_bf16 v[20:23], v[162:165], v[210:213], v[20:23]
	v_mfma_f32_16x16x32_bf16 v[16:19], v[170:173], v[210:213], v[16:19]
	v_mfma_f32_16x16x32_bf16 v[4:7], v[162:165], v[232:235], v[4:7]
	v_mfma_f32_16x16x32_bf16 v[0:3], v[170:173], v[232:235], v[0:3]
	s_setprio 0
	s_barrier
	s_add_i32 s10, s10, 2
	s_add_u32 s56, s56, 0x100
	s_addc_u32 s57, s57, 0
	s_add_u32 s30, s30, 0x100
	s_addc_u32 s31, s31, 0
	s_cmp_gt_u32 s10, 13
	s_cbranch_scc0 .LBB0_438
	s_and_b64 vcc, exec, s[42:43]
	s_cbranch_vccz .LBB0_441
	s_barrier

; #define PG8_STAGE(bufoff, gbase, voff) do { _Pragma("unroll") for (int _i = 0; _i < 2; ++_i) \
;         __builtin_amdgcn_global_load_lds((const unsigned*)((const char*)(gbase) + (voff)[_i]), (PG8_LAS unsigned*)(lds + (bufoff) + ldsw + _i * 8192), 16, 0, 0); } while (0)
; #define PG8_LDA(dst, b, h) do { _Pragma("unroll") for (int m = 0; m < 4; ++m) _Pragma("unroll") for (int k = 0; k < 2; ++k) dst[m][k] = *(const PG8_LAS bf16x8*)(lds + PG8_SA(b, h) + aoff + m * 2048 + k * 1024); } while (0)
; #define PG8_LDB(dst, b, h) do { _Pragma("unroll") for (int n = 0; n < 2; ++n) _Pragma("unroll") for (int k = 0; k < 2; ++k) dst[n][k] = *(const PG8_LAS bf16x8*)(lds + PG8_SB(b, h) + boff + n * 2048 + k * 1024); } while (0)
; #define PG8_WAIT_V(n) asm volatile("s_waitcnt vmcnt(" #n ")" ::: "memory")
; #define PG8_WAIT_L(n) asm volatile("s_waitcnt lgkmcnt(" #n ")" ::: "memory")
; #define PG8_BAR __builtin_amdgcn_s_barrier()
; #define PG8_SCHED __builtin_amdgcn_sched_barrier(0)
; template <class Epi, class Sched, bool ALIGN_EPI = false, bool SP2 = false>
; __device__ __forceinline__ void gemm_phase(PG8_LAS unsigned char* lds, const Gemm g, const Sched& S, const Epi& E) {
;     ...
;         const char* nA = has_next ? (const char*)g.A + (size_t)nxt.pm * tstep : cA; const char* nB = has_next ? (const char*)g.Bt + (size_t)nxt.pn * tstep : cB;
;         for (int t = 0; t < nt; t += 2) {
;             const bool last = (t == nt - 2);
;             const char* a1 = cA + (size_t)(t + 1) * kstep;
;             const char* a2 = last ? nA : cA + (size_t)(t + 2) * kstep; const char* b2 = last ? nB : cB + (size_t)(t + 2) * kstep;
;             const char* a3 = a2 + kstep; const char* b3 = b2 + kstep;
;             if (last && has_next) S.a_ready(nxt);
;             if constexpr (SP2) {
;             PG8_LDB(B0, 0, 0); PG8_LDB(B1, 0, 1); PG8_SCHED; PG8_LDA(At, 0, 0); PG8_STAGE(PG8_SA(1, 1), a1 + hstep, voffA);
;             PG8_WAIT_V(8); PG8_WAIT_L(0); PG8_BAR; PG8_MMA(0, 0, At, B0); PG8_MMA(0, 1, At, B1); PG8_BAR; PG8_SCHED;
;             PG8_LDA(At, 0, 1); PG8_STAGE(PG8_SB(0, 0), b2, voffB); PG8_STAGE(PG8_SB(0, 1), b2 + hstep, voffB); PG8_STAGE(PG8_SA(0, 0), a2, voffA);
;             PG8_WAIT_V(8); PG8_WAIT_L(0); PG8_BAR; PG8_MMA(1, 0, At, B0); PG8_MMA(1, 1, At, B1); PG8_BAR; PG8_SCHED;
.LBB0_506:
	s_add_u32 s11, s60, 0xfffe0080
	s_addc_u32 s12, s61, -1
	s_add_i32 s13, 0, 0x10000
	s_cmp_eq_u32 s10, 4
	s_cselect_b32 vcc_hi, s55, s12
	s_cselect_b32 vcc_lo, s72, s11
	s_cselect_b32 s63, s53, s31
	s_cselect_b32 s62, s73, s30
	s_add_i32 s11, 0, 0x14000
	v_add_u32_e32 v140, s13, v171
	v_add_u32_e32 v166, s11, v171
	ds_read_b128 v[128:131], v140
	ds_read_b128 v[132:135], v140 offset:1024
	ds_read_b128 v[136:139], v140 offset:2048
	ds_read_b128 v[140:143], v140 offset:3072
	ds_read_b128 v[144:147], v166
	ds_read_b128 v[158:161], v166 offset:1024
	ds_read_b128 v[162:165], v166 offset:2048
	ds_read_b128 v[166:169], v166 offset:3072
	s_add_i32 m0, s8, 0xc000
	ds_read_b128 v[174:177], v173
	ds_read_b128 v[178:181], v173 offset:1024
	ds_read_b128 v[198:201], v173 offset:2048
	ds_read_b128 v[202:205], v173 offset:3072
	ds_read_b128 v[206:209], v173 offset:4096
	ds_read_b128 v[210:213], v173 offset:5120
	ds_read_b128 v[214:217], v173 offset:6144
	ds_read_b128 v[232:235], v173 offset:7168
	global_load_lds_dwordx4 v154, s[60:61]
	s_add_i32 m0, s8, 0xe000
	s_nop 0
	global_load_lds_dwordx4 v156, s[60:61]
	s_waitcnt vmcnt(8)
	s_waitcnt lgkmcnt(0)
	s_barrier
	s_setprio 1
	s_waitcnt lgkmcnt(0)
	v_mfma_f32_16x16x32_bf16 v[124:127], v[128:131], v[174:177], v[124:127]
	v_mfma_f32_16x16x32_bf16 v[120:123], v[136:139], v[174:177], v[120:123]
	v_mfma_f32_16x16x32_bf16 v[116:119], v[128:131], v[198:201], v[116:119]
	v_mfma_f32_16x16x32_bf16 v[112:115], v[136:139], v[198:201], v[112:115]
	v_mfma_f32_16x16x32_bf16 v[96:99], v[128:131], v[206:209], v[96:99]
	v_mfma_f32_16x16x32_bf16 v[92:95], v[136:139], v[206:209], v[92:95]
	v_mfma_f32_16x16x32_bf16 v[84:87], v[128:131], v[214:217], v[84:87]
	v_mfma_f32_16x16x32_bf16 v[80:83], v[136:139], v[214:217], v[80:83]
	v_mfma_f32_16x16x32_bf16 v[124:127], v[132:135], v[178:181], v[124:127]
	v_mfma_f32_16x16x32_bf16 v[120:123], v[140:143], v[178:181], v[120:123]
	v_mfma_f32_16x16x32_bf16 v[116:119], v[132:135], v[202:205], v[116:119]
	v_mfma_f32_16x16x32_bf16 v[112:115], v[140:143], v[202:205], v[112:115]
	v_mfma_f32_16x16x32_bf16 v[96:99], v[132:135], v[210:213], v[96:99]
	v_mfma_f32_16x16x32_bf16 v[92:95], v[140:143], v[210:213], v[92:95]
	v_mfma_f32_16x16x32_bf16 v[84:87], v[132:135], v[232:235], v[84:87]
	v_mfma_f32_16x16x32_bf16 v[80:83], v[140:143], v[232:235], v[80:83]
	v_mfma_f32_16x16x32_bf16 v[108:111], v[144:147], v[174:177], v[108:111]
	v_mfma_f32_16x16x32_bf16 v[104:107], v[162:165], v[174:177], v[104:107]
	v_mfma_f32_16x16x32_bf16 v[100:103], v[144:147], v[198:201], v[100:103]
	v_mfma_f32_16x16x32_bf16 v[88:91], v[162:165], v[198:201], v[88:91]
	v_mfma_f32_16x16x32_bf16 v[76:79], v[144:147], v[206:209], v[76:79]
	v_mfma_f32_16x16x32_bf16 v[72:75], v[162:165], v[206:209], v[72:75]
	v_mfma_f32_16x16x32_bf16 v[68:71], v[144:147], v[214:217], v[68:71]
	v_mfma_f32_16x16x32_bf16 v[64:67], v[162:165], v[214:217], v[64:67]
	v_mfma_f32_16x16x32_bf16 v[108:111], v[158:161], v[178:181], v[108:111]
	v_mfma_f32_16x16x32_bf16 v[104:107], v[166:169], v[178:181], v[104:107]
	v_mfma_f32_16x16x32_bf16 v[100:103], v[158:161], v[202:205], v[100:103]
	v_mfma_f32_16x16x32_bf16 v[88:91], v[166:169], v[202:205], v[88:91]
	v_mfma_f32_16x16x32_bf16 v[76:79], v[158:161], v[210:213], v[76:79]
	v_mfma_f32_16x16x32_bf16 v[72:75], v[166:169], v[210:213], v[72:75]
	v_mfma_f32_16x16x32_bf16 v[68:71], v[158:161], v[232:235], v[68:71]
	v_mfma_f32_16x16x32_bf16 v[64:67], v[166:169], v[232:235], v[64:67]
	s_setprio 0
	s_barrier
	s_add_i32 s12, s13, s3
	v_lshl_add_u64 v[182:183], s[62:63], 0, v[188:189]
	s_mov_b32 m0, s12
	ds_read_b128 v[174:177], v173 offset:16384
	ds_read_b128 v[178:181], v173 offset:17408
	ds_read_b128 v[198:201], v173 offset:18432
	ds_read_b128 v[202:205], v173 offset:19456
	ds_read_b128 v[206:209], v173 offset:20480
	ds_read_b128 v[210:213], v173 offset:21504
	ds_read_b128 v[214:217], v173 offset:22528
	ds_read_b128 v[232:235], v173 offset:23552
	global_load_lds_dwordx4 v[182:183], off
	s_add_i32 m0, s12, 0x2000
	s_add_u32 s12, s62, 0x20000
	v_lshl_add_u64 v[236:237], s[62:63], 0, v[148:149]
	s_addc_u32 s13, s63, 0
	s_add_i32 s11, s11, s3
	global_load_lds_dwordx4 v[236:237], off
	s_mov_b32 m0, s11
	v_lshl_add_u64 v[240:241], vcc, 0, v[150:151]
	global_load_lds_dwordx4 v188, s[12:13]
	s_add_i32 m0, s11, 0x2000
	s_nop 0
	global_load_lds_dwordx4 v148, s[12:13]
	v_lshl_add_u64 v[238:239], vcc, 0, v[152:153]
	s_mov_b32 m0, s8
	s_nop 0
	global_load_lds_dwordx4 v[238:239], off
	s_mov_b32 m0, s9
	s_nop 0
	global_load_lds_dwordx4 v[240:241], off
	s_waitcnt vmcnt(8)
	s_waitcnt lgkmcnt(0)
	s_barrier
; #define PG8_STAGE(bufoff, gbase, voff) do { _Pragma("unroll") for (int _i = 0; _i < 2; ++_i) \
;         __builtin_amdgcn_global_load_lds((const unsigned*)((const char*)(gbase) + (voff)[_i]), (PG8_LAS unsigned*)(lds + (bufoff) + ldsw + _i * 8192), 16, 0, 0); } while (0)
; #define PG8_LDA(dst, b, h) do { _Pragma("unroll") for (int m = 0; m < 4; ++m) _Pragma("unroll") for (int k = 0; k < 2; ++k) dst[m][k] = *(const PG8_LAS bf16x8*)(lds + PG8_SA(b, h) + aoff + m * 2048 + k * 1024); } while (0)
; #define PG8_LDB(dst, b, h) do { _Pragma("unroll") for (int n = 0; n < 2; ++n) _Pragma("unroll") for (int k = 0; k < 2; ++k) dst[n][k] = *(const PG8_LAS bf16x8*)(lds + PG8_SB(b, h) + boff + n * 2048 + k * 1024); } while (0)
; #define PG8_MMA(ai, bj, At, Bt) do { __builtin_amdgcn_s_setprio(1); _Pragma("unroll") for (int m = 0; m < 4; ++m) _Pragma("unroll") for (int n = 0; n < 2; ++n) _Pragma("unroll") for (int k = 0; k < 2; ++k) \
;         acc[ai][bj][m][n] = __builtin_amdgcn_mfma_f32_16x16x32_bf16(Bt[n][k], At[m][k], acc[ai][bj][m][n], 0, 0, 0); __builtin_amdgcn_s_setprio(0); } while (0)
; #define PG8_WAIT_V(n) asm volatile("s_waitcnt vmcnt(" #n ")" ::: "memory")
; #define PG8_WAIT_L(n) asm volatile("s_waitcnt lgkmcnt(" #n ")" ::: "memory")
; #define PG8_BAR __builtin_amdgcn_s_barrier()
; #define PG8_SCHED __builtin_amdgcn_sched_barrier(0)
; template <class Epi, class Sched, bool ALIGN_EPI = false, bool SP2 = false>
; __device__ __forceinline__ void gemm_phase(PG8_LAS unsigned char* lds, const Gemm g, const Sched& S, const Epi& E) {
;     ...
;             PG8_WAIT_V(8); PG8_WAIT_L(0); PG8_BAR; PG8_MMA(1, 0, At, B0); PG8_MMA(1, 1, At, B1); PG8_BAR; PG8_SCHED;
;             PG8_LDB(B0, 1, 0); PG8_LDB(B1, 1, 1); PG8_SCHED; PG8_LDA(At, 1, 0); PG8_STAGE(PG8_SA(0, 1), a2 + hstep, voffA);
;             PG8_WAIT_V(8); PG8_WAIT_L(0); PG8_BAR; PG8_MMA(0, 0, At, B0); PG8_MMA(0, 1, At, B1); PG8_BAR; PG8_SCHED;
	s_setprio 1
	s_waitcnt lgkmcnt(0)
	v_mfma_f32_16x16x32_bf16 v[60:63], v[128:131], v[174:177], v[60:63]
	v_mfma_f32_16x16x32_bf16 v[56:59], v[136:139], v[174:177], v[56:59]
	v_mfma_f32_16x16x32_bf16 v[48:51], v[128:131], v[198:201], v[48:51]
	v_mfma_f32_16x16x32_bf16 v[40:43], v[136:139], v[198:201], v[40:43]
	v_mfma_f32_16x16x32_bf16 v[32:35], v[128:131], v[206:209], v[32:35]
	v_mfma_f32_16x16x32_bf16 v[24:27], v[136:139], v[206:209], v[24:27]
	v_mfma_f32_16x16x32_bf16 v[16:19], v[128:131], v[214:217], v[16:19]
	v_mfma_f32_16x16x32_bf16 v[8:11], v[136:139], v[214:217], v[8:11]
	v_mfma_f32_16x16x32_bf16 v[60:63], v[132:135], v[178:181], v[60:63]
	v_mfma_f32_16x16x32_bf16 v[56:59], v[140:143], v[178:181], v[56:59]
	v_mfma_f32_16x16x32_bf16 v[48:51], v[132:135], v[202:205], v[48:51]
	v_mfma_f32_16x16x32_bf16 v[40:43], v[140:143], v[202:205], v[40:43]
	v_mfma_f32_16x16x32_bf16 v[32:35], v[132:135], v[210:213], v[32:35]
	v_mfma_f32_16x16x32_bf16 v[24:27], v[140:143], v[210:213], v[24:27]
	v_mfma_f32_16x16x32_bf16 v[16:19], v[132:135], v[232:235], v[16:19]
	v_mfma_f32_16x16x32_bf16 v[8:11], v[140:143], v[232:235], v[8:11]
	v_mfma_f32_16x16x32_bf16 v[52:55], v[144:147], v[174:177], v[52:55]
	v_mfma_f32_16x16x32_bf16 v[44:47], v[162:165], v[174:177], v[44:47]
	v_mfma_f32_16x16x32_bf16 v[36:39], v[144:147], v[198:201], v[36:39]
	v_mfma_f32_16x16x32_bf16 v[28:31], v[162:165], v[198:201], v[28:31]
	v_mfma_f32_16x16x32_bf16 v[20:23], v[144:147], v[206:209], v[20:23]
	v_mfma_f32_16x16x32_bf16 v[12:15], v[162:165], v[206:209], v[12:15]
	v_mfma_f32_16x16x32_bf16 v[4:7], v[144:147], v[214:217], v[4:7]
	v_mfma_f32_16x16x32_bf16 v[0:3], v[162:165], v[214:217], v[0:3]
	v_mfma_f32_16x16x32_bf16 v[52:55], v[158:161], v[178:181], v[52:55]
	v_mfma_f32_16x16x32_bf16 v[44:47], v[166:169], v[178:181], v[44:47]
	v_mfma_f32_16x16x32_bf16 v[36:39], v[158:161], v[202:205], v[36:39]
	v_mfma_f32_16x16x32_bf16 v[28:31], v[166:169], v[202:205], v[28:31]
	v_mfma_f32_16x16x32_bf16 v[20:23], v[158:161], v[210:213], v[20:23]
	v_mfma_f32_16x16x32_bf16 v[12:15], v[166:169], v[210:213], v[12:15]
	v_mfma_f32_16x16x32_bf16 v[4:7], v[158:161], v[232:235], v[4:7]
	v_mfma_f32_16x16x32_bf16 v[0:3], v[166:169], v[232:235], v[0:3]
	s_setprio 0
	s_barrier
	s_add_i32 s11, 0, 0x18000
	s_add_i32 s14, 0, 0x1c000
	v_add_u32_e32 v140, s11, v171
	v_add_u32_e32 v166, s14, v171
	ds_read_b128 v[128:131], v140
	ds_read_b128 v[132:135], v140 offset:1024
	ds_read_b128 v[136:139], v140 offset:2048
	ds_read_b128 v[140:143], v140 offset:3072
	ds_read_b128 v[144:147], v166
	ds_read_b128 v[158:161], v166 offset:1024
	ds_read_b128 v[162:165], v166 offset:2048
	ds_read_b128 v[166:169], v166 offset:3072
	s_add_u32 s12, vcc_lo, 0x20000
	s_addc_u32 s13, vcc_hi, 0
	s_mov_b32 m0, s20
	ds_read_b128 v[174:177], v173 offset:32768
	ds_read_b128 v[178:181], v173 offset:33792
	ds_read_b128 v[198:201], v173 offset:34816
	ds_read_b128 v[202:205], v173 offset:35840
	ds_read_b128 v[206:209], v173 offset:36864
	ds_read_b128 v[210:213], v173 offset:37888
	ds_read_b128 v[214:217], v173 offset:38912
	ds_read_b128 v[232:235], v173 offset:39936
	global_load_lds_dwordx4 v152, s[12:13]
	s_mov_b32 m0, s21
	s_nop 0
	global_load_lds_dwordx4 v150, s[12:13]
	s_waitcnt vmcnt(8)
	s_waitcnt lgkmcnt(0)
	s_barrier
	s_setprio 1
	s_waitcnt lgkmcnt(0)
	v_mfma_f32_16x16x32_bf16 v[124:127], v[128:131], v[174:177], v[124:127]
	v_mfma_f32_16x16x32_bf16 v[120:123], v[136:139], v[174:177], v[120:123]
	v_mfma_f32_16x16x32_bf16 v[116:119], v[128:131], v[198:201], v[116:119]
	v_mfma_f32_16x16x32_bf16 v[112:115], v[136:139], v[198:201], v[112:115]
	v_mfma_f32_16x16x32_bf16 v[96:99], v[128:131], v[206:209], v[96:99]
	v_mfma_f32_16x16x32_bf16 v[92:95], v[136:139], v[206:209], v[92:95]
	v_mfma_f32_16x16x32_bf16 v[84:87], v[128:131], v[214:217], v[84:87]
	v_mfma_f32_16x16x32_bf16 v[80:83], v[136:139], v[214:217], v[80:83]
	v_mfma_f32_16x16x32_bf16 v[124:127], v[132:135], v[178:181], v[124:127]
	v_mfma_f32_16x16x32_bf16 v[120:123], v[140:143], v[178:181], v[120:123]
	v_mfma_f32_16x16x32_bf16 v[116:119], v[132:135], v[202:205], v[116:119]
	v_mfma_f32_16x16x32_bf16 v[112:115], v[140:143], v[202:205], v[112:115]
	v_mfma_f32_16x16x32_bf16 v[96:99], v[132:135], v[210:213], v[96:99]
	v_mfma_f32_16x16x32_bf16 v[92:95], v[140:143], v[210:213], v[92:95]
	v_mfma_f32_16x16x32_bf16 v[84:87], v[132:135], v[232:235], v[84:87]
	v_mfma_f32_16x16x32_bf16 v[80:83], v[140:143], v[232:235], v[80:83]
	v_mfma_f32_16x16x32_bf16 v[108:111], v[144:147], v[174:177], v[108:111]
	v_mfma_f32_16x16x32_bf16 v[104:107], v[162:165], v[174:177], v[104:107]
	v_mfma_f32_16x16x32_bf16 v[100:103], v[144:147], v[198:201], v[100:103]
	v_mfma_f32_16x16x32_bf16 v[88:91], v[162:165], v[198:201], v[88:91]
	v_mfma_f32_16x16x32_bf16 v[76:79], v[144:147], v[206:209], v[76:79]
	v_mfma_f32_16x16x32_bf16 v[72:75], v[162:165], v[206:209], v[72:75]
	v_mfma_f32_16x16x32_bf16 v[68:71], v[144:147], v[214:217], v[68:71]
	v_mfma_f32_16x16x32_bf16 v[64:67], v[162:165], v[214:217], v[64:67]
	v_mfma_f32_16x16x32_bf16 v[108:111], v[158:161], v[178:181], v[108:111]
	v_mfma_f32_16x16x32_bf16 v[104:107], v[166:169], v[178:181], v[104:107]
	v_mfma_f32_16x16x32_bf16 v[100:103], v[158:161], v[202:205], v[100:103]
	v_mfma_f32_16x16x32_bf16 v[88:91], v[166:169], v[202:205], v[88:91]
	v_mfma_f32_16x16x32_bf16 v[76:79], v[158:161], v[210:213], v[76:79]
	v_mfma_f32_16x16x32_bf16 v[72:75], v[166:169], v[210:213], v[72:75]
	v_mfma_f32_16x16x32_bf16 v[68:71], v[158:161], v[232:235], v[68:71]
	v_mfma_f32_16x16x32_bf16 v[64:67], v[166:169], v[232:235], v[64:67]
	s_setprio 0
	s_barrier
; #define PG8_STAGE(bufoff, gbase, voff) do { _Pragma("unroll") for (int _i = 0; _i < 2; ++_i) \
;         __builtin_amdgcn_global_load_lds((const unsigned*)((const char*)(gbase) + (voff)[_i]), (PG8_LAS unsigned*)(lds + (bufoff) + ldsw + _i * 8192), 16, 0, 0); } while (0)
; #define PG8_LDA(dst, b, h) do { _Pragma("unroll") for (int m = 0; m < 4; ++m) _Pragma("unroll") for (int k = 0; k < 2; ++k) dst[m][k] = *(const PG8_LAS bf16x8*)(lds + PG8_SA(b, h) + aoff + m * 2048 + k * 1024); } while (0)
; #define PG8_MMA(ai, bj, At, Bt) do { __builtin_amdgcn_s_setprio(1); _Pragma("unroll") for (int m = 0; m < 4; ++m) _Pragma("unroll") for (int n = 0; n < 2; ++n) _Pragma("unroll") for (int k = 0; k < 2; ++k) \
;         acc[ai][bj][m][n] = __builtin_amdgcn_mfma_f32_16x16x32_bf16(Bt[n][k], At[m][k], acc[ai][bj][m][n], 0, 0, 0); __builtin_amdgcn_s_setprio(0); } while (0)
; #define PG8_WAIT_V(n) asm volatile("s_waitcnt vmcnt(" #n ")" ::: "memory")
; #define PG8_WAIT_L(n) asm volatile("s_waitcnt lgkmcnt(" #n ")" ::: "memory")
; #define PG8_BAR __builtin_amdgcn_s_barrier()
; #define PG8_SCHED __builtin_amdgcn_sched_barrier(0)
; template <class Epi, class Sched, bool ALIGN_EPI = false, bool SP2 = false>
; __device__ __forceinline__ void gemm_phase(PG8_LAS unsigned char* lds, const Gemm g, const Sched& S, const Epi& E) {
;     ...
;             PG8_LDA(At, 1, 1); PG8_STAGE(PG8_SB(1, 0), b3, voffB); PG8_STAGE(PG8_SB(1, 1), b3 + hstep, voffB); PG8_STAGE(PG8_SA(1, 0), a3, voffA);
;             PG8_WAIT_V(8); PG8_WAIT_L(0); PG8_BAR; PG8_MMA(1, 0, At, B0); PG8_MMA(1, 1, At, B1); PG8_BAR; PG8_SCHED;
;     ...
;         if constexpr (ALIGN_EPI) { if (wr == 0) PG8_BAR; }
	s_add_i32 s11, s11, s3
	v_lshl_add_u64 v[182:183], v[182:183], 0, s[34:35]
	s_mov_b32 m0, s11
	ds_read_b128 v[174:177], v173 offset:49152
	ds_read_b128 v[178:181], v173 offset:50176
	ds_read_b128 v[198:201], v173 offset:51200
	ds_read_b128 v[202:205], v173 offset:52224
	ds_read_b128 v[206:209], v173 offset:53248
	ds_read_b128 v[210:213], v173 offset:54272
	ds_read_b128 v[214:217], v173 offset:55296
	ds_read_b128 v[232:235], v173 offset:56320
	global_load_lds_dwordx4 v[182:183], off
	s_add_i32 m0, s11, 0x2000
	s_add_u32 s12, s62, 0x20080
	v_lshl_add_u64 v[182:183], v[236:237], 0, s[34:35]
	s_addc_u32 s13, s63, 0
	s_add_i32 s11, s14, s3
	global_load_lds_dwordx4 v[182:183], off
	s_mov_b32 m0, s11
	s_nop 0
	global_load_lds_dwordx4 v188, s[12:13]
	s_add_i32 m0, s11, 0x2000
	s_nop 0
	global_load_lds_dwordx4 v148, s[12:13]
	v_lshl_add_u64 v[182:183], v[238:239], 0, s[34:35]
	s_mov_b32 m0, s24
	s_nop 0
	global_load_lds_dwordx4 v[182:183], off
	v_lshl_add_u64 v[182:183], v[240:241], 0, s[34:35]
	s_mov_b32 m0, s29
	s_nop 0
	global_load_lds_dwordx4 v[182:183], off
	s_waitcnt vmcnt(8)
	s_waitcnt lgkmcnt(0)
	s_barrier
	s_setprio 1
	s_waitcnt lgkmcnt(0)
	v_mfma_f32_16x16x32_bf16 v[60:63], v[128:131], v[174:177], v[60:63]
	v_mfma_f32_16x16x32_bf16 v[56:59], v[136:139], v[174:177], v[56:59]
	v_mfma_f32_16x16x32_bf16 v[48:51], v[128:131], v[198:201], v[48:51]
	v_mfma_f32_16x16x32_bf16 v[40:43], v[136:139], v[198:201], v[40:43]
	v_mfma_f32_16x16x32_bf16 v[32:35], v[128:131], v[206:209], v[32:35]
	v_mfma_f32_16x16x32_bf16 v[24:27], v[136:139], v[206:209], v[24:27]
	v_mfma_f32_16x16x32_bf16 v[16:19], v[128:131], v[214:217], v[16:19]
	v_mfma_f32_16x16x32_bf16 v[8:11], v[136:139], v[214:217], v[8:11]
	v_mfma_f32_16x16x32_bf16 v[60:63], v[132:135], v[178:181], v[60:63]
	v_mfma_f32_16x16x32_bf16 v[56:59], v[140:143], v[178:181], v[56:59]
	v_mfma_f32_16x16x32_bf16 v[48:51], v[132:135], v[202:205], v[48:51]
	v_mfma_f32_16x16x32_bf16 v[40:43], v[140:143], v[202:205], v[40:43]
	v_mfma_f32_16x16x32_bf16 v[32:35], v[132:135], v[210:213], v[32:35]
	v_mfma_f32_16x16x32_bf16 v[24:27], v[140:143], v[210:213], v[24:27]
	v_mfma_f32_16x16x32_bf16 v[16:19], v[132:135], v[232:235], v[16:19]
	v_mfma_f32_16x16x32_bf16 v[8:11], v[140:143], v[232:235], v[8:11]
	v_mfma_f32_16x16x32_bf16 v[52:55], v[144:147], v[174:177], v[52:55]
	v_mfma_f32_16x16x32_bf16 v[44:47], v[162:165], v[174:177], v[44:47]
	v_mfma_f32_16x16x32_bf16 v[36:39], v[144:147], v[198:201], v[36:39]
	v_mfma_f32_16x16x32_bf16 v[28:31], v[162:165], v[198:201], v[28:31]
	v_mfma_f32_16x16x32_bf16 v[20:23], v[144:147], v[206:209], v[20:23]
	v_mfma_f32_16x16x32_bf16 v[12:15], v[162:165], v[206:209], v[12:15]
	v_mfma_f32_16x16x32_bf16 v[4:7], v[144:147], v[214:217], v[4:7]
	v_mfma_f32_16x16x32_bf16 v[0:3], v[162:165], v[214:217], v[0:3]
	v_mfma_f32_16x16x32_bf16 v[52:55], v[158:161], v[178:181], v[52:55]
	v_mfma_f32_16x16x32_bf16 v[44:47], v[166:169], v[178:181], v[44:47]
	v_mfma_f32_16x16x32_bf16 v[36:39], v[158:161], v[202:205], v[36:39]
	v_mfma_f32_16x16x32_bf16 v[28:31], v[166:169], v[202:205], v[28:31]
	v_mfma_f32_16x16x32_bf16 v[20:23], v[158:161], v[210:213], v[20:23]
	v_mfma_f32_16x16x32_bf16 v[12:15], v[166:169], v[210:213], v[12:15]
	v_mfma_f32_16x16x32_bf16 v[4:7], v[158:161], v[232:235], v[4:7]
	v_mfma_f32_16x16x32_bf16 v[0:3], v[166:169], v[232:235], v[0:3]
	s_setprio 0
	s_barrier
	s_add_i32 s10, s10, 2
	s_add_u32 s60, s60, 0x100
	s_addc_u32 s61, s61, 0
	s_add_u32 s30, s30, 0x100
	s_addc_u32 s31, s31, 0
	s_cmp_gt_u32 s10, 5
	s_cbranch_scc0 .LBB0_506
	s_and_b64 vcc, exec, s[50:51]
	s_cbranch_vccz .LBB0_509
	s_barrier

; #define PG8_STAGE(bufoff, gbase, voff) do { _Pragma("unroll") for (int _i = 0; _i < 2; ++_i) \
;         __builtin_amdgcn_global_load_lds((const unsigned*)((const char*)(gbase) + (voff)[_i]), (PG8_LAS unsigned*)(lds + (bufoff) + ldsw + _i * 8192), 16, 0, 0); } while (0)
; #define PG8_LDA(dst, b, h) do { _Pragma("unroll") for (int m = 0; m < 4; ++m) _Pragma("unroll") for (int k = 0; k < 2; ++k) dst[m][k] = *(const PG8_LAS bf16x8*)(lds + PG8_SA(b, h) + aoff + m * 2048 + k * 1024); } while (0)
; #define PG8_LDB(dst, b, h) do { _Pragma("unroll") for (int n = 0; n < 2; ++n) _Pragma("unroll") for (int k = 0; k < 2; ++k) dst[n][k] = *(const PG8_LAS bf16x8*)(lds + PG8_SB(b, h) + boff + n * 2048 + k * 1024); } while (0)
; #define PG8_WAIT_V(n) asm volatile("s_waitcnt vmcnt(" #n ")" ::: "memory")
; #define PG8_WAIT_L(n) asm volatile("s_waitcnt lgkmcnt(" #n ")" ::: "memory")
; #define PG8_BAR __builtin_amdgcn_s_barrier()
; #define PG8_SCHED __builtin_amdgcn_sched_barrier(0)
; template <class Epi, class Sched, bool ALIGN_EPI = false, bool SP2 = false>
; __device__ __forceinline__ void gemm_phase(PG8_LAS unsigned char* lds, const Gemm g, const Sched& S, const Epi& E) {
;     ...
;         const char* nA = has_next ? (const char*)g.A + (size_t)nxt.pm * tstep : cA; const char* nB = has_next ? (const char*)g.Bt + (size_t)nxt.pn * tstep : cB;
;         for (int t = 0; t < nt; t += 2) {
;             const bool last = (t == nt - 2);
;             const char* a1 = cA + (size_t)(t + 1) * kstep;
;             const char* a2 = last ? nA : cA + (size_t)(t + 2) * kstep; const char* b2 = last ? nB : cB + (size_t)(t + 2) * kstep;
;             const char* a3 = a2 + kstep; const char* b3 = b2 + kstep;
;             if (last && has_next) S.a_ready(nxt);
;             if constexpr (SP2) {
;             PG8_LDB(B0, 0, 0); PG8_LDB(B1, 0, 1); PG8_SCHED; PG8_LDA(At, 0, 0); PG8_STAGE(PG8_SA(1, 1), a1 + hstep, voffA);
;             PG8_WAIT_V(8); PG8_WAIT_L(0); PG8_BAR; PG8_MMA(0, 0, At, B0); PG8_MMA(0, 1, At, B1); PG8_BAR; PG8_SCHED;
;             PG8_LDA(At, 0, 1); PG8_STAGE(PG8_SB(0, 0), b2, voffB); PG8_STAGE(PG8_SB(0, 1), b2 + hstep, voffB); PG8_STAGE(PG8_SA(0, 0), a2, voffA);
;             PG8_WAIT_V(8); PG8_WAIT_L(0); PG8_BAR; PG8_MMA(1, 0, At, B0); PG8_MMA(1, 1, At, B1); PG8_BAR; PG8_SCHED;
.LBB0_574:
	s_add_u32 s11, s58, 0xfffe0080
	s_addc_u32 s12, s59, -1
	s_add_i32 s13, 0, 0x10000
	s_cmp_eq_u32 s10, 4
	s_cselect_b32 s63, s53, s12
	s_cselect_b32 s62, vcc_lo, s11
	s_cselect_b32 s61, s51, s31
	s_cselect_b32 s60, vcc_hi, s30
	s_add_i32 s11, 0, 0x14000
	v_add_u32_e32 v140, s13, v233
	v_add_u32_e32 v156, s11, v233
	ds_read_b128 v[128:131], v140
	ds_read_b128 v[132:135], v140 offset:1024
	ds_read_b128 v[136:139], v140 offset:2048
	ds_read_b128 v[140:143], v140 offset:3072
	ds_read_b128 v[144:147], v156
	ds_read_b128 v[148:151], v156 offset:1024
	ds_read_b128 v[152:155], v156 offset:2048
	ds_read_b128 v[156:159], v156 offset:3072
	s_add_i32 m0, s20, 0xc000
	ds_read_b128 v[160:163], v235
	ds_read_b128 v[164:167], v235 offset:1024
	ds_read_b128 v[168:171], v235 offset:2048
	ds_read_b128 v[172:175], v235 offset:3072
	ds_read_b128 v[176:179], v235 offset:4096
	ds_read_b128 v[180:183], v235 offset:5120
	ds_read_b128 v[208:211], v235 offset:6144
	ds_read_b128 v[212:215], v235 offset:7168
	global_load_lds_dwordx4 v204, s[58:59]
	s_add_i32 m0, s20, 0xe000
	s_nop 0
	global_load_lds_dwordx4 v206, s[58:59]
	s_waitcnt vmcnt(8)
	s_waitcnt lgkmcnt(0)
	s_barrier
	s_setprio 1
	s_waitcnt lgkmcnt(0)
	v_mfma_f32_16x16x32_bf16 v[124:127], v[128:131], v[160:163], v[124:127]
	v_mfma_f32_16x16x32_bf16 v[120:123], v[136:139], v[160:163], v[120:123]
	v_mfma_f32_16x16x32_bf16 v[108:111], v[128:131], v[168:171], v[108:111]
	v_mfma_f32_16x16x32_bf16 v[104:107], v[136:139], v[168:171], v[104:107]
	v_mfma_f32_16x16x32_bf16 v[92:95], v[128:131], v[176:179], v[92:95]
	v_mfma_f32_16x16x32_bf16 v[88:91], v[136:139], v[176:179], v[88:91]
	v_mfma_f32_16x16x32_bf16 v[76:79], v[128:131], v[208:211], v[76:79]
	v_mfma_f32_16x16x32_bf16 v[72:75], v[136:139], v[208:211], v[72:75]
	v_mfma_f32_16x16x32_bf16 v[124:127], v[132:135], v[164:167], v[124:127]
	v_mfma_f32_16x16x32_bf16 v[120:123], v[140:143], v[164:167], v[120:123]
	v_mfma_f32_16x16x32_bf16 v[108:111], v[132:135], v[172:175], v[108:111]
	v_mfma_f32_16x16x32_bf16 v[104:107], v[140:143], v[172:175], v[104:107]
	v_mfma_f32_16x16x32_bf16 v[92:95], v[132:135], v[180:183], v[92:95]
	v_mfma_f32_16x16x32_bf16 v[88:91], v[140:143], v[180:183], v[88:91]
	v_mfma_f32_16x16x32_bf16 v[76:79], v[132:135], v[212:215], v[76:79]
	v_mfma_f32_16x16x32_bf16 v[72:75], v[140:143], v[212:215], v[72:75]
	v_mfma_f32_16x16x32_bf16 v[116:119], v[144:147], v[160:163], v[116:119]
	v_mfma_f32_16x16x32_bf16 v[112:115], v[152:155], v[160:163], v[112:115]
	v_mfma_f32_16x16x32_bf16 v[100:103], v[144:147], v[168:171], v[100:103]
	v_mfma_f32_16x16x32_bf16 v[96:99], v[152:155], v[168:171], v[96:99]
	v_mfma_f32_16x16x32_bf16 v[84:87], v[144:147], v[176:179], v[84:87]
	v_mfma_f32_16x16x32_bf16 v[80:83], v[152:155], v[176:179], v[80:83]
	v_mfma_f32_16x16x32_bf16 v[68:71], v[144:147], v[208:211], v[68:71]
	v_mfma_f32_16x16x32_bf16 v[64:67], v[152:155], v[208:211], v[64:67]
	v_mfma_f32_16x16x32_bf16 v[116:119], v[148:151], v[164:167], v[116:119]
	v_mfma_f32_16x16x32_bf16 v[112:115], v[156:159], v[164:167], v[112:115]
	v_mfma_f32_16x16x32_bf16 v[100:103], v[148:151], v[172:175], v[100:103]
	v_mfma_f32_16x16x32_bf16 v[96:99], v[156:159], v[172:175], v[96:99]
	v_mfma_f32_16x16x32_bf16 v[84:87], v[148:151], v[180:183], v[84:87]
	v_mfma_f32_16x16x32_bf16 v[80:83], v[156:159], v[180:183], v[80:83]
	v_mfma_f32_16x16x32_bf16 v[68:71], v[148:151], v[212:215], v[68:71]
	v_mfma_f32_16x16x32_bf16 v[64:67], v[156:159], v[212:215], v[64:67]
	s_setprio 0
	s_barrier
	s_add_i32 s12, s13, s9
	v_lshl_add_u64 v[216:217], s[60:61], 0, v[188:189]
	s_mov_b32 m0, s12
	ds_read_b128 v[160:163], v235 offset:16384
	ds_read_b128 v[164:167], v235 offset:17408
	ds_read_b128 v[168:171], v235 offset:18432
	ds_read_b128 v[172:175], v235 offset:19456
	ds_read_b128 v[176:179], v235 offset:20480
	ds_read_b128 v[180:183], v235 offset:21504
	ds_read_b128 v[208:211], v235 offset:22528
	ds_read_b128 v[212:215], v235 offset:23552
	global_load_lds_dwordx4 v[216:217], off
	s_add_i32 m0, s12, 0x2000
	s_add_u32 s12, s60, 0x20000
	v_lshl_add_u64 v[236:237], s[60:61], 0, v[198:199]
	s_addc_u32 s13, s61, 0
	s_add_i32 s11, s11, s9
	global_load_lds_dwordx4 v[236:237], off
	s_mov_b32 m0, s11
	v_lshl_add_u64 v[240:241], s[62:63], 0, v[200:201]
	global_load_lds_dwordx4 v188, s[12:13]
	s_add_i32 m0, s11, 0x2000
	s_nop 0
	global_load_lds_dwordx4 v198, s[12:13]
	v_lshl_add_u64 v[238:239], s[62:63], 0, v[202:203]
	s_mov_b32 m0, s20
	s_nop 0
	global_load_lds_dwordx4 v[238:239], off
	s_mov_b32 m0, s21
	s_nop 0
	global_load_lds_dwordx4 v[240:241], off
	s_waitcnt vmcnt(8)
	s_waitcnt lgkmcnt(0)
	s_barrier
; #define PG8_STAGE(bufoff, gbase, voff) do { _Pragma("unroll") for (int _i = 0; _i < 2; ++_i) \
;         __builtin_amdgcn_global_load_lds((const unsigned*)((const char*)(gbase) + (voff)[_i]), (PG8_LAS unsigned*)(lds + (bufoff) + ldsw + _i * 8192), 16, 0, 0); } while (0)
; #define PG8_LDA(dst, b, h) do { _Pragma("unroll") for (int m = 0; m < 4; ++m) _Pragma("unroll") for (int k = 0; k < 2; ++k) dst[m][k] = *(const PG8_LAS bf16x8*)(lds + PG8_SA(b, h) + aoff + m * 2048 + k * 1024); } while (0)
; #define PG8_LDB(dst, b, h) do { _Pragma("unroll") for (int n = 0; n < 2; ++n) _Pragma("unroll") for (int k = 0; k < 2; ++k) dst[n][k] = *(const PG8_LAS bf16x8*)(lds + PG8_SB(b, h) + boff + n * 2048 + k * 1024); } while (0)
; #define PG8_MMA(ai, bj, At, Bt) do { __builtin_amdgcn_s_setprio(1); _Pragma("unroll") for (int m = 0; m < 4; ++m) _Pragma("unroll") for (int n = 0; n < 2; ++n) _Pragma("unroll") for (int k = 0; k < 2; ++k) \
;         acc[ai][bj][m][n] = __builtin_amdgcn_mfma_f32_16x16x32_bf16(Bt[n][k], At[m][k], acc[ai][bj][m][n], 0, 0, 0); __builtin_amdgcn_s_setprio(0); } while (0)
; #define PG8_WAIT_V(n) asm volatile("s_waitcnt vmcnt(" #n ")" ::: "memory")
; #define PG8_WAIT_L(n) asm volatile("s_waitcnt lgkmcnt(" #n ")" ::: "memory")
; #define PG8_BAR __builtin_amdgcn_s_barrier()
; #define PG8_SCHED __builtin_amdgcn_sched_barrier(0)
; template <class Epi, class Sched, bool ALIGN_EPI = false, bool SP2 = false>
; __device__ __forceinline__ void gemm_phase(PG8_LAS unsigned char* lds, const Gemm g, const Sched& S, const Epi& E) {
;     ...
;             PG8_WAIT_V(8); PG8_WAIT_L(0); PG8_BAR; PG8_MMA(1, 0, At, B0); PG8_MMA(1, 1, At, B1); PG8_BAR; PG8_SCHED;
;             PG8_LDB(B0, 1, 0); PG8_LDB(B1, 1, 1); PG8_SCHED; PG8_LDA(At, 1, 0); PG8_STAGE(PG8_SA(0, 1), a2 + hstep, voffA);
;             PG8_WAIT_V(8); PG8_WAIT_L(0); PG8_BAR; PG8_MMA(0, 0, At, B0); PG8_MMA(0, 1, At, B1); PG8_BAR; PG8_SCHED;
	s_setprio 1
	s_waitcnt lgkmcnt(0)
	v_mfma_f32_16x16x32_bf16 v[60:63], v[128:131], v[160:163], v[60:63]
	v_mfma_f32_16x16x32_bf16 v[56:59], v[136:139], v[160:163], v[56:59]
	v_mfma_f32_16x16x32_bf16 v[44:47], v[128:131], v[168:171], v[44:47]
	v_mfma_f32_16x16x32_bf16 v[40:43], v[136:139], v[168:171], v[40:43]
	v_mfma_f32_16x16x32_bf16 v[28:31], v[128:131], v[176:179], v[28:31]
	v_mfma_f32_16x16x32_bf16 v[24:27], v[136:139], v[176:179], v[24:27]
	v_mfma_f32_16x16x32_bf16 v[12:15], v[128:131], v[208:211], v[12:15]
	v_mfma_f32_16x16x32_bf16 v[8:11], v[136:139], v[208:211], v[8:11]
	v_mfma_f32_16x16x32_bf16 v[60:63], v[132:135], v[164:167], v[60:63]
	v_mfma_f32_16x16x32_bf16 v[56:59], v[140:143], v[164:167], v[56:59]
	v_mfma_f32_16x16x32_bf16 v[44:47], v[132:135], v[172:175], v[44:47]
	v_mfma_f32_16x16x32_bf16 v[40:43], v[140:143], v[172:175], v[40:43]
	v_mfma_f32_16x16x32_bf16 v[28:31], v[132:135], v[180:183], v[28:31]
	v_mfma_f32_16x16x32_bf16 v[24:27], v[140:143], v[180:183], v[24:27]
	v_mfma_f32_16x16x32_bf16 v[12:15], v[132:135], v[212:215], v[12:15]
	v_mfma_f32_16x16x32_bf16 v[8:11], v[140:143], v[212:215], v[8:11]
	v_mfma_f32_16x16x32_bf16 v[52:55], v[144:147], v[160:163], v[52:55]
	v_mfma_f32_16x16x32_bf16 v[48:51], v[152:155], v[160:163], v[48:51]
	v_mfma_f32_16x16x32_bf16 v[36:39], v[144:147], v[168:171], v[36:39]
	v_mfma_f32_16x16x32_bf16 v[32:35], v[152:155], v[168:171], v[32:35]
	v_mfma_f32_16x16x32_bf16 v[20:23], v[144:147], v[176:179], v[20:23]
	v_mfma_f32_16x16x32_bf16 v[16:19], v[152:155], v[176:179], v[16:19]
	v_mfma_f32_16x16x32_bf16 v[4:7], v[144:147], v[208:211], v[4:7]
	v_mfma_f32_16x16x32_bf16 v[0:3], v[152:155], v[208:211], v[0:3]
	v_mfma_f32_16x16x32_bf16 v[52:55], v[148:151], v[164:167], v[52:55]
	v_mfma_f32_16x16x32_bf16 v[48:51], v[156:159], v[164:167], v[48:51]
	v_mfma_f32_16x16x32_bf16 v[36:39], v[148:151], v[172:175], v[36:39]
	v_mfma_f32_16x16x32_bf16 v[32:35], v[156:159], v[172:175], v[32:35]
	v_mfma_f32_16x16x32_bf16 v[20:23], v[148:151], v[180:183], v[20:23]
	v_mfma_f32_16x16x32_bf16 v[16:19], v[156:159], v[180:183], v[16:19]
	v_mfma_f32_16x16x32_bf16 v[4:7], v[148:151], v[212:215], v[4:7]
	v_mfma_f32_16x16x32_bf16 v[0:3], v[156:159], v[212:215], v[0:3]
	s_setprio 0
	s_barrier
	s_add_i32 s11, 0, 0x18000
	s_add_i32 s14, 0, 0x1c000
	v_add_u32_e32 v140, s11, v233
	v_add_u32_e32 v156, s14, v233
	ds_read_b128 v[128:131], v140
	ds_read_b128 v[132:135], v140 offset:1024
	ds_read_b128 v[136:139], v140 offset:2048
	ds_read_b128 v[140:143], v140 offset:3072
	ds_read_b128 v[144:147], v156
	ds_read_b128 v[148:151], v156 offset:1024
	ds_read_b128 v[152:155], v156 offset:2048
	ds_read_b128 v[156:159], v156 offset:3072
	s_add_u32 s12, s62, 0x20000
	s_addc_u32 s13, s63, 0
	s_mov_b32 m0, s24
	ds_read_b128 v[160:163], v235 offset:32768
	ds_read_b128 v[164:167], v235 offset:33792
	ds_read_b128 v[168:171], v235 offset:34816
	ds_read_b128 v[172:175], v235 offset:35840
	ds_read_b128 v[176:179], v235 offset:36864
	ds_read_b128 v[180:183], v235 offset:37888
	ds_read_b128 v[208:211], v235 offset:38912
	ds_read_b128 v[212:215], v235 offset:39936
	global_load_lds_dwordx4 v202, s[12:13]
	s_mov_b32 m0, s29
	s_nop 0
	global_load_lds_dwordx4 v200, s[12:13]
	s_waitcnt vmcnt(8)
	s_waitcnt lgkmcnt(0)
	s_barrier
	s_setprio 1
	s_waitcnt lgkmcnt(0)
	v_mfma_f32_16x16x32_bf16 v[124:127], v[128:131], v[160:163], v[124:127]
	v_mfma_f32_16x16x32_bf16 v[120:123], v[136:139], v[160:163], v[120:123]
	v_mfma_f32_16x16x32_bf16 v[108:111], v[128:131], v[168:171], v[108:111]
	v_mfma_f32_16x16x32_bf16 v[104:107], v[136:139], v[168:171], v[104:107]
	v_mfma_f32_16x16x32_bf16 v[92:95], v[128:131], v[176:179], v[92:95]
	v_mfma_f32_16x16x32_bf16 v[88:91], v[136:139], v[176:179], v[88:91]
	v_mfma_f32_16x16x32_bf16 v[76:79], v[128:131], v[208:211], v[76:79]
	v_mfma_f32_16x16x32_bf16 v[72:75], v[136:139], v[208:211], v[72:75]
	v_mfma_f32_16x16x32_bf16 v[124:127], v[132:135], v[164:167], v[124:127]
	v_mfma_f32_16x16x32_bf16 v[120:123], v[140:143], v[164:167], v[120:123]
	v_mfma_f32_16x16x32_bf16 v[108:111], v[132:135], v[172:175], v[108:111]
	v_mfma_f32_16x16x32_bf16 v[104:107], v[140:143], v[172:175], v[104:107]
	v_mfma_f32_16x16x32_bf16 v[92:95], v[132:135], v[180:183], v[92:95]
	v_mfma_f32_16x16x32_bf16 v[88:91], v[140:143], v[180:183], v[88:91]
	v_mfma_f32_16x16x32_bf16 v[76:79], v[132:135], v[212:215], v[76:79]
	v_mfma_f32_16x16x32_bf16 v[72:75], v[140:143], v[212:215], v[72:75]
	v_mfma_f32_16x16x32_bf16 v[116:119], v[144:147], v[160:163], v[116:119]
	v_mfma_f32_16x16x32_bf16 v[112:115], v[152:155], v[160:163], v[112:115]
	v_mfma_f32_16x16x32_bf16 v[100:103], v[144:147], v[168:171], v[100:103]
	v_mfma_f32_16x16x32_bf16 v[96:99], v[152:155], v[168:171], v[96:99]
	v_mfma_f32_16x16x32_bf16 v[84:87], v[144:147], v[176:179], v[84:87]
	v_mfma_f32_16x16x32_bf16 v[80:83], v[152:155], v[176:179], v[80:83]
	v_mfma_f32_16x16x32_bf16 v[68:71], v[144:147], v[208:211], v[68:71]
	v_mfma_f32_16x16x32_bf16 v[64:67], v[152:155], v[208:211], v[64:67]
	v_mfma_f32_16x16x32_bf16 v[116:119], v[148:151], v[164:167], v[116:119]
	v_mfma_f32_16x16x32_bf16 v[112:115], v[156:159], v[164:167], v[112:115]
	v_mfma_f32_16x16x32_bf16 v[100:103], v[148:151], v[172:175], v[100:103]
	v_mfma_f32_16x16x32_bf16 v[96:99], v[156:159], v[172:175], v[96:99]
	v_mfma_f32_16x16x32_bf16 v[84:87], v[148:151], v[180:183], v[84:87]
	v_mfma_f32_16x16x32_bf16 v[80:83], v[156:159], v[180:183], v[80:83]
	v_mfma_f32_16x16x32_bf16 v[68:71], v[148:151], v[212:215], v[68:71]
	v_mfma_f32_16x16x32_bf16 v[64:67], v[156:159], v[212:215], v[64:67]
	s_setprio 0
	s_barrier
; #define PG8_STAGE(bufoff, gbase, voff) do { _Pragma("unroll") for (int _i = 0; _i < 2; ++_i) \
;         __builtin_amdgcn_global_load_lds((const unsigned*)((const char*)(gbase) + (voff)[_i]), (PG8_LAS unsigned*)(lds + (bufoff) + ldsw + _i * 8192), 16, 0, 0); } while (0)
; #define PG8_LDA(dst, b, h) do { _Pragma("unroll") for (int m = 0; m < 4; ++m) _Pragma("unroll") for (int k = 0; k < 2; ++k) dst[m][k] = *(const PG8_LAS bf16x8*)(lds + PG8_SA(b, h) + aoff + m * 2048 + k * 1024); } while (0)
; #define PG8_MMA(ai, bj, At, Bt) do { __builtin_amdgcn_s_setprio(1); _Pragma("unroll") for (int m = 0; m < 4; ++m) _Pragma("unroll") for (int n = 0; n < 2; ++n) _Pragma("unroll") for (int k = 0; k < 2; ++k) \
;         acc[ai][bj][m][n] = __builtin_amdgcn_mfma_f32_16x16x32_bf16(Bt[n][k], At[m][k], acc[ai][bj][m][n], 0, 0, 0); __builtin_amdgcn_s_setprio(0); } while (0)
; #define PG8_WAIT_V(n) asm volatile("s_waitcnt vmcnt(" #n ")" ::: "memory")
; #define PG8_WAIT_L(n) asm volatile("s_waitcnt lgkmcnt(" #n ")" ::: "memory")
; #define PG8_BAR __builtin_amdgcn_s_barrier()
; #define PG8_SCHED __builtin_amdgcn_sched_barrier(0)
; template <class Epi, class Sched, bool ALIGN_EPI = false, bool SP2 = false>
; __device__ __forceinline__ void gemm_phase(PG8_LAS unsigned char* lds, const Gemm g, const Sched& S, const Epi& E) {
;     ...
;             PG8_LDA(At, 1, 1); PG8_STAGE(PG8_SB(1, 0), b3, voffB); PG8_STAGE(PG8_SB(1, 1), b3 + hstep, voffB); PG8_STAGE(PG8_SA(1, 0), a3, voffA);
;             PG8_WAIT_V(8); PG8_WAIT_L(0); PG8_BAR; PG8_MMA(1, 0, At, B0); PG8_MMA(1, 1, At, B1); PG8_BAR; PG8_SCHED;
;     ...
;         if constexpr (ALIGN_EPI) { if (wr == 0) PG8_BAR; }
	s_add_i32 s11, s11, s9
	v_lshl_add_u64 v[216:217], v[216:217], 0, s[34:35]
	s_mov_b32 m0, s11
	ds_read_b128 v[160:163], v235 offset:49152
	ds_read_b128 v[164:167], v235 offset:50176
	ds_read_b128 v[168:171], v235 offset:51200
	ds_read_b128 v[172:175], v235 offset:52224
	ds_read_b128 v[176:179], v235 offset:53248
	ds_read_b128 v[180:183], v235 offset:54272
	ds_read_b128 v[208:211], v235 offset:55296
	ds_read_b128 v[212:215], v235 offset:56320
	global_load_lds_dwordx4 v[216:217], off
	s_add_i32 m0, s11, 0x2000
	s_add_u32 s12, s60, 0x20080
	v_lshl_add_u64 v[216:217], v[236:237], 0, s[34:35]
	s_addc_u32 s13, s61, 0
	s_add_i32 s11, s14, s9
	global_load_lds_dwordx4 v[216:217], off
	s_mov_b32 m0, s11
	s_nop 0
	global_load_lds_dwordx4 v188, s[12:13]
	s_add_i32 m0, s11, 0x2000
	s_nop 0
	global_load_lds_dwordx4 v198, s[12:13]
	v_lshl_add_u64 v[216:217], v[238:239], 0, s[34:35]
	s_mov_b32 m0, s38
	s_nop 0
	global_load_lds_dwordx4 v[216:217], off
	v_lshl_add_u64 v[216:217], v[240:241], 0, s[34:35]
	s_mov_b32 m0, s39
	s_nop 0
	global_load_lds_dwordx4 v[216:217], off
	s_waitcnt vmcnt(8)
	s_waitcnt lgkmcnt(0)
	s_barrier
	s_setprio 1
	s_waitcnt lgkmcnt(0)
	v_mfma_f32_16x16x32_bf16 v[60:63], v[128:131], v[160:163], v[60:63]
	v_mfma_f32_16x16x32_bf16 v[56:59], v[136:139], v[160:163], v[56:59]
	v_mfma_f32_16x16x32_bf16 v[44:47], v[128:131], v[168:171], v[44:47]
	v_mfma_f32_16x16x32_bf16 v[40:43], v[136:139], v[168:171], v[40:43]
	v_mfma_f32_16x16x32_bf16 v[28:31], v[128:131], v[176:179], v[28:31]
	v_mfma_f32_16x16x32_bf16 v[24:27], v[136:139], v[176:179], v[24:27]
	v_mfma_f32_16x16x32_bf16 v[12:15], v[128:131], v[208:211], v[12:15]
	v_mfma_f32_16x16x32_bf16 v[8:11], v[136:139], v[208:211], v[8:11]
	v_mfma_f32_16x16x32_bf16 v[60:63], v[132:135], v[164:167], v[60:63]
	v_mfma_f32_16x16x32_bf16 v[56:59], v[140:143], v[164:167], v[56:59]
	v_mfma_f32_16x16x32_bf16 v[44:47], v[132:135], v[172:175], v[44:47]
	v_mfma_f32_16x16x32_bf16 v[40:43], v[140:143], v[172:175], v[40:43]
	v_mfma_f32_16x16x32_bf16 v[28:31], v[132:135], v[180:183], v[28:31]
	v_mfma_f32_16x16x32_bf16 v[24:27], v[140:143], v[180:183], v[24:27]
	v_mfma_f32_16x16x32_bf16 v[12:15], v[132:135], v[212:215], v[12:15]
	v_mfma_f32_16x16x32_bf16 v[8:11], v[140:143], v[212:215], v[8:11]
	v_mfma_f32_16x16x32_bf16 v[52:55], v[144:147], v[160:163], v[52:55]
	v_mfma_f32_16x16x32_bf16 v[48:51], v[152:155], v[160:163], v[48:51]
	v_mfma_f32_16x16x32_bf16 v[36:39], v[144:147], v[168:171], v[36:39]
	v_mfma_f32_16x16x32_bf16 v[32:35], v[152:155], v[168:171], v[32:35]
	v_mfma_f32_16x16x32_bf16 v[20:23], v[144:147], v[176:179], v[20:23]
	v_mfma_f32_16x16x32_bf16 v[16:19], v[152:155], v[176:179], v[16:19]
	v_mfma_f32_16x16x32_bf16 v[4:7], v[144:147], v[208:211], v[4:7]
	v_mfma_f32_16x16x32_bf16 v[0:3], v[152:155], v[208:211], v[0:3]
	v_mfma_f32_16x16x32_bf16 v[52:55], v[148:151], v[164:167], v[52:55]
	v_mfma_f32_16x16x32_bf16 v[48:51], v[156:159], v[164:167], v[48:51]
	v_mfma_f32_16x16x32_bf16 v[36:39], v[148:151], v[172:175], v[36:39]
	v_mfma_f32_16x16x32_bf16 v[32:35], v[156:159], v[172:175], v[32:35]
	v_mfma_f32_16x16x32_bf16 v[20:23], v[148:151], v[180:183], v[20:23]
	v_mfma_f32_16x16x32_bf16 v[16:19], v[156:159], v[180:183], v[16:19]
	v_mfma_f32_16x16x32_bf16 v[4:7], v[148:151], v[212:215], v[4:7]
	v_mfma_f32_16x16x32_bf16 v[0:3], v[156:159], v[212:215], v[0:3]
	s_setprio 0
	s_barrier
	s_add_i32 s10, s10, 2
	s_add_u32 s58, s58, 0x100
	s_addc_u32 s59, s59, 0
	s_add_u32 s30, s30, 0x100
	s_addc_u32 s31, s31, 0
	s_cmp_gt_u32 s10, 5
	s_cbranch_scc0 .LBB0_574
	s_and_b64 vcc, exec, s[48:49]
	s_cbranch_vccz .LBB0_577
	s_barrier

; #define PG8_STAGE(bufoff, gbase, voff) do { _Pragma("unroll") for (int _i = 0; _i < 2; ++_i) \
;         __builtin_amdgcn_global_load_lds((const unsigned*)((const char*)(gbase) + (voff)[_i]), (PG8_LAS unsigned*)(lds + (bufoff) + ldsw + _i * 8192), 16, 0, 0); } while (0)
; #define PG8_LDA(dst, b, h) do { _Pragma("unroll") for (int m = 0; m < 4; ++m) _Pragma("unroll") for (int k = 0; k < 2; ++k) dst[m][k] = *(const PG8_LAS bf16x8*)(lds + PG8_SA(b, h) + aoff + m * 2048 + k * 1024); } while (0)
; #define PG8_LDB(dst, b, h) do { _Pragma("unroll") for (int n = 0; n < 2; ++n) _Pragma("unroll") for (int k = 0; k < 2; ++k) dst[n][k] = *(const PG8_LAS bf16x8*)(lds + PG8_SB(b, h) + boff + n * 2048 + k * 1024); } while (0)
; #define PG8_WAIT_V(n) asm volatile("s_waitcnt vmcnt(" #n ")" ::: "memory")
; #define PG8_WAIT_L(n) asm volatile("s_waitcnt lgkmcnt(" #n ")" ::: "memory")
; #define PG8_BAR __builtin_amdgcn_s_barrier()
; #define PG8_SCHED __builtin_amdgcn_sched_barrier(0)
; template <class Epi, class Sched, bool ALIGN_EPI = false, bool SP2 = false>
; __device__ __forceinline__ void gemm_phase(PG8_LAS unsigned char* lds, const Gemm g, const Sched& S, const Epi& E) {
;     ...
;         const char* nA = has_next ? (const char*)g.A + (size_t)nxt.pm * tstep : cA; const char* nB = has_next ? (const char*)g.Bt + (size_t)nxt.pn * tstep : cB;
;         for (int t = 0; t < nt; t += 2) {
;             const bool last = (t == nt - 2);
;             const char* a1 = cA + (size_t)(t + 1) * kstep;
;             const char* a2 = last ? nA : cA + (size_t)(t + 2) * kstep; const char* b2 = last ? nB : cB + (size_t)(t + 2) * kstep;
;             const char* a3 = a2 + kstep; const char* b3 = b2 + kstep;
;             if (last && has_next) S.a_ready(nxt);
;             if constexpr (SP2) {
;             PG8_LDB(B0, 0, 0); PG8_LDB(B1, 0, 1); PG8_SCHED; PG8_LDA(At, 0, 0); PG8_STAGE(PG8_SA(1, 1), a1 + hstep, voffA);
;             PG8_WAIT_V(8); PG8_WAIT_L(0); PG8_BAR; PG8_MMA(0, 0, At, B0); PG8_MMA(0, 1, At, B1); PG8_BAR; PG8_SCHED;
;             PG8_LDA(At, 0, 1); PG8_STAGE(PG8_SB(0, 0), b2, voffB); PG8_STAGE(PG8_SB(0, 1), b2 + hstep, voffB); PG8_STAGE(PG8_SA(0, 0), a2, voffA);
;             PG8_WAIT_V(8); PG8_WAIT_L(0); PG8_BAR; PG8_MMA(1, 0, At, B0); PG8_MMA(1, 1, At, B1); PG8_BAR; PG8_SCHED;
.LBB0_642:
	s_add_u32 s11, s56, 0xfffc0080
	s_addc_u32 s12, s57, -1
	s_add_i32 s13, 0, 0x10000
	s_cmp_eq_u32 s10, 12
	s_cselect_b32 s61, s51, s12
	s_cselect_b32 s60, s72, s11
	s_cselect_b32 s59, s49, s31
	s_cselect_b32 s58, s73, s30
	s_add_i32 s11, 0, 0x14000
	v_add_u32_e32 v154, s13, v139
	v_add_u32_e32 v170, s11, v139
	ds_read_b128 v[142:145], v154
	ds_read_b128 v[146:149], v154 offset:1024
	ds_read_b128 v[150:153], v154 offset:2048
	ds_read_b128 v[154:157], v154 offset:3072
	ds_read_b128 v[158:161], v170
	ds_read_b128 v[162:165], v170 offset:1024
	ds_read_b128 v[166:169], v170 offset:2048
	ds_read_b128 v[170:173], v170 offset:3072
	s_add_i32 m0, s20, 0xc000
	ds_read_b128 v[174:177], v141
	ds_read_b128 v[178:181], v141 offset:1024
	ds_read_b128 v[198:201], v141 offset:2048
	ds_read_b128 v[202:205], v141 offset:3072
	ds_read_b128 v[206:209], v141 offset:4096
	ds_read_b128 v[210:213], v141 offset:5120
	ds_read_b128 v[214:217], v141 offset:6144
	ds_read_b128 v[232:235], v141 offset:7168
	global_load_lds_dwordx4 v134, s[56:57]
	s_add_i32 m0, s20, 0xe000
	s_nop 0
	global_load_lds_dwordx4 v136, s[56:57]
	s_waitcnt vmcnt(8)
	s_waitcnt lgkmcnt(0)
	s_barrier
	s_setprio 1
	s_waitcnt lgkmcnt(0)
	v_mfma_f32_16x16x32_bf16 v[124:127], v[142:145], v[174:177], v[124:127]
	v_mfma_f32_16x16x32_bf16 v[120:123], v[150:153], v[174:177], v[120:123]
	v_mfma_f32_16x16x32_bf16 v[116:119], v[142:145], v[198:201], v[116:119]
	v_mfma_f32_16x16x32_bf16 v[112:115], v[150:153], v[198:201], v[112:115]
	v_mfma_f32_16x16x32_bf16 v[100:103], v[142:145], v[206:209], v[100:103]
	v_mfma_f32_16x16x32_bf16 v[96:99], v[150:153], v[206:209], v[96:99]
	v_mfma_f32_16x16x32_bf16 v[84:87], v[142:145], v[214:217], v[84:87]
	v_mfma_f32_16x16x32_bf16 v[80:83], v[150:153], v[214:217], v[80:83]
	v_mfma_f32_16x16x32_bf16 v[124:127], v[146:149], v[178:181], v[124:127]
	v_mfma_f32_16x16x32_bf16 v[120:123], v[154:157], v[178:181], v[120:123]
	v_mfma_f32_16x16x32_bf16 v[116:119], v[146:149], v[202:205], v[116:119]
	v_mfma_f32_16x16x32_bf16 v[112:115], v[154:157], v[202:205], v[112:115]
	v_mfma_f32_16x16x32_bf16 v[100:103], v[146:149], v[210:213], v[100:103]
	v_mfma_f32_16x16x32_bf16 v[96:99], v[154:157], v[210:213], v[96:99]
	v_mfma_f32_16x16x32_bf16 v[84:87], v[146:149], v[232:235], v[84:87]
	v_mfma_f32_16x16x32_bf16 v[80:83], v[154:157], v[232:235], v[80:83]
	v_mfma_f32_16x16x32_bf16 v[108:111], v[158:161], v[174:177], v[108:111]
	v_mfma_f32_16x16x32_bf16 v[104:107], v[166:169], v[174:177], v[104:107]
	v_mfma_f32_16x16x32_bf16 v[92:95], v[158:161], v[198:201], v[92:95]
	v_mfma_f32_16x16x32_bf16 v[88:91], v[166:169], v[198:201], v[88:91]
	v_mfma_f32_16x16x32_bf16 v[76:79], v[158:161], v[206:209], v[76:79]
	v_mfma_f32_16x16x32_bf16 v[72:75], v[166:169], v[206:209], v[72:75]
	v_mfma_f32_16x16x32_bf16 v[68:71], v[158:161], v[214:217], v[68:71]
	v_mfma_f32_16x16x32_bf16 v[64:67], v[166:169], v[214:217], v[64:67]
	v_mfma_f32_16x16x32_bf16 v[108:111], v[162:165], v[178:181], v[108:111]
	v_mfma_f32_16x16x32_bf16 v[104:107], v[170:173], v[178:181], v[104:107]
	v_mfma_f32_16x16x32_bf16 v[92:95], v[162:165], v[202:205], v[92:95]
	v_mfma_f32_16x16x32_bf16 v[88:91], v[170:173], v[202:205], v[88:91]
	v_mfma_f32_16x16x32_bf16 v[76:79], v[162:165], v[210:213], v[76:79]
	v_mfma_f32_16x16x32_bf16 v[72:75], v[170:173], v[210:213], v[72:75]
	v_mfma_f32_16x16x32_bf16 v[68:71], v[162:165], v[232:235], v[68:71]
	v_mfma_f32_16x16x32_bf16 v[64:67], v[170:173], v[232:235], v[64:67]
	s_setprio 0
	s_barrier
	s_add_i32 s12, s13, s9
	v_lshl_add_u64 v[182:183], s[58:59], 0, v[188:189]
	s_mov_b32 m0, s12
	ds_read_b128 v[174:177], v141 offset:16384
	ds_read_b128 v[178:181], v141 offset:17408
	ds_read_b128 v[198:201], v141 offset:18432
	ds_read_b128 v[202:205], v141 offset:19456
	ds_read_b128 v[206:209], v141 offset:20480
	ds_read_b128 v[210:213], v141 offset:21504
	ds_read_b128 v[214:217], v141 offset:22528
	ds_read_b128 v[232:235], v141 offset:23552
	global_load_lds_dwordx4 v[182:183], off
	s_add_i32 m0, s12, 0x2000
	s_add_u32 s12, s58, 0x40000
	v_lshl_add_u64 v[236:237], s[58:59], 0, v[128:129]
	s_addc_u32 s13, s59, 0
	s_add_i32 s11, s11, s9
	global_load_lds_dwordx4 v[236:237], off
	s_mov_b32 m0, s11
	v_lshl_add_u64 v[240:241], s[60:61], 0, v[130:131]
	global_load_lds_dwordx4 v188, s[12:13]
	s_add_i32 m0, s11, 0x2000
	s_nop 0
	global_load_lds_dwordx4 v128, s[12:13]
	v_lshl_add_u64 v[238:239], s[60:61], 0, v[132:133]
	s_mov_b32 m0, s20
	s_nop 0
	global_load_lds_dwordx4 v[238:239], off
	s_mov_b32 m0, s21
	s_nop 0
	global_load_lds_dwordx4 v[240:241], off
	s_waitcnt vmcnt(8)
	s_waitcnt lgkmcnt(0)
	s_barrier
; #define PG8_STAGE(bufoff, gbase, voff) do { _Pragma("unroll") for (int _i = 0; _i < 2; ++_i) \
;         __builtin_amdgcn_global_load_lds((const unsigned*)((const char*)(gbase) + (voff)[_i]), (PG8_LAS unsigned*)(lds + (bufoff) + ldsw + _i * 8192), 16, 0, 0); } while (0)
; #define PG8_LDA(dst, b, h) do { _Pragma("unroll") for (int m = 0; m < 4; ++m) _Pragma("unroll") for (int k = 0; k < 2; ++k) dst[m][k] = *(const PG8_LAS bf16x8*)(lds + PG8_SA(b, h) + aoff + m * 2048 + k * 1024); } while (0)
; #define PG8_LDB(dst, b, h) do { _Pragma("unroll") for (int n = 0; n < 2; ++n) _Pragma("unroll") for (int k = 0; k < 2; ++k) dst[n][k] = *(const PG8_LAS bf16x8*)(lds + PG8_SB(b, h) + boff + n * 2048 + k * 1024); } while (0)
; #define PG8_MMA(ai, bj, At, Bt) do { __builtin_amdgcn_s_setprio(1); _Pragma("unroll") for (int m = 0; m < 4; ++m) _Pragma("unroll") for (int n = 0; n < 2; ++n) _Pragma("unroll") for (int k = 0; k < 2; ++k) \
;         acc[ai][bj][m][n] = __builtin_amdgcn_mfma_f32_16x16x32_bf16(Bt[n][k], At[m][k], acc[ai][bj][m][n], 0, 0, 0); __builtin_amdgcn_s_setprio(0); } while (0)
; #define PG8_WAIT_V(n) asm volatile("s_waitcnt vmcnt(" #n ")" ::: "memory")
; #define PG8_WAIT_L(n) asm volatile("s_waitcnt lgkmcnt(" #n ")" ::: "memory")
; #define PG8_BAR __builtin_amdgcn_s_barrier()
; #define PG8_SCHED __builtin_amdgcn_sched_barrier(0)
; template <class Epi, class Sched, bool ALIGN_EPI = false, bool SP2 = false>
; __device__ __forceinline__ void gemm_phase(PG8_LAS unsigned char* lds, const Gemm g, const Sched& S, const Epi& E) {
;     ...
;             PG8_WAIT_V(8); PG8_WAIT_L(0); PG8_BAR; PG8_MMA(1, 0, At, B0); PG8_MMA(1, 1, At, B1); PG8_BAR; PG8_SCHED;
;             PG8_LDB(B0, 1, 0); PG8_LDB(B1, 1, 1); PG8_SCHED; PG8_LDA(At, 1, 0); PG8_STAGE(PG8_SA(0, 1), a2 + hstep, voffA);
;             PG8_WAIT_V(8); PG8_WAIT_L(0); PG8_BAR; PG8_MMA(0, 0, At, B0); PG8_MMA(0, 1, At, B1); PG8_BAR; PG8_SCHED;
	s_setprio 1
	s_waitcnt lgkmcnt(0)
	v_mfma_f32_16x16x32_bf16 v[60:63], v[142:145], v[174:177], v[60:63]
	v_mfma_f32_16x16x32_bf16 v[56:59], v[150:153], v[174:177], v[56:59]
	v_mfma_f32_16x16x32_bf16 v[52:55], v[142:145], v[198:201], v[52:55]
	v_mfma_f32_16x16x32_bf16 v[48:51], v[150:153], v[198:201], v[48:51]
	v_mfma_f32_16x16x32_bf16 v[36:39], v[142:145], v[206:209], v[36:39]
	v_mfma_f32_16x16x32_bf16 v[32:35], v[150:153], v[206:209], v[32:35]
	v_mfma_f32_16x16x32_bf16 v[20:23], v[142:145], v[214:217], v[20:23]
	v_mfma_f32_16x16x32_bf16 v[16:19], v[150:153], v[214:217], v[16:19]
	v_mfma_f32_16x16x32_bf16 v[60:63], v[146:149], v[178:181], v[60:63]
	v_mfma_f32_16x16x32_bf16 v[56:59], v[154:157], v[178:181], v[56:59]
	v_mfma_f32_16x16x32_bf16 v[52:55], v[146:149], v[202:205], v[52:55]
	v_mfma_f32_16x16x32_bf16 v[48:51], v[154:157], v[202:205], v[48:51]
	v_mfma_f32_16x16x32_bf16 v[36:39], v[146:149], v[210:213], v[36:39]
	v_mfma_f32_16x16x32_bf16 v[32:35], v[154:157], v[210:213], v[32:35]
	v_mfma_f32_16x16x32_bf16 v[20:23], v[146:149], v[232:235], v[20:23]
	v_mfma_f32_16x16x32_bf16 v[16:19], v[154:157], v[232:235], v[16:19]
	v_mfma_f32_16x16x32_bf16 v[44:47], v[158:161], v[174:177], v[44:47]
	v_mfma_f32_16x16x32_bf16 v[40:43], v[166:169], v[174:177], v[40:43]
	v_mfma_f32_16x16x32_bf16 v[28:31], v[158:161], v[198:201], v[28:31]
	v_mfma_f32_16x16x32_bf16 v[24:27], v[166:169], v[198:201], v[24:27]
	v_mfma_f32_16x16x32_bf16 v[12:15], v[158:161], v[206:209], v[12:15]
	v_mfma_f32_16x16x32_bf16 v[8:11], v[166:169], v[206:209], v[8:11]
	v_mfma_f32_16x16x32_bf16 v[4:7], v[158:161], v[214:217], v[4:7]
	v_mfma_f32_16x16x32_bf16 v[0:3], v[166:169], v[214:217], v[0:3]
	v_mfma_f32_16x16x32_bf16 v[44:47], v[162:165], v[178:181], v[44:47]
	v_mfma_f32_16x16x32_bf16 v[40:43], v[170:173], v[178:181], v[40:43]
	v_mfma_f32_16x16x32_bf16 v[28:31], v[162:165], v[202:205], v[28:31]
	v_mfma_f32_16x16x32_bf16 v[24:27], v[170:173], v[202:205], v[24:27]
	v_mfma_f32_16x16x32_bf16 v[12:15], v[162:165], v[210:213], v[12:15]
	v_mfma_f32_16x16x32_bf16 v[8:11], v[170:173], v[210:213], v[8:11]
	v_mfma_f32_16x16x32_bf16 v[4:7], v[162:165], v[232:235], v[4:7]
	v_mfma_f32_16x16x32_bf16 v[0:3], v[170:173], v[232:235], v[0:3]
	s_setprio 0
	s_barrier
	s_add_i32 s11, 0, 0x18000
	s_add_i32 s14, 0, 0x1c000
	v_add_u32_e32 v154, s11, v139
	v_add_u32_e32 v170, s14, v139
	ds_read_b128 v[142:145], v154
	ds_read_b128 v[146:149], v154 offset:1024
	ds_read_b128 v[150:153], v154 offset:2048
	ds_read_b128 v[154:157], v154 offset:3072
	ds_read_b128 v[158:161], v170
	ds_read_b128 v[162:165], v170 offset:1024
	ds_read_b128 v[166:169], v170 offset:2048
	ds_read_b128 v[170:173], v170 offset:3072
	s_add_u32 s12, s60, 0x40000
	s_addc_u32 s13, s61, 0
	s_mov_b32 m0, s24
	ds_read_b128 v[174:177], v141 offset:32768
	ds_read_b128 v[178:181], v141 offset:33792
	ds_read_b128 v[198:201], v141 offset:34816
	ds_read_b128 v[202:205], v141 offset:35840
	ds_read_b128 v[206:209], v141 offset:36864
	ds_read_b128 v[210:213], v141 offset:37888
	ds_read_b128 v[214:217], v141 offset:38912
	ds_read_b128 v[232:235], v141 offset:39936
	global_load_lds_dwordx4 v132, s[12:13]
	s_mov_b32 m0, s29
	s_nop 0
	global_load_lds_dwordx4 v130, s[12:13]
	s_waitcnt vmcnt(8)
	s_waitcnt lgkmcnt(0)
	s_barrier
	s_setprio 1
	s_waitcnt lgkmcnt(0)
	v_mfma_f32_16x16x32_bf16 v[124:127], v[142:145], v[174:177], v[124:127]
	v_mfma_f32_16x16x32_bf16 v[120:123], v[150:153], v[174:177], v[120:123]
	v_mfma_f32_16x16x32_bf16 v[116:119], v[142:145], v[198:201], v[116:119]
	v_mfma_f32_16x16x32_bf16 v[112:115], v[150:153], v[198:201], v[112:115]
	v_mfma_f32_16x16x32_bf16 v[100:103], v[142:145], v[206:209], v[100:103]
	v_mfma_f32_16x16x32_bf16 v[96:99], v[150:153], v[206:209], v[96:99]
	v_mfma_f32_16x16x32_bf16 v[84:87], v[142:145], v[214:217], v[84:87]
	v_mfma_f32_16x16x32_bf16 v[80:83], v[150:153], v[214:217], v[80:83]
	v_mfma_f32_16x16x32_bf16 v[124:127], v[146:149], v[178:181], v[124:127]
	v_mfma_f32_16x16x32_bf16 v[120:123], v[154:157], v[178:181], v[120:123]
	v_mfma_f32_16x16x32_bf16 v[116:119], v[146:149], v[202:205], v[116:119]
	v_mfma_f32_16x16x32_bf16 v[112:115], v[154:157], v[202:205], v[112:115]
	v_mfma_f32_16x16x32_bf16 v[100:103], v[146:149], v[210:213], v[100:103]
	v_mfma_f32_16x16x32_bf16 v[96:99], v[154:157], v[210:213], v[96:99]
	v_mfma_f32_16x16x32_bf16 v[84:87], v[146:149], v[232:235], v[84:87]
	v_mfma_f32_16x16x32_bf16 v[80:83], v[154:157], v[232:235], v[80:83]
	v_mfma_f32_16x16x32_bf16 v[108:111], v[158:161], v[174:177], v[108:111]
	v_mfma_f32_16x16x32_bf16 v[104:107], v[166:169], v[174:177], v[104:107]
	v_mfma_f32_16x16x32_bf16 v[92:95], v[158:161], v[198:201], v[92:95]
	v_mfma_f32_16x16x32_bf16 v[88:91], v[166:169], v[198:201], v[88:91]
	v_mfma_f32_16x16x32_bf16 v[76:79], v[158:161], v[206:209], v[76:79]
	v_mfma_f32_16x16x32_bf16 v[72:75], v[166:169], v[206:209], v[72:75]
	v_mfma_f32_16x16x32_bf16 v[68:71], v[158:161], v[214:217], v[68:71]
	v_mfma_f32_16x16x32_bf16 v[64:67], v[166:169], v[214:217], v[64:67]
	v_mfma_f32_16x16x32_bf16 v[108:111], v[162:165], v[178:181], v[108:111]
	v_mfma_f32_16x16x32_bf16 v[104:107], v[170:173], v[178:181], v[104:107]
	v_mfma_f32_16x16x32_bf16 v[92:95], v[162:165], v[202:205], v[92:95]
	v_mfma_f32_16x16x32_bf16 v[88:91], v[170:173], v[202:205], v[88:91]
	v_mfma_f32_16x16x32_bf16 v[76:79], v[162:165], v[210:213], v[76:79]
	v_mfma_f32_16x16x32_bf16 v[72:75], v[170:173], v[210:213], v[72:75]
	v_mfma_f32_16x16x32_bf16 v[68:71], v[162:165], v[232:235], v[68:71]
	v_mfma_f32_16x16x32_bf16 v[64:67], v[170:173], v[232:235], v[64:67]
	s_setprio 0
	s_barrier
; #define PG8_STAGE(bufoff, gbase, voff) do { _Pragma("unroll") for (int _i = 0; _i < 2; ++_i) \
;         __builtin_amdgcn_global_load_lds((const unsigned*)((const char*)(gbase) + (voff)[_i]), (PG8_LAS unsigned*)(lds + (bufoff) + ldsw + _i * 8192), 16, 0, 0); } while (0)
; #define PG8_LDA(dst, b, h) do { _Pragma("unroll") for (int m = 0; m < 4; ++m) _Pragma("unroll") for (int k = 0; k < 2; ++k) dst[m][k] = *(const PG8_LAS bf16x8*)(lds + PG8_SA(b, h) + aoff + m * 2048 + k * 1024); } while (0)
; #define PG8_MMA(ai, bj, At, Bt) do { __builtin_amdgcn_s_setprio(1); _Pragma("unroll") for (int m = 0; m < 4; ++m) _Pragma("unroll") for (int n = 0; n < 2; ++n) _Pragma("unroll") for (int k = 0; k < 2; ++k) \
;         acc[ai][bj][m][n] = __builtin_amdgcn_mfma_f32_16x16x32_bf16(Bt[n][k], At[m][k], acc[ai][bj][m][n], 0, 0, 0); __builtin_amdgcn_s_setprio(0); } while (0)
; #define PG8_WAIT_V(n) asm volatile("s_waitcnt vmcnt(" #n ")" ::: "memory")
; #define PG8_WAIT_L(n) asm volatile("s_waitcnt lgkmcnt(" #n ")" ::: "memory")
; #define PG8_BAR __builtin_amdgcn_s_barrier()
; #define PG8_SCHED __builtin_amdgcn_sched_barrier(0)
; template <class Epi, class Sched, bool ALIGN_EPI = false, bool SP2 = false>
; __device__ __forceinline__ void gemm_phase(PG8_LAS unsigned char* lds, const Gemm g, const Sched& S, const Epi& E) {
;     ...
;             PG8_LDA(At, 1, 1); PG8_STAGE(PG8_SB(1, 0), b3, voffB); PG8_STAGE(PG8_SB(1, 1), b3 + hstep, voffB); PG8_STAGE(PG8_SA(1, 0), a3, voffA);
;             PG8_WAIT_V(8); PG8_WAIT_L(0); PG8_BAR; PG8_MMA(1, 0, At, B0); PG8_MMA(1, 1, At, B1); PG8_BAR; PG8_SCHED;
;     ...
;         if constexpr (ALIGN_EPI) { if (wr == 0) PG8_BAR; }
	s_add_i32 s11, s11, s9
	v_lshl_add_u64 v[182:183], v[182:183], 0, s[34:35]
	s_mov_b32 m0, s11
	ds_read_b128 v[174:177], v141 offset:49152
	ds_read_b128 v[178:181], v141 offset:50176
	ds_read_b128 v[198:201], v141 offset:51200
	ds_read_b128 v[202:205], v141 offset:52224
	ds_read_b128 v[206:209], v141 offset:53248
	ds_read_b128 v[210:213], v141 offset:54272
	ds_read_b128 v[214:217], v141 offset:55296
	ds_read_b128 v[232:235], v141 offset:56320
	global_load_lds_dwordx4 v[182:183], off
	s_add_i32 m0, s11, 0x2000
	s_add_u32 s12, s58, 0x40080
	v_lshl_add_u64 v[182:183], v[236:237], 0, s[34:35]
	s_addc_u32 s13, s59, 0
	s_add_i32 s11, s14, s9
	global_load_lds_dwordx4 v[182:183], off
	s_mov_b32 m0, s11
	s_nop 0
	global_load_lds_dwordx4 v188, s[12:13]
	s_add_i32 m0, s11, 0x2000
	s_nop 0
	global_load_lds_dwordx4 v128, s[12:13]
	v_lshl_add_u64 v[182:183], v[238:239], 0, s[34:35]
	s_mov_b32 m0, s38
	s_nop 0
	global_load_lds_dwordx4 v[182:183], off
	v_lshl_add_u64 v[182:183], v[240:241], 0, s[34:35]
	s_mov_b32 m0, s39
	s_nop 0
	global_load_lds_dwordx4 v[182:183], off
	s_waitcnt vmcnt(8)
	s_waitcnt lgkmcnt(0)
	s_barrier
	s_setprio 1
	s_waitcnt lgkmcnt(0)
	v_mfma_f32_16x16x32_bf16 v[60:63], v[142:145], v[174:177], v[60:63]
	v_mfma_f32_16x16x32_bf16 v[56:59], v[150:153], v[174:177], v[56:59]
	v_mfma_f32_16x16x32_bf16 v[52:55], v[142:145], v[198:201], v[52:55]
	v_mfma_f32_16x16x32_bf16 v[48:51], v[150:153], v[198:201], v[48:51]
	v_mfma_f32_16x16x32_bf16 v[36:39], v[142:145], v[206:209], v[36:39]
	v_mfma_f32_16x16x32_bf16 v[32:35], v[150:153], v[206:209], v[32:35]
	v_mfma_f32_16x16x32_bf16 v[20:23], v[142:145], v[214:217], v[20:23]
	v_mfma_f32_16x16x32_bf16 v[16:19], v[150:153], v[214:217], v[16:19]
	v_mfma_f32_16x16x32_bf16 v[60:63], v[146:149], v[178:181], v[60:63]
	v_mfma_f32_16x16x32_bf16 v[56:59], v[154:157], v[178:181], v[56:59]
	v_mfma_f32_16x16x32_bf16 v[52:55], v[146:149], v[202:205], v[52:55]
	v_mfma_f32_16x16x32_bf16 v[48:51], v[154:157], v[202:205], v[48:51]
	v_mfma_f32_16x16x32_bf16 v[36:39], v[146:149], v[210:213], v[36:39]
	v_mfma_f32_16x16x32_bf16 v[32:35], v[154:157], v[210:213], v[32:35]
	v_mfma_f32_16x16x32_bf16 v[20:23], v[146:149], v[232:235], v[20:23]
	v_mfma_f32_16x16x32_bf16 v[16:19], v[154:157], v[232:235], v[16:19]
	v_mfma_f32_16x16x32_bf16 v[44:47], v[158:161], v[174:177], v[44:47]
	v_mfma_f32_16x16x32_bf16 v[40:43], v[166:169], v[174:177], v[40:43]
	v_mfma_f32_16x16x32_bf16 v[28:31], v[158:161], v[198:201], v[28:31]
	v_mfma_f32_16x16x32_bf16 v[24:27], v[166:169], v[198:201], v[24:27]
	v_mfma_f32_16x16x32_bf16 v[12:15], v[158:161], v[206:209], v[12:15]
	v_mfma_f32_16x16x32_bf16 v[8:11], v[166:169], v[206:209], v[8:11]
	v_mfma_f32_16x16x32_bf16 v[4:7], v[158:161], v[214:217], v[4:7]
	v_mfma_f32_16x16x32_bf16 v[0:3], v[166:169], v[214:217], v[0:3]
	v_mfma_f32_16x16x32_bf16 v[44:47], v[162:165], v[178:181], v[44:47]
	v_mfma_f32_16x16x32_bf16 v[40:43], v[170:173], v[178:181], v[40:43]
	v_mfma_f32_16x16x32_bf16 v[28:31], v[162:165], v[202:205], v[28:31]
	v_mfma_f32_16x16x32_bf16 v[24:27], v[170:173], v[202:205], v[24:27]
	v_mfma_f32_16x16x32_bf16 v[12:15], v[162:165], v[210:213], v[12:15]
	v_mfma_f32_16x16x32_bf16 v[8:11], v[170:173], v[210:213], v[8:11]
	v_mfma_f32_16x16x32_bf16 v[4:7], v[162:165], v[232:235], v[4:7]
	v_mfma_f32_16x16x32_bf16 v[0:3], v[170:173], v[232:235], v[0:3]
	s_setprio 0
	s_barrier
	s_add_i32 s10, s10, 2
	s_add_u32 s56, s56, 0x100
	s_addc_u32 s57, s57, 0
	s_add_u32 s30, s30, 0x100
	s_addc_u32 s31, s31, 0
	s_cmp_gt_u32 s10, 13
	s_cbranch_scc0 .LBB0_642
	s_and_b64 vcc, exec, s[42:43]
	s_cbranch_vccz .LBB0_645
	s_barrier

; #define PG8_STAGE(bufoff, gbase, voff) do { _Pragma("unroll") for (int _i = 0; _i < 2; ++_i) \
;         __builtin_amdgcn_global_load_lds((const unsigned*)((const char*)(gbase) + (voff)[_i]), (PG8_LAS unsigned*)(lds + (bufoff) + ldsw + _i * 8192), 16, 0, 0); } while (0)
; #define PG8_LDA(dst, b, h) do { _Pragma("unroll") for (int m = 0; m < 4; ++m) _Pragma("unroll") for (int k = 0; k < 2; ++k) dst[m][k] = *(const PG8_LAS bf16x8*)(lds + PG8_SA(b, h) + aoff + m * 2048 + k * 1024); } while (0)
; #define PG8_LDB(dst, b, h) do { _Pragma("unroll") for (int n = 0; n < 2; ++n) _Pragma("unroll") for (int k = 0; k < 2; ++k) dst[n][k] = *(const PG8_LAS bf16x8*)(lds + PG8_SB(b, h) + boff + n * 2048 + k * 1024); } while (0)
; #define PG8_WAIT_V(n) asm volatile("s_waitcnt vmcnt(" #n ")" ::: "memory")
; #define PG8_WAIT_L(n) asm volatile("s_waitcnt lgkmcnt(" #n ")" ::: "memory")
; #define PG8_BAR __builtin_amdgcn_s_barrier()
; #define PG8_SCHED __builtin_amdgcn_sched_barrier(0)
; template <class Epi, class Sched, bool ALIGN_EPI = false, bool SP2 = false>
; __device__ __forceinline__ void gemm_phase(PG8_LAS unsigned char* lds, const Gemm g, const Sched& S, const Epi& E) {
;     ...
;         const char* nA = has_next ? (const char*)g.A + (size_t)nxt.pm * tstep : cA; const char* nB = has_next ? (const char*)g.Bt + (size_t)nxt.pn * tstep : cB;
;         for (int t = 0; t < nt; t += 2) {
;             const bool last = (t == nt - 2);
;             const char* a1 = cA + (size_t)(t + 1) * kstep;
;             const char* a2 = last ? nA : cA + (size_t)(t + 2) * kstep; const char* b2 = last ? nB : cB + (size_t)(t + 2) * kstep;
;             const char* a3 = a2 + kstep; const char* b3 = b2 + kstep;
;             if (last && has_next) S.a_ready(nxt);
;             if constexpr (SP2) {
;             PG8_LDB(B0, 0, 0); PG8_LDB(B1, 0, 1); PG8_SCHED; PG8_LDA(At, 0, 0); PG8_STAGE(PG8_SA(1, 1), a1 + hstep, voffA);
;             PG8_WAIT_V(8); PG8_WAIT_L(0); PG8_BAR; PG8_MMA(0, 0, At, B0); PG8_MMA(0, 1, At, B1); PG8_BAR; PG8_SCHED;
;             PG8_LDA(At, 0, 1); PG8_STAGE(PG8_SB(0, 0), b2, voffB); PG8_STAGE(PG8_SB(0, 1), b2 + hstep, voffB); PG8_STAGE(PG8_SA(0, 0), a2, voffA);
;             PG8_WAIT_V(8); PG8_WAIT_L(0); PG8_BAR; PG8_MMA(1, 0, At, B0); PG8_MMA(1, 1, At, B1); PG8_BAR; PG8_SCHED;
.LBB0_767:
	s_add_u32 s11, s60, 0xfffc0080
	s_addc_u32 s12, s61, -1
	s_add_i32 s13, 0, 0x10000
	s_cmp_eq_u32 s10, 12
	s_cselect_b32 vcc_hi, s53, s12
	s_cselect_b32 vcc_lo, s55, s11
	s_cselect_b32 s63, s51, s31
	s_cselect_b32 s62, s72, s30
	s_add_i32 s11, 0, 0x14000
	v_add_u32_e32 v154, s13, v143
	v_add_u32_e32 v170, s11, v143
	ds_read_b128 v[138:141], v154
	ds_read_b128 v[146:149], v154 offset:1024
	ds_read_b128 v[150:153], v154 offset:2048
	ds_read_b128 v[154:157], v154 offset:3072
	ds_read_b128 v[158:161], v170
	ds_read_b128 v[162:165], v170 offset:1024
	ds_read_b128 v[166:169], v170 offset:2048
	ds_read_b128 v[170:173], v170 offset:3072
	s_add_i32 m0, s20, 0xc000
	ds_read_b128 v[174:177], v145
	ds_read_b128 v[178:181], v145 offset:1024
	ds_read_b128 v[198:201], v145 offset:2048
	ds_read_b128 v[202:205], v145 offset:3072
	ds_read_b128 v[206:209], v145 offset:4096
	ds_read_b128 v[210:213], v145 offset:5120
	ds_read_b128 v[214:217], v145 offset:6144
	ds_read_b128 v[232:235], v145 offset:7168
	global_load_lds_dwordx4 v134, s[60:61]
	s_add_i32 m0, s20, 0xe000
	s_nop 0
	global_load_lds_dwordx4 v136, s[60:61]
	s_waitcnt vmcnt(8)
	s_waitcnt lgkmcnt(0)
	s_barrier
	s_setprio 1
	s_waitcnt lgkmcnt(0)
	v_mfma_f32_16x16x32_bf16 v[124:127], v[138:141], v[174:177], v[124:127]
	v_mfma_f32_16x16x32_bf16 v[120:123], v[150:153], v[174:177], v[120:123]
	v_mfma_f32_16x16x32_bf16 v[108:111], v[138:141], v[198:201], v[108:111]
	v_mfma_f32_16x16x32_bf16 v[104:107], v[150:153], v[198:201], v[104:107]
	v_mfma_f32_16x16x32_bf16 v[92:95], v[138:141], v[206:209], v[92:95]
	v_mfma_f32_16x16x32_bf16 v[88:91], v[150:153], v[206:209], v[88:91]
	v_mfma_f32_16x16x32_bf16 v[76:79], v[138:141], v[214:217], v[76:79]
	v_mfma_f32_16x16x32_bf16 v[72:75], v[150:153], v[214:217], v[72:75]
	v_mfma_f32_16x16x32_bf16 v[124:127], v[146:149], v[178:181], v[124:127]
	v_mfma_f32_16x16x32_bf16 v[120:123], v[154:157], v[178:181], v[120:123]
	v_mfma_f32_16x16x32_bf16 v[108:111], v[146:149], v[202:205], v[108:111]
	v_mfma_f32_16x16x32_bf16 v[104:107], v[154:157], v[202:205], v[104:107]
	v_mfma_f32_16x16x32_bf16 v[92:95], v[146:149], v[210:213], v[92:95]
	v_mfma_f32_16x16x32_bf16 v[88:91], v[154:157], v[210:213], v[88:91]
	v_mfma_f32_16x16x32_bf16 v[76:79], v[146:149], v[232:235], v[76:79]
	v_mfma_f32_16x16x32_bf16 v[72:75], v[154:157], v[232:235], v[72:75]
	v_mfma_f32_16x16x32_bf16 v[116:119], v[158:161], v[174:177], v[116:119]
	v_mfma_f32_16x16x32_bf16 v[112:115], v[166:169], v[174:177], v[112:115]
	v_mfma_f32_16x16x32_bf16 v[100:103], v[158:161], v[198:201], v[100:103]
	v_mfma_f32_16x16x32_bf16 v[96:99], v[166:169], v[198:201], v[96:99]
	v_mfma_f32_16x16x32_bf16 v[84:87], v[158:161], v[206:209], v[84:87]
	v_mfma_f32_16x16x32_bf16 v[80:83], v[166:169], v[206:209], v[80:83]
	v_mfma_f32_16x16x32_bf16 v[68:71], v[158:161], v[214:217], v[68:71]
	v_mfma_f32_16x16x32_bf16 v[64:67], v[166:169], v[214:217], v[64:67]
	v_mfma_f32_16x16x32_bf16 v[116:119], v[162:165], v[178:181], v[116:119]
	v_mfma_f32_16x16x32_bf16 v[112:115], v[170:173], v[178:181], v[112:115]
	v_mfma_f32_16x16x32_bf16 v[100:103], v[162:165], v[202:205], v[100:103]
	v_mfma_f32_16x16x32_bf16 v[96:99], v[170:173], v[202:205], v[96:99]
	v_mfma_f32_16x16x32_bf16 v[84:87], v[162:165], v[210:213], v[84:87]
	v_mfma_f32_16x16x32_bf16 v[80:83], v[170:173], v[210:213], v[80:83]
	v_mfma_f32_16x16x32_bf16 v[68:71], v[162:165], v[232:235], v[68:71]
	v_mfma_f32_16x16x32_bf16 v[64:67], v[170:173], v[232:235], v[64:67]
	s_setprio 0
	s_barrier
	s_add_i32 s12, s13, s9
	v_lshl_add_u64 v[182:183], s[62:63], 0, v[188:189]
	s_mov_b32 m0, s12
	ds_read_b128 v[174:177], v145 offset:16384
	ds_read_b128 v[178:181], v145 offset:17408
	ds_read_b128 v[198:201], v145 offset:18432
	ds_read_b128 v[202:205], v145 offset:19456
	ds_read_b128 v[206:209], v145 offset:20480
	ds_read_b128 v[210:213], v145 offset:21504
	ds_read_b128 v[214:217], v145 offset:22528
	ds_read_b128 v[232:235], v145 offset:23552
	global_load_lds_dwordx4 v[182:183], off
	s_add_i32 m0, s12, 0x2000
	s_add_u32 s12, s62, 0x40000
	v_lshl_add_u64 v[236:237], s[62:63], 0, v[128:129]
	s_addc_u32 s13, s63, 0
	s_add_i32 s11, s11, s9
	global_load_lds_dwordx4 v[236:237], off
	s_mov_b32 m0, s11
	v_lshl_add_u64 v[240:241], vcc, 0, v[130:131]
	global_load_lds_dwordx4 v188, s[12:13]
	s_add_i32 m0, s11, 0x2000
	s_nop 0
	global_load_lds_dwordx4 v128, s[12:13]
	v_lshl_add_u64 v[238:239], vcc, 0, v[132:133]
	s_mov_b32 m0, s20
	s_nop 0
	global_load_lds_dwordx4 v[238:239], off
	s_mov_b32 m0, s21
	s_nop 0
	global_load_lds_dwordx4 v[240:241], off
	s_waitcnt vmcnt(8)
	s_waitcnt lgkmcnt(0)
	s_barrier
; #define PG8_STAGE(bufoff, gbase, voff) do { _Pragma("unroll") for (int _i = 0; _i < 2; ++_i) \
;         __builtin_amdgcn_global_load_lds((const unsigned*)((const char*)(gbase) + (voff)[_i]), (PG8_LAS unsigned*)(lds + (bufoff) + ldsw + _i * 8192), 16, 0, 0); } while (0)
; #define PG8_LDA(dst, b, h) do { _Pragma("unroll") for (int m = 0; m < 4; ++m) _Pragma("unroll") for (int k = 0; k < 2; ++k) dst[m][k] = *(const PG8_LAS bf16x8*)(lds + PG8_SA(b, h) + aoff + m * 2048 + k * 1024); } while (0)
; #define PG8_LDB(dst, b, h) do { _Pragma("unroll") for (int n = 0; n < 2; ++n) _Pragma("unroll") for (int k = 0; k < 2; ++k) dst[n][k] = *(const PG8_LAS bf16x8*)(lds + PG8_SB(b, h) + boff + n * 2048 + k * 1024); } while (0)
; #define PG8_MMA(ai, bj, At, Bt) do { __builtin_amdgcn_s_setprio(1); _Pragma("unroll") for (int m = 0; m < 4; ++m) _Pragma("unroll") for (int n = 0; n < 2; ++n) _Pragma("unroll") for (int k = 0; k < 2; ++k) \
;         acc[ai][bj][m][n] = __builtin_amdgcn_mfma_f32_16x16x32_bf16(Bt[n][k], At[m][k], acc[ai][bj][m][n], 0, 0, 0); __builtin_amdgcn_s_setprio(0); } while (0)
; #define PG8_WAIT_V(n) asm volatile("s_waitcnt vmcnt(" #n ")" ::: "memory")
; #define PG8_WAIT_L(n) asm volatile("s_waitcnt lgkmcnt(" #n ")" ::: "memory")
; #define PG8_BAR __builtin_amdgcn_s_barrier()
; #define PG8_SCHED __builtin_amdgcn_sched_barrier(0)
; template <class Epi, class Sched, bool ALIGN_EPI = false, bool SP2 = false>
; __device__ __forceinline__ void gemm_phase(PG8_LAS unsigned char* lds, const Gemm g, const Sched& S, const Epi& E) {
;     ...
;             PG8_WAIT_V(8); PG8_WAIT_L(0); PG8_BAR; PG8_MMA(1, 0, At, B0); PG8_MMA(1, 1, At, B1); PG8_BAR; PG8_SCHED;
;             PG8_LDB(B0, 1, 0); PG8_LDB(B1, 1, 1); PG8_SCHED; PG8_LDA(At, 1, 0); PG8_STAGE(PG8_SA(0, 1), a2 + hstep, voffA);
;             PG8_WAIT_V(8); PG8_WAIT_L(0); PG8_BAR; PG8_MMA(0, 0, At, B0); PG8_MMA(0, 1, At, B1); PG8_BAR; PG8_SCHED;
	s_setprio 1
	s_waitcnt lgkmcnt(0)
	v_mfma_f32_16x16x32_bf16 v[60:63], v[138:141], v[174:177], v[60:63]
	v_mfma_f32_16x16x32_bf16 v[56:59], v[150:153], v[174:177], v[56:59]
	v_mfma_f32_16x16x32_bf16 v[44:47], v[138:141], v[198:201], v[44:47]
	v_mfma_f32_16x16x32_bf16 v[40:43], v[150:153], v[198:201], v[40:43]
	v_mfma_f32_16x16x32_bf16 v[28:31], v[138:141], v[206:209], v[28:31]
	v_mfma_f32_16x16x32_bf16 v[24:27], v[150:153], v[206:209], v[24:27]
	v_mfma_f32_16x16x32_bf16 v[12:15], v[138:141], v[214:217], v[12:15]
	v_mfma_f32_16x16x32_bf16 v[8:11], v[150:153], v[214:217], v[8:11]
	v_mfma_f32_16x16x32_bf16 v[60:63], v[146:149], v[178:181], v[60:63]
	v_mfma_f32_16x16x32_bf16 v[56:59], v[154:157], v[178:181], v[56:59]
	v_mfma_f32_16x16x32_bf16 v[44:47], v[146:149], v[202:205], v[44:47]
	v_mfma_f32_16x16x32_bf16 v[40:43], v[154:157], v[202:205], v[40:43]
	v_mfma_f32_16x16x32_bf16 v[28:31], v[146:149], v[210:213], v[28:31]
	v_mfma_f32_16x16x32_bf16 v[24:27], v[154:157], v[210:213], v[24:27]
	v_mfma_f32_16x16x32_bf16 v[12:15], v[146:149], v[232:235], v[12:15]
	v_mfma_f32_16x16x32_bf16 v[8:11], v[154:157], v[232:235], v[8:11]
	v_mfma_f32_16x16x32_bf16 v[52:55], v[158:161], v[174:177], v[52:55]
	v_mfma_f32_16x16x32_bf16 v[48:51], v[166:169], v[174:177], v[48:51]
	v_mfma_f32_16x16x32_bf16 v[36:39], v[158:161], v[198:201], v[36:39]
	v_mfma_f32_16x16x32_bf16 v[32:35], v[166:169], v[198:201], v[32:35]
	v_mfma_f32_16x16x32_bf16 v[20:23], v[158:161], v[206:209], v[20:23]
	v_mfma_f32_16x16x32_bf16 v[16:19], v[166:169], v[206:209], v[16:19]
	v_mfma_f32_16x16x32_bf16 v[4:7], v[158:161], v[214:217], v[4:7]
	v_mfma_f32_16x16x32_bf16 v[0:3], v[166:169], v[214:217], v[0:3]
	v_mfma_f32_16x16x32_bf16 v[52:55], v[162:165], v[178:181], v[52:55]
	v_mfma_f32_16x16x32_bf16 v[48:51], v[170:173], v[178:181], v[48:51]
	v_mfma_f32_16x16x32_bf16 v[36:39], v[162:165], v[202:205], v[36:39]
	v_mfma_f32_16x16x32_bf16 v[32:35], v[170:173], v[202:205], v[32:35]
	v_mfma_f32_16x16x32_bf16 v[20:23], v[162:165], v[210:213], v[20:23]
	v_mfma_f32_16x16x32_bf16 v[16:19], v[170:173], v[210:213], v[16:19]
	v_mfma_f32_16x16x32_bf16 v[4:7], v[162:165], v[232:235], v[4:7]
	v_mfma_f32_16x16x32_bf16 v[0:3], v[170:173], v[232:235], v[0:3]
	s_setprio 0
	s_barrier
	s_add_i32 s11, 0, 0x18000
	s_add_i32 s14, 0, 0x1c000
	v_add_u32_e32 v154, s11, v143
	v_add_u32_e32 v170, s14, v143
	ds_read_b128 v[138:141], v154
	ds_read_b128 v[146:149], v154 offset:1024
	ds_read_b128 v[150:153], v154 offset:2048
	ds_read_b128 v[154:157], v154 offset:3072
	ds_read_b128 v[158:161], v170
	ds_read_b128 v[162:165], v170 offset:1024
	ds_read_b128 v[166:169], v170 offset:2048
	ds_read_b128 v[170:173], v170 offset:3072
	s_add_u32 s12, vcc_lo, 0x40000
	s_addc_u32 s13, vcc_hi, 0
	s_mov_b32 m0, s29
	ds_read_b128 v[174:177], v145 offset:32768
	ds_read_b128 v[178:181], v145 offset:33792
	ds_read_b128 v[198:201], v145 offset:34816
	ds_read_b128 v[202:205], v145 offset:35840
	ds_read_b128 v[206:209], v145 offset:36864
	ds_read_b128 v[210:213], v145 offset:37888
	ds_read_b128 v[214:217], v145 offset:38912
	ds_read_b128 v[232:235], v145 offset:39936
	global_load_lds_dwordx4 v132, s[12:13]
	s_mov_b32 m0, s38
	s_nop 0
	global_load_lds_dwordx4 v130, s[12:13]
	s_waitcnt vmcnt(8)
	s_waitcnt lgkmcnt(0)
	s_barrier
	s_setprio 1
	s_waitcnt lgkmcnt(0)
	v_mfma_f32_16x16x32_bf16 v[124:127], v[138:141], v[174:177], v[124:127]
	v_mfma_f32_16x16x32_bf16 v[120:123], v[150:153], v[174:177], v[120:123]
	v_mfma_f32_16x16x32_bf16 v[108:111], v[138:141], v[198:201], v[108:111]
	v_mfma_f32_16x16x32_bf16 v[104:107], v[150:153], v[198:201], v[104:107]
	v_mfma_f32_16x16x32_bf16 v[92:95], v[138:141], v[206:209], v[92:95]
	v_mfma_f32_16x16x32_bf16 v[88:91], v[150:153], v[206:209], v[88:91]
	v_mfma_f32_16x16x32_bf16 v[76:79], v[138:141], v[214:217], v[76:79]
	v_mfma_f32_16x16x32_bf16 v[72:75], v[150:153], v[214:217], v[72:75]
	v_mfma_f32_16x16x32_bf16 v[124:127], v[146:149], v[178:181], v[124:127]
	v_mfma_f32_16x16x32_bf16 v[120:123], v[154:157], v[178:181], v[120:123]
	v_mfma_f32_16x16x32_bf16 v[108:111], v[146:149], v[202:205], v[108:111]
	v_mfma_f32_16x16x32_bf16 v[104:107], v[154:157], v[202:205], v[104:107]
	v_mfma_f32_16x16x32_bf16 v[92:95], v[146:149], v[210:213], v[92:95]
	v_mfma_f32_16x16x32_bf16 v[88:91], v[154:157], v[210:213], v[88:91]
	v_mfma_f32_16x16x32_bf16 v[76:79], v[146:149], v[232:235], v[76:79]
	v_mfma_f32_16x16x32_bf16 v[72:75], v[154:157], v[232:235], v[72:75]
	v_mfma_f32_16x16x32_bf16 v[116:119], v[158:161], v[174:177], v[116:119]
	v_mfma_f32_16x16x32_bf16 v[112:115], v[166:169], v[174:177], v[112:115]
	v_mfma_f32_16x16x32_bf16 v[100:103], v[158:161], v[198:201], v[100:103]
	v_mfma_f32_16x16x32_bf16 v[96:99], v[166:169], v[198:201], v[96:99]
	v_mfma_f32_16x16x32_bf16 v[84:87], v[158:161], v[206:209], v[84:87]
	v_mfma_f32_16x16x32_bf16 v[80:83], v[166:169], v[206:209], v[80:83]
	v_mfma_f32_16x16x32_bf16 v[68:71], v[158:161], v[214:217], v[68:71]
	v_mfma_f32_16x16x32_bf16 v[64:67], v[166:169], v[214:217], v[64:67]
	v_mfma_f32_16x16x32_bf16 v[116:119], v[162:165], v[178:181], v[116:119]
	v_mfma_f32_16x16x32_bf16 v[112:115], v[170:173], v[178:181], v[112:115]
	v_mfma_f32_16x16x32_bf16 v[100:103], v[162:165], v[202:205], v[100:103]
	v_mfma_f32_16x16x32_bf16 v[96:99], v[170:173], v[202:205], v[96:99]
	v_mfma_f32_16x16x32_bf16 v[84:87], v[162:165], v[210:213], v[84:87]
	v_mfma_f32_16x16x32_bf16 v[80:83], v[170:173], v[210:213], v[80:83]
	v_mfma_f32_16x16x32_bf16 v[68:71], v[162:165], v[232:235], v[68:71]
	v_mfma_f32_16x16x32_bf16 v[64:67], v[170:173], v[232:235], v[64:67]
	s_setprio 0
	s_barrier
; #define PG8_STAGE(bufoff, gbase, voff) do { _Pragma("unroll") for (int _i = 0; _i < 2; ++_i) \
;         __builtin_amdgcn_global_load_lds((const unsigned*)((const char*)(gbase) + (voff)[_i]), (PG8_LAS unsigned*)(lds + (bufoff) + ldsw + _i * 8192), 16, 0, 0); } while (0)
; #define PG8_LDA(dst, b, h) do { _Pragma("unroll") for (int m = 0; m < 4; ++m) _Pragma("unroll") for (int k = 0; k < 2; ++k) dst[m][k] = *(const PG8_LAS bf16x8*)(lds + PG8_SA(b, h) + aoff + m * 2048 + k * 1024); } while (0)
; #define PG8_MMA(ai, bj, At, Bt) do { __builtin_amdgcn_s_setprio(1); _Pragma("unroll") for (int m = 0; m < 4; ++m) _Pragma("unroll") for (int n = 0; n < 2; ++n) _Pragma("unroll") for (int k = 0; k < 2; ++k) \
;         acc[ai][bj][m][n] = __builtin_amdgcn_mfma_f32_16x16x32_bf16(Bt[n][k], At[m][k], acc[ai][bj][m][n], 0, 0, 0); __builtin_amdgcn_s_setprio(0); } while (0)
; #define PG8_WAIT_V(n) asm volatile("s_waitcnt vmcnt(" #n ")" ::: "memory")
; #define PG8_WAIT_L(n) asm volatile("s_waitcnt lgkmcnt(" #n ")" ::: "memory")
; #define PG8_BAR __builtin_amdgcn_s_barrier()
; #define PG8_SCHED __builtin_amdgcn_sched_barrier(0)
; template <class Epi, class Sched, bool ALIGN_EPI = false, bool SP2 = false>
; __device__ __forceinline__ void gemm_phase(PG8_LAS unsigned char* lds, const Gemm g, const Sched& S, const Epi& E) {
;     ...
;             PG8_LDA(At, 1, 1); PG8_STAGE(PG8_SB(1, 0), b3, voffB); PG8_STAGE(PG8_SB(1, 1), b3 + hstep, voffB); PG8_STAGE(PG8_SA(1, 0), a3, voffA);
;             PG8_WAIT_V(8); PG8_WAIT_L(0); PG8_BAR; PG8_MMA(1, 0, At, B0); PG8_MMA(1, 1, At, B1); PG8_BAR; PG8_SCHED;
;     ...
;         if constexpr (ALIGN_EPI) { if (wr == 0) PG8_BAR; }
	s_add_i32 s11, s11, s9
	v_lshl_add_u64 v[182:183], v[182:183], 0, s[34:35]
	s_mov_b32 m0, s11
	ds_read_b128 v[174:177], v145 offset:49152
	ds_read_b128 v[178:181], v145 offset:50176
	ds_read_b128 v[198:201], v145 offset:51200
	ds_read_b128 v[202:205], v145 offset:52224
	ds_read_b128 v[206:209], v145 offset:53248
	ds_read_b128 v[210:213], v145 offset:54272
	ds_read_b128 v[214:217], v145 offset:55296
	ds_read_b128 v[232:235], v145 offset:56320
	global_load_lds_dwordx4 v[182:183], off
	s_add_i32 m0, s11, 0x2000
	s_add_u32 s12, s62, 0x40080
	v_lshl_add_u64 v[182:183], v[236:237], 0, s[34:35]
	s_addc_u32 s13, s63, 0
	s_add_i32 s11, s14, s9
	global_load_lds_dwordx4 v[182:183], off
	s_mov_b32 m0, s11
	s_nop 0
	global_load_lds_dwordx4 v188, s[12:13]
	s_add_i32 m0, s11, 0x2000
	s_nop 0
	global_load_lds_dwordx4 v128, s[12:13]
	v_lshl_add_u64 v[182:183], v[238:239], 0, s[34:35]
	s_mov_b32 m0, s39
	s_nop 0
	global_load_lds_dwordx4 v[182:183], off
	v_lshl_add_u64 v[182:183], v[240:241], 0, s[34:35]
	s_mov_b32 m0, s44
	s_nop 0
	global_load_lds_dwordx4 v[182:183], off
	s_waitcnt vmcnt(8)
	s_waitcnt lgkmcnt(0)
	s_barrier
	s_setprio 1
	s_waitcnt lgkmcnt(0)
	v_mfma_f32_16x16x32_bf16 v[60:63], v[138:141], v[174:177], v[60:63]
	v_mfma_f32_16x16x32_bf16 v[56:59], v[150:153], v[174:177], v[56:59]
	v_mfma_f32_16x16x32_bf16 v[44:47], v[138:141], v[198:201], v[44:47]
	v_mfma_f32_16x16x32_bf16 v[40:43], v[150:153], v[198:201], v[40:43]
	v_mfma_f32_16x16x32_bf16 v[28:31], v[138:141], v[206:209], v[28:31]
	v_mfma_f32_16x16x32_bf16 v[24:27], v[150:153], v[206:209], v[24:27]
	v_mfma_f32_16x16x32_bf16 v[12:15], v[138:141], v[214:217], v[12:15]
	v_mfma_f32_16x16x32_bf16 v[8:11], v[150:153], v[214:217], v[8:11]
	v_mfma_f32_16x16x32_bf16 v[60:63], v[146:149], v[178:181], v[60:63]
	v_mfma_f32_16x16x32_bf16 v[56:59], v[154:157], v[178:181], v[56:59]
	v_mfma_f32_16x16x32_bf16 v[44:47], v[146:149], v[202:205], v[44:47]
	v_mfma_f32_16x16x32_bf16 v[40:43], v[154:157], v[202:205], v[40:43]
	v_mfma_f32_16x16x32_bf16 v[28:31], v[146:149], v[210:213], v[28:31]
	v_mfma_f32_16x16x32_bf16 v[24:27], v[154:157], v[210:213], v[24:27]
	v_mfma_f32_16x16x32_bf16 v[12:15], v[146:149], v[232:235], v[12:15]
	v_mfma_f32_16x16x32_bf16 v[8:11], v[154:157], v[232:235], v[8:11]
	v_mfma_f32_16x16x32_bf16 v[52:55], v[158:161], v[174:177], v[52:55]
	v_mfma_f32_16x16x32_bf16 v[48:51], v[166:169], v[174:177], v[48:51]
	v_mfma_f32_16x16x32_bf16 v[36:39], v[158:161], v[198:201], v[36:39]
	v_mfma_f32_16x16x32_bf16 v[32:35], v[166:169], v[198:201], v[32:35]
	v_mfma_f32_16x16x32_bf16 v[20:23], v[158:161], v[206:209], v[20:23]
	v_mfma_f32_16x16x32_bf16 v[16:19], v[166:169], v[206:209], v[16:19]
	v_mfma_f32_16x16x32_bf16 v[4:7], v[158:161], v[214:217], v[4:7]
	v_mfma_f32_16x16x32_bf16 v[0:3], v[166:169], v[214:217], v[0:3]
	v_mfma_f32_16x16x32_bf16 v[52:55], v[162:165], v[178:181], v[52:55]
	v_mfma_f32_16x16x32_bf16 v[48:51], v[170:173], v[178:181], v[48:51]
	v_mfma_f32_16x16x32_bf16 v[36:39], v[162:165], v[202:205], v[36:39]
	v_mfma_f32_16x16x32_bf16 v[32:35], v[170:173], v[202:205], v[32:35]
	v_mfma_f32_16x16x32_bf16 v[20:23], v[162:165], v[210:213], v[20:23]
	v_mfma_f32_16x16x32_bf16 v[16:19], v[170:173], v[210:213], v[16:19]
	v_mfma_f32_16x16x32_bf16 v[4:7], v[162:165], v[232:235], v[4:7]
	v_mfma_f32_16x16x32_bf16 v[0:3], v[170:173], v[232:235], v[0:3]
	s_setprio 0
	s_barrier
	s_add_i32 s10, s10, 2
	s_add_u32 s60, s60, 0x100
	s_addc_u32 s61, s61, 0
	s_add_u32 s30, s30, 0x100
	s_addc_u32 s31, s31, 0
	s_cmp_gt_u32 s10, 13
	s_cbranch_scc0 .LBB0_767
	s_and_b64 vcc, exec, s[48:49]
	s_cbranch_vccz .LBB0_770
	s_barrier

; #define PG8_STAGE(bufoff, gbase, voff) do { _Pragma("unroll") for (int _i = 0; _i < 2; ++_i) \
;         __builtin_amdgcn_global_load_lds((const unsigned*)((const char*)(gbase) + (voff)[_i]), (PG8_LAS unsigned*)(lds + (bufoff) + ldsw + _i * 8192), 16, 0, 0); } while (0)
; #define PG8_LDA(dst, b, h) do { _Pragma("unroll") for (int m = 0; m < 4; ++m) _Pragma("unroll") for (int k = 0; k < 2; ++k) dst[m][k] = *(const PG8_LAS bf16x8*)(lds + PG8_SA(b, h) + aoff + m * 2048 + k * 1024); } while (0)
; #define PG8_LDB(dst, b, h) do { _Pragma("unroll") for (int n = 0; n < 2; ++n) _Pragma("unroll") for (int k = 0; k < 2; ++k) dst[n][k] = *(const PG8_LAS bf16x8*)(lds + PG8_SB(b, h) + boff + n * 2048 + k * 1024); } while (0)
; #define PG8_WAIT_V(n) asm volatile("s_waitcnt vmcnt(" #n ")" ::: "memory")
; #define PG8_WAIT_L(n) asm volatile("s_waitcnt lgkmcnt(" #n ")" ::: "memory")
; #define PG8_BAR __builtin_amdgcn_s_barrier()
; #define PG8_SCHED __builtin_amdgcn_sched_barrier(0)
; template <class Epi, class Sched, bool ALIGN_EPI = false, bool SP2 = false>
; __device__ __forceinline__ void gemm_phase(PG8_LAS unsigned char* lds, const Gemm g, const Sched& S, const Epi& E) {
;     ...
;         const char* nA = has_next ? (const char*)g.A + (size_t)nxt.pm * tstep : cA; const char* nB = has_next ? (const char*)g.Bt + (size_t)nxt.pn * tstep : cB;
;         for (int t = 0; t < nt; t += 2) {
;             const bool last = (t == nt - 2);
;             const char* a1 = cA + (size_t)(t + 1) * kstep;
;             const char* a2 = last ? nA : cA + (size_t)(t + 2) * kstep; const char* b2 = last ? nB : cB + (size_t)(t + 2) * kstep;
;             const char* a3 = a2 + kstep; const char* b3 = b2 + kstep;
;             if (last && has_next) S.a_ready(nxt);
;             if constexpr (SP2) {
;             PG8_LDB(B0, 0, 0); PG8_LDB(B1, 0, 1); PG8_SCHED; PG8_LDA(At, 0, 0); PG8_STAGE(PG8_SA(1, 1), a1 + hstep, voffA);
;             PG8_WAIT_V(8); PG8_WAIT_L(0); PG8_BAR; PG8_MMA(0, 0, At, B0); PG8_MMA(0, 1, At, B1); PG8_BAR; PG8_SCHED;
;             PG8_LDA(At, 0, 1); PG8_STAGE(PG8_SB(0, 0), b2, voffB); PG8_STAGE(PG8_SB(0, 1), b2 + hstep, voffB); PG8_STAGE(PG8_SA(0, 0), a2, voffA);
;             PG8_WAIT_V(8); PG8_WAIT_L(0); PG8_BAR; PG8_MMA(1, 0, At, B0); PG8_MMA(1, 1, At, B1); PG8_BAR; PG8_SCHED;
.LBB0_839:
	s_add_u32 s58, s56, 0x100
	s_addc_u32 s59, s57, 0
	s_add_i32 s11, 0, 0x10000
	s_cmp_eq_u32 s10, 40
	s_cselect_b32 s63, s43, s59
	s_cselect_b32 s62, s42, s58
	s_cselect_b32 s61, s55, s31
	s_cselect_b32 s60, s54, s30
	s_add_i32 s14, 0, 0x14000
	v_add_u32_e32 v154, s11, v139
	v_add_u32_e32 v170, s14, v139
	ds_read_b128 v[142:145], v154
	ds_read_b128 v[146:149], v154 offset:1024
	ds_read_b128 v[150:153], v154 offset:2048
	ds_read_b128 v[154:157], v154 offset:3072
	ds_read_b128 v[158:161], v170
	ds_read_b128 v[162:165], v170 offset:1024
	ds_read_b128 v[166:169], v170 offset:2048
	ds_read_b128 v[170:173], v170 offset:3072
	s_add_i32 m0, s8, 0xc000
	ds_read_b128 v[174:177], v141
	ds_read_b128 v[178:181], v141 offset:1024
	ds_read_b128 v[198:201], v141 offset:2048
	ds_read_b128 v[202:205], v141 offset:3072
	ds_read_b128 v[206:209], v141 offset:4096
	ds_read_b128 v[210:213], v141 offset:5120
	ds_read_b128 v[214:217], v141 offset:6144
	ds_read_b128 v[232:235], v141 offset:7168
	global_load_lds_dwordx4 v134, s[56:57]
	s_add_i32 m0, s8, 0xe000
	s_nop 0
	global_load_lds_dwordx4 v136, s[56:57]
	s_waitcnt vmcnt(8)
	s_waitcnt lgkmcnt(0)
	s_barrier
	s_setprio 1
	s_waitcnt lgkmcnt(0)
	v_mfma_f32_16x16x32_bf16 v[124:127], v[142:145], v[174:177], v[124:127]
	v_mfma_f32_16x16x32_bf16 v[120:123], v[150:153], v[174:177], v[120:123]
	v_mfma_f32_16x16x32_bf16 v[116:119], v[142:145], v[198:201], v[116:119]
	v_mfma_f32_16x16x32_bf16 v[112:115], v[150:153], v[198:201], v[112:115]
	v_mfma_f32_16x16x32_bf16 v[100:103], v[142:145], v[206:209], v[100:103]
	v_mfma_f32_16x16x32_bf16 v[96:99], v[150:153], v[206:209], v[96:99]
	v_mfma_f32_16x16x32_bf16 v[84:87], v[142:145], v[214:217], v[84:87]
	v_mfma_f32_16x16x32_bf16 v[80:83], v[150:153], v[214:217], v[80:83]
	v_mfma_f32_16x16x32_bf16 v[124:127], v[146:149], v[178:181], v[124:127]
	v_mfma_f32_16x16x32_bf16 v[120:123], v[154:157], v[178:181], v[120:123]
	v_mfma_f32_16x16x32_bf16 v[116:119], v[146:149], v[202:205], v[116:119]
	v_mfma_f32_16x16x32_bf16 v[112:115], v[154:157], v[202:205], v[112:115]
	v_mfma_f32_16x16x32_bf16 v[100:103], v[146:149], v[210:213], v[100:103]
	v_mfma_f32_16x16x32_bf16 v[96:99], v[154:157], v[210:213], v[96:99]
	v_mfma_f32_16x16x32_bf16 v[84:87], v[146:149], v[232:235], v[84:87]
	v_mfma_f32_16x16x32_bf16 v[80:83], v[154:157], v[232:235], v[80:83]
	v_mfma_f32_16x16x32_bf16 v[108:111], v[158:161], v[174:177], v[108:111]
	v_mfma_f32_16x16x32_bf16 v[104:107], v[166:169], v[174:177], v[104:107]
	v_mfma_f32_16x16x32_bf16 v[92:95], v[158:161], v[198:201], v[92:95]
	v_mfma_f32_16x16x32_bf16 v[88:91], v[166:169], v[198:201], v[88:91]
	v_mfma_f32_16x16x32_bf16 v[76:79], v[158:161], v[206:209], v[76:79]
	v_mfma_f32_16x16x32_bf16 v[72:75], v[166:169], v[206:209], v[72:75]
	v_mfma_f32_16x16x32_bf16 v[68:71], v[158:161], v[214:217], v[68:71]
	v_mfma_f32_16x16x32_bf16 v[64:67], v[166:169], v[214:217], v[64:67]
	v_mfma_f32_16x16x32_bf16 v[108:111], v[162:165], v[178:181], v[108:111]
	v_mfma_f32_16x16x32_bf16 v[104:107], v[170:173], v[178:181], v[104:107]
	v_mfma_f32_16x16x32_bf16 v[92:95], v[162:165], v[202:205], v[92:95]
	v_mfma_f32_16x16x32_bf16 v[88:91], v[170:173], v[202:205], v[88:91]
	v_mfma_f32_16x16x32_bf16 v[76:79], v[162:165], v[210:213], v[76:79]
	v_mfma_f32_16x16x32_bf16 v[72:75], v[170:173], v[210:213], v[72:75]
	v_mfma_f32_16x16x32_bf16 v[68:71], v[162:165], v[232:235], v[68:71]
	v_mfma_f32_16x16x32_bf16 v[64:67], v[170:173], v[232:235], v[64:67]
	s_setprio 0
	s_barrier
	s_add_i32 s11, s11, s3
	v_lshl_add_u64 v[182:183], s[60:61], 0, v[188:189]
	s_mov_b32 m0, s11
	ds_read_b128 v[174:177], v141 offset:16384
	ds_read_b128 v[178:181], v141 offset:17408
	ds_read_b128 v[198:201], v141 offset:18432
	ds_read_b128 v[202:205], v141 offset:19456
	ds_read_b128 v[206:209], v141 offset:20480
	ds_read_b128 v[210:213], v141 offset:21504
	ds_read_b128 v[214:217], v141 offset:22528
	ds_read_b128 v[232:235], v141 offset:23552
	global_load_lds_dwordx4 v[182:183], off
	s_add_i32 m0, s11, 0x2000
	s_add_u32 s12, s60, 0xb0000
	v_lshl_add_u64 v[236:237], s[60:61], 0, v[128:129]
	s_addc_u32 s13, s61, 0
	s_add_i32 s11, s14, s3
	global_load_lds_dwordx4 v[236:237], off
	s_mov_b32 m0, s11
	v_lshl_add_u64 v[240:241], s[62:63], 0, v[130:131]
	global_load_lds_dwordx4 v188, s[12:13]
	s_add_i32 m0, s11, 0x2000
	s_nop 0
	global_load_lds_dwordx4 v128, s[12:13]
	v_lshl_add_u64 v[238:239], s[62:63], 0, v[132:133]
	s_mov_b32 m0, s8
	s_nop 0
	global_load_lds_dwordx4 v[238:239], off
	s_mov_b32 m0, s9
	s_nop 0
	global_load_lds_dwordx4 v[240:241], off
	s_waitcnt vmcnt(8)
	s_waitcnt lgkmcnt(0)
	s_barrier
; #define PG8_STAGE(bufoff, gbase, voff) do { _Pragma("unroll") for (int _i = 0; _i < 2; ++_i) \
;         __builtin_amdgcn_global_load_lds((const unsigned*)((const char*)(gbase) + (voff)[_i]), (PG8_LAS unsigned*)(lds + (bufoff) + ldsw + _i * 8192), 16, 0, 0); } while (0)
; #define PG8_LDA(dst, b, h) do { _Pragma("unroll") for (int m = 0; m < 4; ++m) _Pragma("unroll") for (int k = 0; k < 2; ++k) dst[m][k] = *(const PG8_LAS bf16x8*)(lds + PG8_SA(b, h) + aoff + m * 2048 + k * 1024); } while (0)
; #define PG8_LDB(dst, b, h) do { _Pragma("unroll") for (int n = 0; n < 2; ++n) _Pragma("unroll") for (int k = 0; k < 2; ++k) dst[n][k] = *(const PG8_LAS bf16x8*)(lds + PG8_SB(b, h) + boff + n * 2048 + k * 1024); } while (0)
; #define PG8_MMA(ai, bj, At, Bt) do { __builtin_amdgcn_s_setprio(1); _Pragma("unroll") for (int m = 0; m < 4; ++m) _Pragma("unroll") for (int n = 0; n < 2; ++n) _Pragma("unroll") for (int k = 0; k < 2; ++k) \
;         acc[ai][bj][m][n] = __builtin_amdgcn_mfma_f32_16x16x32_bf16(Bt[n][k], At[m][k], acc[ai][bj][m][n], 0, 0, 0); __builtin_amdgcn_s_setprio(0); } while (0)
; #define PG8_WAIT_V(n) asm volatile("s_waitcnt vmcnt(" #n ")" ::: "memory")
; #define PG8_WAIT_L(n) asm volatile("s_waitcnt lgkmcnt(" #n ")" ::: "memory")
; #define PG8_BAR __builtin_amdgcn_s_barrier()
; #define PG8_SCHED __builtin_amdgcn_sched_barrier(0)
; template <class Epi, class Sched, bool ALIGN_EPI = false, bool SP2 = false>
; __device__ __forceinline__ void gemm_phase(PG8_LAS unsigned char* lds, const Gemm g, const Sched& S, const Epi& E) {
;     ...
;             PG8_WAIT_V(8); PG8_WAIT_L(0); PG8_BAR; PG8_MMA(1, 0, At, B0); PG8_MMA(1, 1, At, B1); PG8_BAR; PG8_SCHED;
;             PG8_LDB(B0, 1, 0); PG8_LDB(B1, 1, 1); PG8_SCHED; PG8_LDA(At, 1, 0); PG8_STAGE(PG8_SA(0, 1), a2 + hstep, voffA);
;             PG8_WAIT_V(8); PG8_WAIT_L(0); PG8_BAR; PG8_MMA(0, 0, At, B0); PG8_MMA(0, 1, At, B1); PG8_BAR; PG8_SCHED;
	s_setprio 1
	s_waitcnt lgkmcnt(0)
	v_mfma_f32_16x16x32_bf16 v[60:63], v[142:145], v[174:177], v[60:63]
	v_mfma_f32_16x16x32_bf16 v[56:59], v[150:153], v[174:177], v[56:59]
	v_mfma_f32_16x16x32_bf16 v[52:55], v[142:145], v[198:201], v[52:55]
	v_mfma_f32_16x16x32_bf16 v[48:51], v[150:153], v[198:201], v[48:51]
	v_mfma_f32_16x16x32_bf16 v[36:39], v[142:145], v[206:209], v[36:39]
	v_mfma_f32_16x16x32_bf16 v[32:35], v[150:153], v[206:209], v[32:35]
	v_mfma_f32_16x16x32_bf16 v[20:23], v[142:145], v[214:217], v[20:23]
	v_mfma_f32_16x16x32_bf16 v[16:19], v[150:153], v[214:217], v[16:19]
	v_mfma_f32_16x16x32_bf16 v[60:63], v[146:149], v[178:181], v[60:63]
	v_mfma_f32_16x16x32_bf16 v[56:59], v[154:157], v[178:181], v[56:59]
	v_mfma_f32_16x16x32_bf16 v[52:55], v[146:149], v[202:205], v[52:55]
	v_mfma_f32_16x16x32_bf16 v[48:51], v[154:157], v[202:205], v[48:51]
	v_mfma_f32_16x16x32_bf16 v[36:39], v[146:149], v[210:213], v[36:39]
	v_mfma_f32_16x16x32_bf16 v[32:35], v[154:157], v[210:213], v[32:35]
	v_mfma_f32_16x16x32_bf16 v[20:23], v[146:149], v[232:235], v[20:23]
	v_mfma_f32_16x16x32_bf16 v[16:19], v[154:157], v[232:235], v[16:19]
	v_mfma_f32_16x16x32_bf16 v[44:47], v[158:161], v[174:177], v[44:47]
	v_mfma_f32_16x16x32_bf16 v[40:43], v[166:169], v[174:177], v[40:43]
	v_mfma_f32_16x16x32_bf16 v[28:31], v[158:161], v[198:201], v[28:31]
	v_mfma_f32_16x16x32_bf16 v[24:27], v[166:169], v[198:201], v[24:27]
	v_mfma_f32_16x16x32_bf16 v[12:15], v[158:161], v[206:209], v[12:15]
	v_mfma_f32_16x16x32_bf16 v[8:11], v[166:169], v[206:209], v[8:11]
	v_mfma_f32_16x16x32_bf16 v[4:7], v[158:161], v[214:217], v[4:7]
	v_mfma_f32_16x16x32_bf16 v[0:3], v[166:169], v[214:217], v[0:3]
	v_mfma_f32_16x16x32_bf16 v[44:47], v[162:165], v[178:181], v[44:47]
	v_mfma_f32_16x16x32_bf16 v[40:43], v[170:173], v[178:181], v[40:43]
	v_mfma_f32_16x16x32_bf16 v[28:31], v[162:165], v[202:205], v[28:31]
	v_mfma_f32_16x16x32_bf16 v[24:27], v[170:173], v[202:205], v[24:27]
	v_mfma_f32_16x16x32_bf16 v[12:15], v[162:165], v[210:213], v[12:15]
	v_mfma_f32_16x16x32_bf16 v[8:11], v[170:173], v[210:213], v[8:11]
	v_mfma_f32_16x16x32_bf16 v[4:7], v[162:165], v[232:235], v[4:7]
	v_mfma_f32_16x16x32_bf16 v[0:3], v[170:173], v[232:235], v[0:3]
	s_setprio 0
	s_barrier
	s_add_i32 s11, 0, 0x18000
	s_add_i32 s14, 0, 0x1c000
	v_add_u32_e32 v154, s11, v139
	v_add_u32_e32 v170, s14, v139
	ds_read_b128 v[142:145], v154
	ds_read_b128 v[146:149], v154 offset:1024
	ds_read_b128 v[150:153], v154 offset:2048
	ds_read_b128 v[154:157], v154 offset:3072
	ds_read_b128 v[158:161], v170
	ds_read_b128 v[162:165], v170 offset:1024
	ds_read_b128 v[166:169], v170 offset:2048
	ds_read_b128 v[170:173], v170 offset:3072
	s_add_u32 s12, s62, 0xb0000
	s_addc_u32 s13, s63, 0
	s_mov_b32 m0, s20
	ds_read_b128 v[174:177], v141 offset:32768
	ds_read_b128 v[178:181], v141 offset:33792
	ds_read_b128 v[198:201], v141 offset:34816
	ds_read_b128 v[202:205], v141 offset:35840
	ds_read_b128 v[206:209], v141 offset:36864
	ds_read_b128 v[210:213], v141 offset:37888
	ds_read_b128 v[214:217], v141 offset:38912
	ds_read_b128 v[232:235], v141 offset:39936
	global_load_lds_dwordx4 v132, s[12:13]
	s_mov_b32 m0, s21
	s_nop 0
	global_load_lds_dwordx4 v130, s[12:13]
	s_waitcnt vmcnt(8)
	s_waitcnt lgkmcnt(0)
	s_barrier
	s_setprio 1
	s_waitcnt lgkmcnt(0)
	v_mfma_f32_16x16x32_bf16 v[124:127], v[142:145], v[174:177], v[124:127]
	v_mfma_f32_16x16x32_bf16 v[120:123], v[150:153], v[174:177], v[120:123]
	v_mfma_f32_16x16x32_bf16 v[116:119], v[142:145], v[198:201], v[116:119]
	v_mfma_f32_16x16x32_bf16 v[112:115], v[150:153], v[198:201], v[112:115]
	v_mfma_f32_16x16x32_bf16 v[100:103], v[142:145], v[206:209], v[100:103]
	v_mfma_f32_16x16x32_bf16 v[96:99], v[150:153], v[206:209], v[96:99]
	v_mfma_f32_16x16x32_bf16 v[84:87], v[142:145], v[214:217], v[84:87]
	v_mfma_f32_16x16x32_bf16 v[80:83], v[150:153], v[214:217], v[80:83]
	v_mfma_f32_16x16x32_bf16 v[124:127], v[146:149], v[178:181], v[124:127]
	v_mfma_f32_16x16x32_bf16 v[120:123], v[154:157], v[178:181], v[120:123]
	v_mfma_f32_16x16x32_bf16 v[116:119], v[146:149], v[202:205], v[116:119]
	v_mfma_f32_16x16x32_bf16 v[112:115], v[154:157], v[202:205], v[112:115]
	v_mfma_f32_16x16x32_bf16 v[100:103], v[146:149], v[210:213], v[100:103]
	v_mfma_f32_16x16x32_bf16 v[96:99], v[154:157], v[210:213], v[96:99]
	v_mfma_f32_16x16x32_bf16 v[84:87], v[146:149], v[232:235], v[84:87]
	v_mfma_f32_16x16x32_bf16 v[80:83], v[154:157], v[232:235], v[80:83]
	v_mfma_f32_16x16x32_bf16 v[108:111], v[158:161], v[174:177], v[108:111]
	v_mfma_f32_16x16x32_bf16 v[104:107], v[166:169], v[174:177], v[104:107]
	v_mfma_f32_16x16x32_bf16 v[92:95], v[158:161], v[198:201], v[92:95]
	v_mfma_f32_16x16x32_bf16 v[88:91], v[166:169], v[198:201], v[88:91]
	v_mfma_f32_16x16x32_bf16 v[76:79], v[158:161], v[206:209], v[76:79]
	v_mfma_f32_16x16x32_bf16 v[72:75], v[166:169], v[206:209], v[72:75]
	v_mfma_f32_16x16x32_bf16 v[68:71], v[158:161], v[214:217], v[68:71]
	v_mfma_f32_16x16x32_bf16 v[64:67], v[166:169], v[214:217], v[64:67]
	v_mfma_f32_16x16x32_bf16 v[108:111], v[162:165], v[178:181], v[108:111]
	v_mfma_f32_16x16x32_bf16 v[104:107], v[170:173], v[178:181], v[104:107]
	v_mfma_f32_16x16x32_bf16 v[92:95], v[162:165], v[202:205], v[92:95]
	v_mfma_f32_16x16x32_bf16 v[88:91], v[170:173], v[202:205], v[88:91]
	v_mfma_f32_16x16x32_bf16 v[76:79], v[162:165], v[210:213], v[76:79]
	v_mfma_f32_16x16x32_bf16 v[72:75], v[170:173], v[210:213], v[72:75]
	v_mfma_f32_16x16x32_bf16 v[68:71], v[162:165], v[232:235], v[68:71]
	v_mfma_f32_16x16x32_bf16 v[64:67], v[170:173], v[232:235], v[64:67]
	s_setprio 0
	s_barrier
; #define PG8_STAGE(bufoff, gbase, voff) do { _Pragma("unroll") for (int _i = 0; _i < 2; ++_i) \
;         __builtin_amdgcn_global_load_lds((const unsigned*)((const char*)(gbase) + (voff)[_i]), (PG8_LAS unsigned*)(lds + (bufoff) + ldsw + _i * 8192), 16, 0, 0); } while (0)
; #define PG8_LDA(dst, b, h) do { _Pragma("unroll") for (int m = 0; m < 4; ++m) _Pragma("unroll") for (int k = 0; k < 2; ++k) dst[m][k] = *(const PG8_LAS bf16x8*)(lds + PG8_SA(b, h) + aoff + m * 2048 + k * 1024); } while (0)
; #define PG8_MMA(ai, bj, At, Bt) do { __builtin_amdgcn_s_setprio(1); _Pragma("unroll") for (int m = 0; m < 4; ++m) _Pragma("unroll") for (int n = 0; n < 2; ++n) _Pragma("unroll") for (int k = 0; k < 2; ++k) \
;         acc[ai][bj][m][n] = __builtin_amdgcn_mfma_f32_16x16x32_bf16(Bt[n][k], At[m][k], acc[ai][bj][m][n], 0, 0, 0); __builtin_amdgcn_s_setprio(0); } while (0)
; #define PG8_WAIT_V(n) asm volatile("s_waitcnt vmcnt(" #n ")" ::: "memory")
; #define PG8_WAIT_L(n) asm volatile("s_waitcnt lgkmcnt(" #n ")" ::: "memory")
; #define PG8_BAR __builtin_amdgcn_s_barrier()
; #define PG8_SCHED __builtin_amdgcn_sched_barrier(0)
; template <class Epi, class Sched, bool ALIGN_EPI = false, bool SP2 = false>
; __device__ __forceinline__ void gemm_phase(PG8_LAS unsigned char* lds, const Gemm g, const Sched& S, const Epi& E) {
;     ...
;             PG8_LDA(At, 1, 1); PG8_STAGE(PG8_SB(1, 0), b3, voffB); PG8_STAGE(PG8_SB(1, 1), b3 + hstep, voffB); PG8_STAGE(PG8_SA(1, 0), a3, voffA);
;             PG8_WAIT_V(8); PG8_WAIT_L(0); PG8_BAR; PG8_MMA(1, 0, At, B0); PG8_MMA(1, 1, At, B1); PG8_BAR; PG8_SCHED;
	s_add_i32 s11, s11, s3
	v_lshl_add_u64 v[182:183], v[182:183], 0, s[34:35]
	s_mov_b32 m0, s11
	ds_read_b128 v[174:177], v141 offset:49152
	ds_read_b128 v[178:181], v141 offset:50176
	ds_read_b128 v[198:201], v141 offset:51200
	ds_read_b128 v[202:205], v141 offset:52224
	ds_read_b128 v[206:209], v141 offset:53248
	ds_read_b128 v[210:213], v141 offset:54272
	ds_read_b128 v[214:217], v141 offset:55296
	ds_read_b128 v[232:235], v141 offset:56320
	global_load_lds_dwordx4 v[182:183], off
	s_add_i32 m0, s11, 0x2000
	s_add_u32 s12, s60, 0xb0080
	v_lshl_add_u64 v[182:183], v[236:237], 0, s[34:35]
	s_addc_u32 s13, s61, 0
	s_add_i32 s11, s14, s3
	global_load_lds_dwordx4 v[182:183], off
	s_mov_b32 m0, s11
	s_nop 0
	global_load_lds_dwordx4 v188, s[12:13]
	s_add_i32 m0, s11, 0x2000
	s_nop 0
	global_load_lds_dwordx4 v128, s[12:13]
	v_lshl_add_u64 v[182:183], v[238:239], 0, s[34:35]
	s_mov_b32 m0, s29
	s_nop 0
	global_load_lds_dwordx4 v[182:183], off
	v_lshl_add_u64 v[182:183], v[240:241], 0, s[34:35]
	s_mov_b32 m0, s40
	s_nop 0
	global_load_lds_dwordx4 v[182:183], off
	s_waitcnt vmcnt(8)
	s_waitcnt lgkmcnt(0)
	s_barrier
	s_setprio 1
	s_waitcnt lgkmcnt(0)
	v_mfma_f32_16x16x32_bf16 v[60:63], v[142:145], v[174:177], v[60:63]
	v_mfma_f32_16x16x32_bf16 v[56:59], v[150:153], v[174:177], v[56:59]
	v_mfma_f32_16x16x32_bf16 v[52:55], v[142:145], v[198:201], v[52:55]
	v_mfma_f32_16x16x32_bf16 v[48:51], v[150:153], v[198:201], v[48:51]
	v_mfma_f32_16x16x32_bf16 v[36:39], v[142:145], v[206:209], v[36:39]
	v_mfma_f32_16x16x32_bf16 v[32:35], v[150:153], v[206:209], v[32:35]
	v_mfma_f32_16x16x32_bf16 v[20:23], v[142:145], v[214:217], v[20:23]
	v_mfma_f32_16x16x32_bf16 v[16:19], v[150:153], v[214:217], v[16:19]
	v_mfma_f32_16x16x32_bf16 v[60:63], v[146:149], v[178:181], v[60:63]
	v_mfma_f32_16x16x32_bf16 v[56:59], v[154:157], v[178:181], v[56:59]
	v_mfma_f32_16x16x32_bf16 v[52:55], v[146:149], v[202:205], v[52:55]
	v_mfma_f32_16x16x32_bf16 v[48:51], v[154:157], v[202:205], v[48:51]
	v_mfma_f32_16x16x32_bf16 v[36:39], v[146:149], v[210:213], v[36:39]
	v_mfma_f32_16x16x32_bf16 v[32:35], v[154:157], v[210:213], v[32:35]
	v_mfma_f32_16x16x32_bf16 v[20:23], v[146:149], v[232:235], v[20:23]
	v_mfma_f32_16x16x32_bf16 v[16:19], v[154:157], v[232:235], v[16:19]
	v_mfma_f32_16x16x32_bf16 v[44:47], v[158:161], v[174:177], v[44:47]
	v_mfma_f32_16x16x32_bf16 v[40:43], v[166:169], v[174:177], v[40:43]
	v_mfma_f32_16x16x32_bf16 v[28:31], v[158:161], v[198:201], v[28:31]
	v_mfma_f32_16x16x32_bf16 v[24:27], v[166:169], v[198:201], v[24:27]
	v_mfma_f32_16x16x32_bf16 v[12:15], v[158:161], v[206:209], v[12:15]
	v_mfma_f32_16x16x32_bf16 v[8:11], v[166:169], v[206:209], v[8:11]
	v_mfma_f32_16x16x32_bf16 v[4:7], v[158:161], v[214:217], v[4:7]
	v_mfma_f32_16x16x32_bf16 v[0:3], v[166:169], v[214:217], v[0:3]
	v_mfma_f32_16x16x32_bf16 v[44:47], v[162:165], v[178:181], v[44:47]
	v_mfma_f32_16x16x32_bf16 v[40:43], v[170:173], v[178:181], v[40:43]
	v_mfma_f32_16x16x32_bf16 v[28:31], v[162:165], v[202:205], v[28:31]
	v_mfma_f32_16x16x32_bf16 v[24:27], v[170:173], v[202:205], v[24:27]
	v_mfma_f32_16x16x32_bf16 v[12:15], v[162:165], v[210:213], v[12:15]
	v_mfma_f32_16x16x32_bf16 v[8:11], v[170:173], v[210:213], v[8:11]
	v_mfma_f32_16x16x32_bf16 v[4:7], v[162:165], v[232:235], v[4:7]
	v_mfma_f32_16x16x32_bf16 v[0:3], v[170:173], v[232:235], v[0:3]
	s_setprio 0
	s_barrier
	s_add_i32 s10, s10, 2
	s_add_u32 s30, s30, 0x100
	s_addc_u32 s31, s31, 0
	s_cmp_gt_u32 s10, 41
	s_mov_b64 s[56:57], s[58:59]
	s_cbranch_scc0 .LBB0_839
	s_and_b64 vcc, exec, s[50:51]
	s_cbranch_vccz .LBB0_842
	s_barrier
